# v88 plus: per-phase s_setprio flips removed from the seven GEMM K-loops (16 scalar instructions fewer per K-iteration)
# speedup vs baseline: 1.0055x; 1.0048x over previous
; #define PG8_STAGE(bufoff, gbase, voff) do { _Pragma("unroll") for (int _i = 0; _i < 2; ++_i) \
;     __builtin_amdgcn_global_load_lds((const unsigned*)((const char*)(gbase) + (voff)[_i]), (LAS unsigned*)(lds + (bufoff) + ldsw + _i * 8192), 16, 0, 0); } while (0)
; #define PG8_LDA(dst, b, h) do { _Pragma("unroll") for (int m = 0; m < 4; ++m) _Pragma("unroll") for (int k = 0; k < 2; ++k) dst[m][k] = *(const LAS bf16x8*)(lds + PG8_SA(b, h) + aoff + m * 2048 + k * 1024); } while (0)
; #define PG8_LDB(dst, b, h) do { _Pragma("unroll") for (int n = 0; n < 2; ++n) _Pragma("unroll") for (int k = 0; k < 2; ++k) dst[n][k] = *(const LAS bf16x8*)(lds + PG8_SB(b, h) + boff + n * 2048 + k * 1024); } while (0)
; #define PG8_MMA(ai, bj, At, Bt) do { __builtin_amdgcn_s_setprio(1); _Pragma("unroll") for (int m = 0; m < 4; ++m) _Pragma("unroll") for (int n = 0; n < 2; ++n) _Pragma("unroll") for (int k = 0; k < 2; ++k) \
;     acc[ai][bj][m][n] = __builtin_amdgcn_mfma_f32_16x16x32_bf16(Bt[n][k], At[m][k], acc[ai][bj][m][n], 0, 0, 0); __builtin_amdgcn_s_setprio(0); } while (0)
; #define PG8_WAIT_V(n) asm volatile("s_waitcnt vmcnt(" #n ")" ::: "memory")
; #define PG8_WAIT_L(n) asm volatile("s_waitcnt lgkmcnt(" #n ")" ::: "memory")
; #define PG8_BAR __builtin_amdgcn_s_barrier()
; #define PG8_SCHED __builtin_amdgcn_sched_barrier(0)
; template <class Epi, class Sched>
; DI void gemm_phase(LAS unsigned char* lds, const Gemm g, const Sched& S, const Epi& E) {
;     ...
;     for (int t = 0; t < nt; t += 2) {
;       const bool last = (t == nt - 2);
;       const char* a1 = cA + (size_t)(t + 1) * kstep;
;       const char* a2 = last ? nA : cA + (size_t)(t + 2) * kstep; const char* b2 = last ? nB : cB + (size_t)(t + 2) * kstep;
;       const char* a3 = a2 + kstep; const char* b3 = b2 + kstep;
;       PG8_LDB(B0, 0, 0); PG8_SCHED; PG8_LDA(At, 0, 0); PG8_STAGE(PG8_SA(1, 1), a1 + hstep, voffA);
;       PG8_WAIT_L(8); PG8_BAR; PG8_WAIT_L(0); PG8_MMA(0, 0, At, B0); PG8_BAR; PG8_SCHED;
;       PG8_LDB(B1, 0, 1); PG8_STAGE(PG8_SB(0, 0), b2, voffB);
;       PG8_BAR; PG8_WAIT_L(0); PG8_MMA(0, 1, At, B1); PG8_BAR;
;       PG8_LDA(At, 0, 1); PG8_STAGE(PG8_SA(0, 0), a2, voffA);
;       PG8_BAR; PG8_WAIT_L(0); PG8_MMA(1, 0, At, B0); PG8_BAR; PG8_SCHED;
;       PG8_STAGE(PG8_SB(0, 1), b2 + hstep, voffB);
;       PG8_WAIT_V(6); PG8_BAR; PG8_MMA(1, 1, At, B1); PG8_BAR;
.LBB0_370:
	s_add_u32 s4, s2, 0xfffc0080
	s_addc_u32 s5, s3, -1
	s_add_i32 s51, 0, 0x10000
	v_add_u32_e32 v144, s51, v155
	ds_read_b128 v[128:131], v144
	ds_read_b128 v[146:149], v144 offset:1024
	ds_read_b128 v[150:153], v144 offset:2048
	ds_read_b128 v[160:163], v144 offset:3072
	s_cmp_eq_u32 s50, 12
	s_cselect_b32 s21, s15, s5
	s_cselect_b32 s20, s29, s4
	s_cselect_b32 s5, s13, s49
	s_cselect_b32 s4, s36, s37
	v_lshl_add_u64 v[156:157], s[2:3], 0, v[140:141]
	s_add_i32 m0, s40, 0xc000
	ds_read_b128 v[164:167], v158
	ds_read_b128 v[168:171], v158 offset:1024
	ds_read_b128 v[172:175], v158 offset:2048
	ds_read_b128 v[176:179], v158 offset:3072
	ds_read_b128 v[196:199], v158 offset:4096
	ds_read_b128 v[200:203], v158 offset:5120
	ds_read_b128 v[204:207], v158 offset:6144
	ds_read_b128 v[208:211], v158 offset:7168
	global_load_lds_dwordx4 v[156:157], off
	v_lshl_add_u64 v[156:157], s[2:3], 0, v[142:143]
	s_add_i32 m0, s40, 0xe000
	s_nop 0
	global_load_lds_dwordx4 v[156:157], off
	s_waitcnt lgkmcnt(8)
	s_barrier
	s_waitcnt lgkmcnt(0)
	s_waitcnt lgkmcnt(0)
	v_mfma_f32_16x16x32_bf16 v[124:127], v[128:131], v[164:167], v[124:127]
	v_mfma_f32_16x16x32_bf16 v[120:123], v[150:153], v[164:167], v[120:123]
	v_mfma_f32_16x16x32_bf16 v[108:111], v[128:131], v[172:175], v[108:111]
	v_mfma_f32_16x16x32_bf16 v[104:107], v[150:153], v[172:175], v[104:107]
	v_mfma_f32_16x16x32_bf16 v[92:95], v[128:131], v[196:199], v[92:95]
	v_mfma_f32_16x16x32_bf16 v[88:91], v[150:153], v[196:199], v[88:91]
	v_mfma_f32_16x16x32_bf16 v[76:79], v[128:131], v[204:207], v[76:79]
	v_mfma_f32_16x16x32_bf16 v[72:75], v[150:153], v[204:207], v[72:75]
	v_mfma_f32_16x16x32_bf16 v[124:127], v[146:149], v[168:171], v[124:127]
	v_mfma_f32_16x16x32_bf16 v[120:123], v[160:163], v[168:171], v[120:123]
	v_mfma_f32_16x16x32_bf16 v[108:111], v[146:149], v[176:179], v[108:111]
	v_mfma_f32_16x16x32_bf16 v[104:107], v[160:163], v[176:179], v[104:107]
	v_mfma_f32_16x16x32_bf16 v[92:95], v[146:149], v[200:203], v[92:95]
	v_mfma_f32_16x16x32_bf16 v[88:91], v[160:163], v[200:203], v[88:91]
	v_mfma_f32_16x16x32_bf16 v[76:79], v[146:149], v[208:211], v[76:79]
	v_mfma_f32_16x16x32_bf16 v[72:75], v[160:163], v[208:211], v[72:75]
	s_barrier
	s_add_i32 s54, 0, 0x14000
	s_add_i32 s51, s51, s34
	v_add_u32_e32 v144, s54, v155
	v_lshl_add_u64 v[156:157], s[4:5], 0, v[136:137]
	s_mov_b32 m0, s51
	ds_read_b128 v[212:215], v144
	ds_read_b128 v[216:219], v144 offset:1024
	ds_read_b128 v[220:223], v144 offset:2048
	ds_read_b128 v[224:227], v144 offset:3072
	global_load_lds_dwordx4 v[156:157], off
	v_lshl_add_u64 v[180:181], s[4:5], 0, v[132:133]
	s_add_i32 m0, s51, 0x2000
	s_nop 0
	global_load_lds_dwordx4 v[180:181], off
	s_barrier
	s_waitcnt lgkmcnt(0)
	s_waitcnt lgkmcnt(0)
	v_mfma_f32_16x16x32_bf16 v[116:119], v[212:215], v[164:167], v[116:119]
	v_mfma_f32_16x16x32_bf16 v[112:115], v[220:223], v[164:167], v[112:115]
	v_mfma_f32_16x16x32_bf16 v[100:103], v[212:215], v[172:175], v[100:103]
	v_mfma_f32_16x16x32_bf16 v[96:99], v[220:223], v[172:175], v[96:99]
	v_mfma_f32_16x16x32_bf16 v[84:87], v[212:215], v[196:199], v[84:87]
	v_mfma_f32_16x16x32_bf16 v[80:83], v[220:223], v[196:199], v[80:83]
	v_mfma_f32_16x16x32_bf16 v[68:71], v[212:215], v[204:207], v[68:71]
	v_mfma_f32_16x16x32_bf16 v[64:67], v[220:223], v[204:207], v[64:67]
	v_mfma_f32_16x16x32_bf16 v[116:119], v[216:219], v[168:171], v[116:119]
	v_mfma_f32_16x16x32_bf16 v[112:115], v[224:227], v[168:171], v[112:115]
	v_mfma_f32_16x16x32_bf16 v[100:103], v[216:219], v[176:179], v[100:103]
	v_mfma_f32_16x16x32_bf16 v[96:99], v[224:227], v[176:179], v[96:99]
	v_mfma_f32_16x16x32_bf16 v[84:87], v[216:219], v[200:203], v[84:87]
	v_mfma_f32_16x16x32_bf16 v[80:83], v[224:227], v[200:203], v[80:83]
	v_mfma_f32_16x16x32_bf16 v[68:71], v[216:219], v[208:211], v[68:71]
	v_mfma_f32_16x16x32_bf16 v[64:67], v[224:227], v[208:211], v[64:67]
	s_mov_b32 m0, s40
	v_lshl_add_u64 v[228:229], s[20:21], 0, v[138:139]
	s_barrier
	ds_read_b128 v[164:167], v158 offset:16384
	ds_read_b128 v[168:171], v158 offset:17408
	ds_read_b128 v[172:175], v158 offset:18432
	ds_read_b128 v[176:179], v158 offset:19456
	ds_read_b128 v[196:199], v158 offset:20480
	ds_read_b128 v[200:203], v158 offset:21504
	ds_read_b128 v[204:207], v158 offset:22528
	ds_read_b128 v[208:211], v158 offset:23552
	global_load_lds_dwordx4 v[228:229], off
	v_lshl_add_u64 v[230:231], s[20:21], 0, v[134:135]
	s_mov_b32 m0, s41
	s_nop 0
	global_load_lds_dwordx4 v[230:231], off
	s_barrier
	s_waitcnt lgkmcnt(0)
	s_waitcnt lgkmcnt(0)
	v_mfma_f32_16x16x32_bf16 v[60:63], v[128:131], v[164:167], v[60:63]
	v_mfma_f32_16x16x32_bf16 v[56:59], v[150:153], v[164:167], v[56:59]
	v_mfma_f32_16x16x32_bf16 v[44:47], v[128:131], v[172:175], v[44:47]
	v_mfma_f32_16x16x32_bf16 v[40:43], v[150:153], v[172:175], v[40:43]
	v_mfma_f32_16x16x32_bf16 v[28:31], v[128:131], v[196:199], v[28:31]
	v_mfma_f32_16x16x32_bf16 v[24:27], v[150:153], v[196:199], v[24:27]
	v_mfma_f32_16x16x32_bf16 v[12:15], v[128:131], v[204:207], v[12:15]
	v_mfma_f32_16x16x32_bf16 v[8:11], v[150:153], v[204:207], v[8:11]
	v_mfma_f32_16x16x32_bf16 v[60:63], v[146:149], v[168:171], v[60:63]
	v_mfma_f32_16x16x32_bf16 v[56:59], v[160:163], v[168:171], v[56:59]
	v_mfma_f32_16x16x32_bf16 v[44:47], v[146:149], v[176:179], v[44:47]
	v_mfma_f32_16x16x32_bf16 v[40:43], v[160:163], v[176:179], v[40:43]
	v_mfma_f32_16x16x32_bf16 v[28:31], v[146:149], v[200:203], v[28:31]
	v_mfma_f32_16x16x32_bf16 v[24:27], v[160:163], v[200:203], v[24:27]
	v_mfma_f32_16x16x32_bf16 v[12:15], v[146:149], v[208:211], v[12:15]
	v_mfma_f32_16x16x32_bf16 v[8:11], v[160:163], v[208:211], v[8:11]
	s_barrier
; #define PG8_STAGE(bufoff, gbase, voff) do { _Pragma("unroll") for (int _i = 0; _i < 2; ++_i) \
;     __builtin_amdgcn_global_load_lds((const unsigned*)((const char*)(gbase) + (voff)[_i]), (LAS unsigned*)(lds + (bufoff) + ldsw + _i * 8192), 16, 0, 0); } while (0)
; #define PG8_LDA(dst, b, h) do { _Pragma("unroll") for (int m = 0; m < 4; ++m) _Pragma("unroll") for (int k = 0; k < 2; ++k) dst[m][k] = *(const LAS bf16x8*)(lds + PG8_SA(b, h) + aoff + m * 2048 + k * 1024); } while (0)
; #define PG8_LDB(dst, b, h) do { _Pragma("unroll") for (int n = 0; n < 2; ++n) _Pragma("unroll") for (int k = 0; k < 2; ++k) dst[n][k] = *(const LAS bf16x8*)(lds + PG8_SB(b, h) + boff + n * 2048 + k * 1024); } while (0)
; #define PG8_MMA(ai, bj, At, Bt) do { __builtin_amdgcn_s_setprio(1); _Pragma("unroll") for (int m = 0; m < 4; ++m) _Pragma("unroll") for (int n = 0; n < 2; ++n) _Pragma("unroll") for (int k = 0; k < 2; ++k) \
;     acc[ai][bj][m][n] = __builtin_amdgcn_mfma_f32_16x16x32_bf16(Bt[n][k], At[m][k], acc[ai][bj][m][n], 0, 0, 0); __builtin_amdgcn_s_setprio(0); } while (0)
; #define PG8_WAIT_V(n) asm volatile("s_waitcnt vmcnt(" #n ")" ::: "memory")
; #define PG8_WAIT_L(n) asm volatile("s_waitcnt lgkmcnt(" #n ")" ::: "memory")
; #define PG8_BAR __builtin_amdgcn_s_barrier()
; #define PG8_SCHED __builtin_amdgcn_sched_barrier(0)
; template <class Epi, class Sched>
; DI void gemm_phase(LAS unsigned char* lds, const Gemm g, const Sched& S, const Epi& E) {
;     ...
;       PG8_STAGE(PG8_SB(0, 1), b2 + hstep, voffB);
;       PG8_WAIT_V(6); PG8_BAR; PG8_MMA(1, 1, At, B1); PG8_BAR;
;       PG8_LDB(B0, 1, 0); PG8_SCHED; PG8_LDA(At, 1, 0); PG8_STAGE(PG8_SA(0, 1), a2 + hstep, voffA);
;       PG8_WAIT_L(8); PG8_BAR; PG8_WAIT_L(0); PG8_MMA(0, 0, At, B0); PG8_BAR; PG8_SCHED;
;       PG8_LDB(B1, 1, 1); PG8_STAGE(PG8_SB(1, 0), b3, voffB);
;       PG8_BAR; PG8_WAIT_L(0); PG8_MMA(0, 1, At, B1); PG8_BAR;
;       PG8_LDA(At, 1, 1); PG8_STAGE(PG8_SA(1, 0), a3, voffA);
	s_add_u32 s52, s4, 0x40000
	s_addc_u32 s53, s5, 0
	s_add_i32 s51, s54, s34
	v_lshl_add_u64 v[128:129], s[52:53], 0, v[136:137]
	s_mov_b32 m0, s51
	s_nop 0
	global_load_lds_dwordx4 v[128:129], off
	v_lshl_add_u64 v[128:129], s[52:53], 0, v[132:133]
	s_add_i32 m0, s51, 0x2000
	s_nop 0
	global_load_lds_dwordx4 v[128:129], off
	s_waitcnt vmcnt(6)
	s_barrier
	v_mfma_f32_16x16x32_bf16 v[52:55], v[212:215], v[164:167], v[52:55]
	v_mfma_f32_16x16x32_bf16 v[48:51], v[220:223], v[164:167], v[48:51]
	v_mfma_f32_16x16x32_bf16 v[36:39], v[212:215], v[172:175], v[36:39]
	v_mfma_f32_16x16x32_bf16 v[32:35], v[220:223], v[172:175], v[32:35]
	v_mfma_f32_16x16x32_bf16 v[20:23], v[212:215], v[196:199], v[20:23]
	v_mfma_f32_16x16x32_bf16 v[16:19], v[220:223], v[196:199], v[16:19]
	v_mfma_f32_16x16x32_bf16 v[4:7], v[212:215], v[204:207], v[4:7]
	v_mfma_f32_16x16x32_bf16 v[0:3], v[220:223], v[204:207], v[0:3]
	v_mfma_f32_16x16x32_bf16 v[52:55], v[216:219], v[168:171], v[52:55]
	v_mfma_f32_16x16x32_bf16 v[48:51], v[224:227], v[168:171], v[48:51]
	v_mfma_f32_16x16x32_bf16 v[36:39], v[216:219], v[176:179], v[36:39]
	v_mfma_f32_16x16x32_bf16 v[32:35], v[224:227], v[176:179], v[32:35]
	v_mfma_f32_16x16x32_bf16 v[20:23], v[216:219], v[200:203], v[20:23]
	v_mfma_f32_16x16x32_bf16 v[16:19], v[224:227], v[200:203], v[16:19]
	v_mfma_f32_16x16x32_bf16 v[4:7], v[216:219], v[208:211], v[4:7]
	v_mfma_f32_16x16x32_bf16 v[0:3], v[224:227], v[208:211], v[0:3]
	s_add_i32 s51, 0, 0x18000
	v_add_u32_e32 v144, s51, v155
	s_barrier
	ds_read_b128 v[128:131], v144
	ds_read_b128 v[146:149], v144 offset:1024
	ds_read_b128 v[150:153], v144 offset:2048
	ds_read_b128 v[160:163], v144 offset:3072
	s_add_u32 s20, s20, 0x40000
	s_addc_u32 s21, s21, 0
	s_mov_b32 m0, s42
	v_lshl_add_u64 v[212:213], s[20:21], 0, v[138:139]
	ds_read_b128 v[164:167], v158 offset:32768
	ds_read_b128 v[168:171], v158 offset:33792
	ds_read_b128 v[172:175], v158 offset:34816
	ds_read_b128 v[176:179], v158 offset:35840
	ds_read_b128 v[196:199], v158 offset:36864
	ds_read_b128 v[200:203], v158 offset:37888
	ds_read_b128 v[204:207], v158 offset:38912
	ds_read_b128 v[208:211], v158 offset:39936
	global_load_lds_dwordx4 v[212:213], off
	v_lshl_add_u64 v[212:213], s[20:21], 0, v[134:135]
	s_mov_b32 m0, s43
	s_nop 0
	global_load_lds_dwordx4 v[212:213], off
	s_waitcnt lgkmcnt(8)
	s_barrier
	s_waitcnt lgkmcnt(0)
	s_waitcnt lgkmcnt(0)
	v_mfma_f32_16x16x32_bf16 v[124:127], v[128:131], v[164:167], v[124:127]
	v_mfma_f32_16x16x32_bf16 v[120:123], v[150:153], v[164:167], v[120:123]
	v_mfma_f32_16x16x32_bf16 v[108:111], v[128:131], v[172:175], v[108:111]
	v_mfma_f32_16x16x32_bf16 v[104:107], v[150:153], v[172:175], v[104:107]
	v_mfma_f32_16x16x32_bf16 v[92:95], v[128:131], v[196:199], v[92:95]
	v_mfma_f32_16x16x32_bf16 v[88:91], v[150:153], v[196:199], v[88:91]
	v_mfma_f32_16x16x32_bf16 v[76:79], v[128:131], v[204:207], v[76:79]
	v_mfma_f32_16x16x32_bf16 v[72:75], v[150:153], v[204:207], v[72:75]
	v_mfma_f32_16x16x32_bf16 v[124:127], v[146:149], v[168:171], v[124:127]
	v_mfma_f32_16x16x32_bf16 v[120:123], v[160:163], v[168:171], v[120:123]
	v_mfma_f32_16x16x32_bf16 v[108:111], v[146:149], v[176:179], v[108:111]
	v_mfma_f32_16x16x32_bf16 v[104:107], v[160:163], v[176:179], v[104:107]
	v_mfma_f32_16x16x32_bf16 v[92:95], v[146:149], v[200:203], v[92:95]
	v_mfma_f32_16x16x32_bf16 v[88:91], v[160:163], v[200:203], v[88:91]
	v_mfma_f32_16x16x32_bf16 v[76:79], v[146:149], v[208:211], v[76:79]
	v_mfma_f32_16x16x32_bf16 v[72:75], v[160:163], v[208:211], v[72:75]
	s_barrier
	s_add_i32 s20, 0, 0x1c000
	s_add_i32 s21, s51, s34
	v_add_u32_e32 v144, s20, v155
	v_lshl_add_u64 v[156:157], v[156:157], 0, s[0:1]
	s_mov_b32 m0, s21
	ds_read_b128 v[212:215], v144
	ds_read_b128 v[216:219], v144 offset:1024
	ds_read_b128 v[220:223], v144 offset:2048
	ds_read_b128 v[224:227], v144 offset:3072
	global_load_lds_dwordx4 v[156:157], off
	v_lshl_add_u64 v[156:157], v[180:181], 0, s[0:1]
	s_add_i32 m0, s21, 0x2000
	s_nop 0
	global_load_lds_dwordx4 v[156:157], off
	s_barrier
	s_waitcnt lgkmcnt(0)
	s_waitcnt lgkmcnt(0)
	v_mfma_f32_16x16x32_bf16 v[116:119], v[212:215], v[164:167], v[116:119]
	v_mfma_f32_16x16x32_bf16 v[112:115], v[220:223], v[164:167], v[112:115]
	v_mfma_f32_16x16x32_bf16 v[100:103], v[212:215], v[172:175], v[100:103]
	v_mfma_f32_16x16x32_bf16 v[96:99], v[220:223], v[172:175], v[96:99]
	v_mfma_f32_16x16x32_bf16 v[84:87], v[212:215], v[196:199], v[84:87]
	v_mfma_f32_16x16x32_bf16 v[80:83], v[220:223], v[196:199], v[80:83]
	v_mfma_f32_16x16x32_bf16 v[68:71], v[212:215], v[204:207], v[68:71]
	v_mfma_f32_16x16x32_bf16 v[64:67], v[220:223], v[204:207], v[64:67]
	v_mfma_f32_16x16x32_bf16 v[116:119], v[216:219], v[168:171], v[116:119]
	v_mfma_f32_16x16x32_bf16 v[112:115], v[224:227], v[168:171], v[112:115]
	v_mfma_f32_16x16x32_bf16 v[100:103], v[216:219], v[176:179], v[100:103]
	v_mfma_f32_16x16x32_bf16 v[96:99], v[224:227], v[176:179], v[96:99]
	v_mfma_f32_16x16x32_bf16 v[84:87], v[216:219], v[200:203], v[84:87]
	v_mfma_f32_16x16x32_bf16 v[80:83], v[224:227], v[200:203], v[80:83]
	v_mfma_f32_16x16x32_bf16 v[68:71], v[216:219], v[208:211], v[68:71]
	v_mfma_f32_16x16x32_bf16 v[64:67], v[224:227], v[208:211], v[64:67]
	s_mov_b32 m0, s46
	v_lshl_add_u64 v[156:157], v[228:229], 0, s[0:1]
	s_barrier
; #define PG8_STAGE(bufoff, gbase, voff) do { _Pragma("unroll") for (int _i = 0; _i < 2; ++_i) \
;     __builtin_amdgcn_global_load_lds((const unsigned*)((const char*)(gbase) + (voff)[_i]), (LAS unsigned*)(lds + (bufoff) + ldsw + _i * 8192), 16, 0, 0); } while (0)
; #define PG8_LDA(dst, b, h) do { _Pragma("unroll") for (int m = 0; m < 4; ++m) _Pragma("unroll") for (int k = 0; k < 2; ++k) dst[m][k] = *(const LAS bf16x8*)(lds + PG8_SA(b, h) + aoff + m * 2048 + k * 1024); } while (0)
; #define PG8_MMA(ai, bj, At, Bt) do { __builtin_amdgcn_s_setprio(1); _Pragma("unroll") for (int m = 0; m < 4; ++m) _Pragma("unroll") for (int n = 0; n < 2; ++n) _Pragma("unroll") for (int k = 0; k < 2; ++k) \
;     acc[ai][bj][m][n] = __builtin_amdgcn_mfma_f32_16x16x32_bf16(Bt[n][k], At[m][k], acc[ai][bj][m][n], 0, 0, 0); __builtin_amdgcn_s_setprio(0); } while (0)
; #define PG8_WAIT_V(n) asm volatile("s_waitcnt vmcnt(" #n ")" ::: "memory")
; #define PG8_WAIT_L(n) asm volatile("s_waitcnt lgkmcnt(" #n ")" ::: "memory")
; #define PG8_BAR __builtin_amdgcn_s_barrier()
; #define PG8_SCHED __builtin_amdgcn_sched_barrier(0)
; template <class Epi, class Sched>
; DI void gemm_phase(LAS unsigned char* lds, const Gemm g, const Sched& S, const Epi& E) {
;     ...
;       PG8_LDA(At, 1, 1); PG8_STAGE(PG8_SA(1, 0), a3, voffA);
;       PG8_BAR; PG8_WAIT_L(0); PG8_MMA(1, 0, At, B0); PG8_BAR; PG8_SCHED;
;       PG8_STAGE(PG8_SB(1, 1), b3 + hstep, voffB);
;       PG8_WAIT_V(6); PG8_BAR; PG8_MMA(1, 1, At, B1); PG8_BAR;
;     }
;     E(acc, cur, wr, wc, fr, fq);
;   DI void operator()(const f32x4 (&acc)[2][2][4][2], const pg8::Unit& u, int wr, int wc, int fr_, int fq_) const {
;     ...
;             } else if (EPI == EPI_CIN) {
;               if (n == 0) {
;                 const int gb = u.pn * 256 + bj * 128 + wc * 32;
;                 const int f8 = gb + 8 * fq;
;                 const f32x4 v1 = acc[ai][bj][m][1];
;                 if (gb < 1024) st_bf8((u16*)(big + O_QD) + (size_t)token * 1024 + f8, v, v1, rinv * (0.125f * LOG2E));
;                 else if (gb < 2048) st_bf8((u16*)(big + O_KD) + (size_t)token * 1024 + (f8 - 1024), v, v1, rinv);
;                 else st_bf8((u16*)(big + O_VDT) + (size_t)token * 1024 + (f8 - 2048), v, v1, rinv);
;               }
	ds_read_b128 v[164:167], v158 offset:49152
	ds_read_b128 v[168:171], v158 offset:50176
	ds_read_b128 v[172:175], v158 offset:51200
	ds_read_b128 v[176:179], v158 offset:52224
	ds_read_b128 v[196:199], v158 offset:53248
	ds_read_b128 v[200:203], v158 offset:54272
	ds_read_b128 v[204:207], v158 offset:55296
	ds_read_b128 v[208:211], v158 offset:56320
	global_load_lds_dwordx4 v[156:157], off
	v_lshl_add_u64 v[156:157], v[230:231], 0, s[0:1]
	s_mov_b32 m0, s47
	s_nop 0
	global_load_lds_dwordx4 v[156:157], off
	s_barrier
	s_waitcnt lgkmcnt(0)
	s_waitcnt lgkmcnt(0)
	v_mfma_f32_16x16x32_bf16 v[60:63], v[128:131], v[164:167], v[60:63]
	v_mfma_f32_16x16x32_bf16 v[56:59], v[150:153], v[164:167], v[56:59]
	v_mfma_f32_16x16x32_bf16 v[44:47], v[128:131], v[172:175], v[44:47]
	v_mfma_f32_16x16x32_bf16 v[40:43], v[150:153], v[172:175], v[40:43]
	v_mfma_f32_16x16x32_bf16 v[28:31], v[128:131], v[196:199], v[28:31]
	v_mfma_f32_16x16x32_bf16 v[24:27], v[150:153], v[196:199], v[24:27]
	v_mfma_f32_16x16x32_bf16 v[12:15], v[128:131], v[204:207], v[12:15]
	v_mfma_f32_16x16x32_bf16 v[8:11], v[150:153], v[204:207], v[8:11]
	v_mfma_f32_16x16x32_bf16 v[60:63], v[146:149], v[168:171], v[60:63]
	v_mfma_f32_16x16x32_bf16 v[56:59], v[160:163], v[168:171], v[56:59]
	v_mfma_f32_16x16x32_bf16 v[44:47], v[146:149], v[176:179], v[44:47]
	v_mfma_f32_16x16x32_bf16 v[40:43], v[160:163], v[176:179], v[40:43]
	v_mfma_f32_16x16x32_bf16 v[28:31], v[146:149], v[200:203], v[28:31]
	v_mfma_f32_16x16x32_bf16 v[24:27], v[160:163], v[200:203], v[24:27]
	v_mfma_f32_16x16x32_bf16 v[12:15], v[146:149], v[208:211], v[12:15]
	v_mfma_f32_16x16x32_bf16 v[8:11], v[160:163], v[208:211], v[8:11]
	s_barrier
	s_add_u32 s4, s4, 0x40080
	s_addc_u32 s5, s5, 0
	s_add_i32 s20, s20, s34
	v_lshl_add_u64 v[128:129], s[4:5], 0, v[136:137]
	s_mov_b32 m0, s20
	s_nop 0
	global_load_lds_dwordx4 v[128:129], off
	v_lshl_add_u64 v[128:129], s[4:5], 0, v[132:133]
	s_add_i32 m0, s20, 0x2000
	s_nop 0
	global_load_lds_dwordx4 v[128:129], off
	s_waitcnt vmcnt(6)
	s_barrier
	v_mfma_f32_16x16x32_bf16 v[52:55], v[212:215], v[164:167], v[52:55]
	v_mfma_f32_16x16x32_bf16 v[48:51], v[220:223], v[164:167], v[48:51]
	v_mfma_f32_16x16x32_bf16 v[36:39], v[212:215], v[172:175], v[36:39]
	v_mfma_f32_16x16x32_bf16 v[32:35], v[220:223], v[172:175], v[32:35]
	v_mfma_f32_16x16x32_bf16 v[20:23], v[212:215], v[196:199], v[20:23]
	v_mfma_f32_16x16x32_bf16 v[16:19], v[220:223], v[196:199], v[16:19]
	v_mfma_f32_16x16x32_bf16 v[4:7], v[212:215], v[204:207], v[4:7]
	v_mfma_f32_16x16x32_bf16 v[0:3], v[220:223], v[204:207], v[0:3]
	v_mfma_f32_16x16x32_bf16 v[52:55], v[216:219], v[168:171], v[52:55]
	v_mfma_f32_16x16x32_bf16 v[48:51], v[224:227], v[168:171], v[48:51]
	v_mfma_f32_16x16x32_bf16 v[36:39], v[216:219], v[176:179], v[36:39]
	v_mfma_f32_16x16x32_bf16 v[32:35], v[224:227], v[176:179], v[32:35]
	v_mfma_f32_16x16x32_bf16 v[20:23], v[216:219], v[200:203], v[20:23]
	v_mfma_f32_16x16x32_bf16 v[16:19], v[224:227], v[200:203], v[16:19]
	v_mfma_f32_16x16x32_bf16 v[4:7], v[216:219], v[208:211], v[4:7]
	v_mfma_f32_16x16x32_bf16 v[0:3], v[224:227], v[208:211], v[0:3]
	s_add_i32 s50, s50, 2
	s_add_u32 s2, s2, 0x100
	s_addc_u32 s3, s3, 0
	s_add_u32 s37, s37, 0x100
	s_addc_u32 s49, s49, 0
	s_cmp_gt_u32 s50, 13
	s_barrier
	s_cbranch_scc0 .LBB0_370
	v_mov_b32_e32 v128, v182
	s_lshl_b32 s2, s22, 10
	v_and_or_b32 v160, v128, 15, s44
	v_lshrrev_b32_e32 v128, 1, v128
	s_add_i32 s2, s2, 0
	v_and_b32_e32 v146, 24, v128
	v_lshl_add_u32 v128, v160, 2, s2
	v_add_u32_e32 v159, 0x20000, v128
	s_lshl_b32 s13, s28, 8
	s_lshl_b32 s3, s23, 8
	ds_read_b32 v154, v159
	v_add_u32_e32 v150, s13, v160
	s_or_b32 s20, s3, s45
	v_ashrrev_i32_e32 v151, 31, v150
	s_cmpk_gt_i32 s20, 0x3ff
	v_lshlrev_b64 v[128:129], 11, v[150:151]
	v_or_b32_e32 v148, s20, v146
	s_cselect_b64 s[4:5], -1, 0
	s_cmpk_gt_u32 s3, 0x7ff
	s_cselect_b64 s[2:3], -1, 0
	v_mov_b32_e32 v144, v148
	v_lshl_add_u64 v[152:153], s[10:11], 0, v[128:129]
	s_mov_b64 s[22:23], -1
	s_and_b64 vcc, exec, s[4:5]
	s_cbranch_vccz .LBB0_377
	s_waitcnt lgkmcnt(0)
	v_pk_mul_f32 v[128:129], v[124:125], v[154:155] op_sel_hi:[1,0]
	v_pk_mul_f32 v[130:131], v[126:127], v[154:155] op_sel_hi:[1,0]
	v_cvt_pk_bf16_f32 v128, v128, v129
	v_cvt_pk_bf16_f32 v129, v130, v131
	v_pk_mul_f32 v[130:131], v[120:121], v[154:155] op_sel_hi:[1,0]
	v_pk_mul_f32 v[162:163], v[122:123], v[154:155] op_sel_hi:[1,0]
	v_lshl_add_u64 v[156:157], v[144:145], 1, v[152:153]
	v_cvt_pk_bf16_f32 v130, v130, v131
	v_cvt_pk_bf16_f32 v131, v162, v163
	s_and_b64 vcc, exec, s[2:3]
	s_cbranch_vccz .LBB0_374
	v_add_co_u32_e32 v162, vcc, 0x7fff000, v156
	s_mov_b64 s[22:23], 0
	s_nop 0
	v_addc_co_u32_e32 v163, vcc, 0, v157, vcc
	global_store_dwordx4 v[162:163], v[128:131], off

; #define PG8_STAGE(bufoff, gbase, voff) do { _Pragma("unroll") for (int _i = 0; _i < 2; ++_i) \
;     __builtin_amdgcn_global_load_lds((const unsigned*)((const char*)(gbase) + (voff)[_i]), (LAS unsigned*)(lds + (bufoff) + ldsw + _i * 8192), 16, 0, 0); } while (0)
; #define PG8_LDA(dst, b, h) do { _Pragma("unroll") for (int m = 0; m < 4; ++m) _Pragma("unroll") for (int k = 0; k < 2; ++k) dst[m][k] = *(const LAS bf16x8*)(lds + PG8_SA(b, h) + aoff + m * 2048 + k * 1024); } while (0)
; #define PG8_LDB(dst, b, h) do { _Pragma("unroll") for (int n = 0; n < 2; ++n) _Pragma("unroll") for (int k = 0; k < 2; ++k) dst[n][k] = *(const LAS bf16x8*)(lds + PG8_SB(b, h) + boff + n * 2048 + k * 1024); } while (0)
; #define PG8_MMA(ai, bj, At, Bt) do { __builtin_amdgcn_s_setprio(1); _Pragma("unroll") for (int m = 0; m < 4; ++m) _Pragma("unroll") for (int n = 0; n < 2; ++n) _Pragma("unroll") for (int k = 0; k < 2; ++k) \
;     acc[ai][bj][m][n] = __builtin_amdgcn_mfma_f32_16x16x32_bf16(Bt[n][k], At[m][k], acc[ai][bj][m][n], 0, 0, 0); __builtin_amdgcn_s_setprio(0); } while (0)
; #define PG8_WAIT_V(n) asm volatile("s_waitcnt vmcnt(" #n ")" ::: "memory")
; #define PG8_WAIT_L(n) asm volatile("s_waitcnt lgkmcnt(" #n ")" ::: "memory")
; #define PG8_BAR __builtin_amdgcn_s_barrier()
; #define PG8_SCHED __builtin_amdgcn_sched_barrier(0)
; template <class Epi, class Sched>
; DI void gemm_phase(LAS unsigned char* lds, const Gemm g, const Sched& S, const Epi& E) {
;     ...
;     for (int t = 0; t < nt; t += 2) {
;       const bool last = (t == nt - 2);
;       const char* a1 = cA + (size_t)(t + 1) * kstep;
;       const char* a2 = last ? nA : cA + (size_t)(t + 2) * kstep; const char* b2 = last ? nB : cB + (size_t)(t + 2) * kstep;
;       const char* a3 = a2 + kstep; const char* b3 = b2 + kstep;
;       PG8_LDB(B0, 0, 0); PG8_SCHED; PG8_LDA(At, 0, 0); PG8_STAGE(PG8_SA(1, 1), a1 + hstep, voffA);
;       PG8_WAIT_L(8); PG8_BAR; PG8_WAIT_L(0); PG8_MMA(0, 0, At, B0); PG8_BAR; PG8_SCHED;
;       PG8_LDB(B1, 0, 1); PG8_STAGE(PG8_SB(0, 0), b2, voffB);
;       PG8_BAR; PG8_WAIT_L(0); PG8_MMA(0, 1, At, B1); PG8_BAR;
;       PG8_LDA(At, 0, 1); PG8_STAGE(PG8_SA(0, 0), a2, voffA);
;       PG8_BAR; PG8_WAIT_L(0); PG8_MMA(1, 0, At, B0); PG8_BAR; PG8_SCHED;
;       PG8_STAGE(PG8_SB(0, 1), b2 + hstep, voffB);
;       PG8_WAIT_V(6); PG8_BAR; PG8_MMA(1, 1, At, B1); PG8_BAR;
.LBB0_689:
	s_add_u32 s22, s20, 0xfffc0080
	s_addc_u32 s23, s21, -1
	s_add_i32 s42, 0, 0x10000
	v_add_u32_e32 v144, s42, v196
	ds_read_b128 v[128:131], v144
	ds_read_b128 v[132:135], v144 offset:1024
	ds_read_b128 v[150:153], v144 offset:2048
	ds_read_b128 v[154:157], v144 offset:3072
	s_cmp_eq_u32 s41, 12
	s_cselect_b32 s29, s13, s23
	s_cselect_b32 s28, s37, s22
	s_cselect_b32 s23, s15, s40
	s_cselect_b32 s22, s38, s39
	v_lshl_add_u64 v[206:207], s[20:21], 0, v[146:147]
	s_add_i32 m0, s56, 0xc000
	ds_read_b128 v[158:161], v197
	ds_read_b128 v[162:165], v197 offset:1024
	ds_read_b128 v[166:169], v197 offset:2048
	ds_read_b128 v[170:173], v197 offset:3072
	ds_read_b128 v[174:177], v197 offset:4096
	ds_read_b128 v[178:181], v197 offset:5120
	ds_read_b128 v[198:201], v197 offset:6144
	ds_read_b128 v[202:205], v197 offset:7168
	global_load_lds_dwordx4 v[206:207], off
	v_lshl_add_u64 v[206:207], s[20:21], 0, v[148:149]
	s_add_i32 m0, s56, 0xe000
	s_nop 0
	global_load_lds_dwordx4 v[206:207], off
	s_waitcnt lgkmcnt(8)
	s_barrier
	s_waitcnt lgkmcnt(0)
	s_waitcnt lgkmcnt(0)
	v_mfma_f32_16x16x32_bf16 v[124:127], v[128:131], v[158:161], v[124:127]
	v_mfma_f32_16x16x32_bf16 v[120:123], v[150:153], v[158:161], v[120:123]
	v_mfma_f32_16x16x32_bf16 v[108:111], v[128:131], v[166:169], v[108:111]
	v_mfma_f32_16x16x32_bf16 v[104:107], v[150:153], v[166:169], v[104:107]
	v_mfma_f32_16x16x32_bf16 v[92:95], v[128:131], v[174:177], v[92:95]
	v_mfma_f32_16x16x32_bf16 v[88:91], v[150:153], v[174:177], v[88:91]
	v_mfma_f32_16x16x32_bf16 v[76:79], v[128:131], v[198:201], v[76:79]
	v_mfma_f32_16x16x32_bf16 v[72:75], v[150:153], v[198:201], v[72:75]
	v_mfma_f32_16x16x32_bf16 v[124:127], v[132:135], v[162:165], v[124:127]
	v_mfma_f32_16x16x32_bf16 v[120:123], v[154:157], v[162:165], v[120:123]
	v_mfma_f32_16x16x32_bf16 v[108:111], v[132:135], v[170:173], v[108:111]
	v_mfma_f32_16x16x32_bf16 v[104:107], v[154:157], v[170:173], v[104:107]
	v_mfma_f32_16x16x32_bf16 v[92:95], v[132:135], v[178:181], v[92:95]
	v_mfma_f32_16x16x32_bf16 v[88:91], v[154:157], v[178:181], v[88:91]
	v_mfma_f32_16x16x32_bf16 v[76:79], v[132:135], v[202:205], v[76:79]
	v_mfma_f32_16x16x32_bf16 v[72:75], v[154:157], v[202:205], v[72:75]
	s_barrier
	s_add_i32 s44, 0, 0x14000
	s_add_i32 s42, s42, s52
	v_add_u32_e32 v144, s44, v196
	v_lshl_add_u64 v[222:223], s[22:23], 0, v[140:141]
	s_mov_b32 m0, s42
	ds_read_b128 v[206:209], v144
	ds_read_b128 v[210:213], v144 offset:1024
	ds_read_b128 v[214:217], v144 offset:2048
	ds_read_b128 v[218:221], v144 offset:3072
	global_load_lds_dwordx4 v[222:223], off
	v_lshl_add_u64 v[224:225], s[22:23], 0, v[136:137]
	s_add_i32 m0, s42, 0x2000
	s_nop 0
	global_load_lds_dwordx4 v[224:225], off
	s_barrier
	s_waitcnt lgkmcnt(0)
	s_waitcnt lgkmcnt(0)
	v_mfma_f32_16x16x32_bf16 v[116:119], v[206:209], v[158:161], v[116:119]
	v_mfma_f32_16x16x32_bf16 v[112:115], v[214:217], v[158:161], v[112:115]
	v_mfma_f32_16x16x32_bf16 v[100:103], v[206:209], v[166:169], v[100:103]
	v_mfma_f32_16x16x32_bf16 v[96:99], v[214:217], v[166:169], v[96:99]
	v_mfma_f32_16x16x32_bf16 v[84:87], v[206:209], v[174:177], v[84:87]
	v_mfma_f32_16x16x32_bf16 v[80:83], v[214:217], v[174:177], v[80:83]
	v_mfma_f32_16x16x32_bf16 v[68:71], v[206:209], v[198:201], v[68:71]
	v_mfma_f32_16x16x32_bf16 v[64:67], v[214:217], v[198:201], v[64:67]
	v_mfma_f32_16x16x32_bf16 v[116:119], v[210:213], v[162:165], v[116:119]
	v_mfma_f32_16x16x32_bf16 v[112:115], v[218:221], v[162:165], v[112:115]
	v_mfma_f32_16x16x32_bf16 v[100:103], v[210:213], v[170:173], v[100:103]
	v_mfma_f32_16x16x32_bf16 v[96:99], v[218:221], v[170:173], v[96:99]
	v_mfma_f32_16x16x32_bf16 v[84:87], v[210:213], v[178:181], v[84:87]
	v_mfma_f32_16x16x32_bf16 v[80:83], v[218:221], v[178:181], v[80:83]
	v_mfma_f32_16x16x32_bf16 v[68:71], v[210:213], v[202:205], v[68:71]
	v_mfma_f32_16x16x32_bf16 v[64:67], v[218:221], v[202:205], v[64:67]
	s_mov_b32 m0, s56
	v_lshl_add_u64 v[226:227], s[28:29], 0, v[142:143]
	s_barrier
	ds_read_b128 v[158:161], v197 offset:16384
	ds_read_b128 v[162:165], v197 offset:17408
	ds_read_b128 v[166:169], v197 offset:18432
	ds_read_b128 v[170:173], v197 offset:19456
	ds_read_b128 v[174:177], v197 offset:20480
	ds_read_b128 v[178:181], v197 offset:21504
	ds_read_b128 v[198:201], v197 offset:22528
	ds_read_b128 v[202:205], v197 offset:23552
	global_load_lds_dwordx4 v[226:227], off
	v_lshl_add_u64 v[228:229], s[28:29], 0, v[138:139]
	s_mov_b32 m0, s57
	s_nop 0
	global_load_lds_dwordx4 v[228:229], off
	s_barrier
	s_waitcnt lgkmcnt(0)
	s_waitcnt lgkmcnt(0)
	v_mfma_f32_16x16x32_bf16 v[60:63], v[128:131], v[158:161], v[60:63]
	v_mfma_f32_16x16x32_bf16 v[56:59], v[150:153], v[158:161], v[56:59]
	v_mfma_f32_16x16x32_bf16 v[44:47], v[128:131], v[166:169], v[44:47]
	v_mfma_f32_16x16x32_bf16 v[40:43], v[150:153], v[166:169], v[40:43]
	v_mfma_f32_16x16x32_bf16 v[28:31], v[128:131], v[174:177], v[28:31]
	v_mfma_f32_16x16x32_bf16 v[24:27], v[150:153], v[174:177], v[24:27]
	v_mfma_f32_16x16x32_bf16 v[12:15], v[128:131], v[198:201], v[12:15]
	v_mfma_f32_16x16x32_bf16 v[8:11], v[150:153], v[198:201], v[8:11]
	v_mfma_f32_16x16x32_bf16 v[60:63], v[132:135], v[162:165], v[60:63]
	v_mfma_f32_16x16x32_bf16 v[56:59], v[154:157], v[162:165], v[56:59]
	v_mfma_f32_16x16x32_bf16 v[44:47], v[132:135], v[170:173], v[44:47]
	v_mfma_f32_16x16x32_bf16 v[40:43], v[154:157], v[170:173], v[40:43]
	v_mfma_f32_16x16x32_bf16 v[28:31], v[132:135], v[178:181], v[28:31]
	v_mfma_f32_16x16x32_bf16 v[24:27], v[154:157], v[178:181], v[24:27]
	v_mfma_f32_16x16x32_bf16 v[12:15], v[132:135], v[202:205], v[12:15]
	v_mfma_f32_16x16x32_bf16 v[8:11], v[154:157], v[202:205], v[8:11]
	s_barrier
; #define PG8_STAGE(bufoff, gbase, voff) do { _Pragma("unroll") for (int _i = 0; _i < 2; ++_i) \
;     __builtin_amdgcn_global_load_lds((const unsigned*)((const char*)(gbase) + (voff)[_i]), (LAS unsigned*)(lds + (bufoff) + ldsw + _i * 8192), 16, 0, 0); } while (0)
; #define PG8_LDA(dst, b, h) do { _Pragma("unroll") for (int m = 0; m < 4; ++m) _Pragma("unroll") for (int k = 0; k < 2; ++k) dst[m][k] = *(const LAS bf16x8*)(lds + PG8_SA(b, h) + aoff + m * 2048 + k * 1024); } while (0)
; #define PG8_LDB(dst, b, h) do { _Pragma("unroll") for (int n = 0; n < 2; ++n) _Pragma("unroll") for (int k = 0; k < 2; ++k) dst[n][k] = *(const LAS bf16x8*)(lds + PG8_SB(b, h) + boff + n * 2048 + k * 1024); } while (0)
; #define PG8_MMA(ai, bj, At, Bt) do { __builtin_amdgcn_s_setprio(1); _Pragma("unroll") for (int m = 0; m < 4; ++m) _Pragma("unroll") for (int n = 0; n < 2; ++n) _Pragma("unroll") for (int k = 0; k < 2; ++k) \
;     acc[ai][bj][m][n] = __builtin_amdgcn_mfma_f32_16x16x32_bf16(Bt[n][k], At[m][k], acc[ai][bj][m][n], 0, 0, 0); __builtin_amdgcn_s_setprio(0); } while (0)
; #define PG8_WAIT_V(n) asm volatile("s_waitcnt vmcnt(" #n ")" ::: "memory")
; #define PG8_WAIT_L(n) asm volatile("s_waitcnt lgkmcnt(" #n ")" ::: "memory")
; #define PG8_BAR __builtin_amdgcn_s_barrier()
; #define PG8_SCHED __builtin_amdgcn_sched_barrier(0)
; template <class Epi, class Sched>
; DI void gemm_phase(LAS unsigned char* lds, const Gemm g, const Sched& S, const Epi& E) {
;     ...
;       PG8_STAGE(PG8_SB(0, 1), b2 + hstep, voffB);
;       PG8_WAIT_V(6); PG8_BAR; PG8_MMA(1, 1, At, B1); PG8_BAR;
;       PG8_LDB(B0, 1, 0); PG8_SCHED; PG8_LDA(At, 1, 0); PG8_STAGE(PG8_SA(0, 1), a2 + hstep, voffA);
;       PG8_WAIT_L(8); PG8_BAR; PG8_WAIT_L(0); PG8_MMA(0, 0, At, B0); PG8_BAR; PG8_SCHED;
;       PG8_LDB(B1, 1, 1); PG8_STAGE(PG8_SB(1, 0), b3, voffB);
;       PG8_BAR; PG8_WAIT_L(0); PG8_MMA(0, 1, At, B1); PG8_BAR;
;       PG8_LDA(At, 1, 1); PG8_STAGE(PG8_SA(1, 0), a3, voffA);
	s_add_u32 s42, s22, 0x40000
	s_addc_u32 s43, s23, 0
	s_add_i32 s44, s44, s52
	v_lshl_add_u64 v[128:129], s[42:43], 0, v[140:141]
	s_mov_b32 m0, s44
	s_nop 0
	global_load_lds_dwordx4 v[128:129], off
	v_lshl_add_u64 v[128:129], s[42:43], 0, v[136:137]
	s_add_i32 m0, s44, 0x2000
	s_nop 0
	global_load_lds_dwordx4 v[128:129], off
	s_waitcnt vmcnt(6)
	s_barrier
	v_mfma_f32_16x16x32_bf16 v[52:55], v[206:209], v[158:161], v[52:55]
	v_mfma_f32_16x16x32_bf16 v[48:51], v[214:217], v[158:161], v[48:51]
	v_mfma_f32_16x16x32_bf16 v[36:39], v[206:209], v[166:169], v[36:39]
	v_mfma_f32_16x16x32_bf16 v[32:35], v[214:217], v[166:169], v[32:35]
	v_mfma_f32_16x16x32_bf16 v[20:23], v[206:209], v[174:177], v[20:23]
	v_mfma_f32_16x16x32_bf16 v[16:19], v[214:217], v[174:177], v[16:19]
	v_mfma_f32_16x16x32_bf16 v[4:7], v[206:209], v[198:201], v[4:7]
	v_mfma_f32_16x16x32_bf16 v[0:3], v[214:217], v[198:201], v[0:3]
	v_mfma_f32_16x16x32_bf16 v[52:55], v[210:213], v[162:165], v[52:55]
	v_mfma_f32_16x16x32_bf16 v[48:51], v[218:221], v[162:165], v[48:51]
	v_mfma_f32_16x16x32_bf16 v[36:39], v[210:213], v[170:173], v[36:39]
	v_mfma_f32_16x16x32_bf16 v[32:35], v[218:221], v[170:173], v[32:35]
	v_mfma_f32_16x16x32_bf16 v[20:23], v[210:213], v[178:181], v[20:23]
	v_mfma_f32_16x16x32_bf16 v[16:19], v[218:221], v[178:181], v[16:19]
	v_mfma_f32_16x16x32_bf16 v[4:7], v[210:213], v[202:205], v[4:7]
	v_mfma_f32_16x16x32_bf16 v[0:3], v[218:221], v[202:205], v[0:3]
	s_add_i32 s42, 0, 0x18000
	v_add_u32_e32 v144, s42, v196
	s_barrier
	ds_read_b128 v[128:131], v144
	ds_read_b128 v[132:135], v144 offset:1024
	ds_read_b128 v[150:153], v144 offset:2048
	ds_read_b128 v[154:157], v144 offset:3072
	s_add_u32 s28, s28, 0x40000
	s_addc_u32 s29, s29, 0
	s_mov_b32 m0, s58
	v_lshl_add_u64 v[206:207], s[28:29], 0, v[142:143]
	ds_read_b128 v[158:161], v197 offset:32768
	ds_read_b128 v[162:165], v197 offset:33792
	ds_read_b128 v[166:169], v197 offset:34816
	ds_read_b128 v[170:173], v197 offset:35840
	ds_read_b128 v[174:177], v197 offset:36864
	ds_read_b128 v[178:181], v197 offset:37888
	ds_read_b128 v[198:201], v197 offset:38912
	ds_read_b128 v[202:205], v197 offset:39936
	global_load_lds_dwordx4 v[206:207], off
	v_lshl_add_u64 v[206:207], s[28:29], 0, v[138:139]
	s_mov_b32 m0, s59
	s_nop 0
	global_load_lds_dwordx4 v[206:207], off
	s_waitcnt lgkmcnt(8)
	s_barrier
	s_waitcnt lgkmcnt(0)
	s_waitcnt lgkmcnt(0)
	v_mfma_f32_16x16x32_bf16 v[124:127], v[128:131], v[158:161], v[124:127]
	v_mfma_f32_16x16x32_bf16 v[120:123], v[150:153], v[158:161], v[120:123]
	v_mfma_f32_16x16x32_bf16 v[108:111], v[128:131], v[166:169], v[108:111]
	v_mfma_f32_16x16x32_bf16 v[104:107], v[150:153], v[166:169], v[104:107]
	v_mfma_f32_16x16x32_bf16 v[92:95], v[128:131], v[174:177], v[92:95]
	v_mfma_f32_16x16x32_bf16 v[88:91], v[150:153], v[174:177], v[88:91]
	v_mfma_f32_16x16x32_bf16 v[76:79], v[128:131], v[198:201], v[76:79]
	v_mfma_f32_16x16x32_bf16 v[72:75], v[150:153], v[198:201], v[72:75]
	v_mfma_f32_16x16x32_bf16 v[124:127], v[132:135], v[162:165], v[124:127]
	v_mfma_f32_16x16x32_bf16 v[120:123], v[154:157], v[162:165], v[120:123]
	v_mfma_f32_16x16x32_bf16 v[108:111], v[132:135], v[170:173], v[108:111]
	v_mfma_f32_16x16x32_bf16 v[104:107], v[154:157], v[170:173], v[104:107]
	v_mfma_f32_16x16x32_bf16 v[92:95], v[132:135], v[178:181], v[92:95]
	v_mfma_f32_16x16x32_bf16 v[88:91], v[154:157], v[178:181], v[88:91]
	v_mfma_f32_16x16x32_bf16 v[76:79], v[132:135], v[202:205], v[76:79]
	v_mfma_f32_16x16x32_bf16 v[72:75], v[154:157], v[202:205], v[72:75]
	s_barrier
	s_add_i32 s28, 0, 0x1c000
	s_add_i32 s29, s42, s52
	v_add_u32_e32 v144, s28, v196
	v_lshl_add_u64 v[222:223], v[222:223], 0, s[0:1]
	s_mov_b32 m0, s29
	ds_read_b128 v[206:209], v144
	ds_read_b128 v[210:213], v144 offset:1024
	ds_read_b128 v[214:217], v144 offset:2048
	ds_read_b128 v[218:221], v144 offset:3072
	global_load_lds_dwordx4 v[222:223], off
	v_lshl_add_u64 v[222:223], v[224:225], 0, s[0:1]
	s_add_i32 m0, s29, 0x2000
	s_nop 0
	global_load_lds_dwordx4 v[222:223], off
	s_barrier
	s_waitcnt lgkmcnt(0)
	s_waitcnt lgkmcnt(0)
	v_mfma_f32_16x16x32_bf16 v[116:119], v[206:209], v[158:161], v[116:119]
	v_mfma_f32_16x16x32_bf16 v[112:115], v[214:217], v[158:161], v[112:115]
	v_mfma_f32_16x16x32_bf16 v[100:103], v[206:209], v[166:169], v[100:103]
	v_mfma_f32_16x16x32_bf16 v[96:99], v[214:217], v[166:169], v[96:99]
	v_mfma_f32_16x16x32_bf16 v[84:87], v[206:209], v[174:177], v[84:87]
	v_mfma_f32_16x16x32_bf16 v[80:83], v[214:217], v[174:177], v[80:83]
	v_mfma_f32_16x16x32_bf16 v[68:71], v[206:209], v[198:201], v[68:71]
	v_mfma_f32_16x16x32_bf16 v[64:67], v[214:217], v[198:201], v[64:67]
	v_mfma_f32_16x16x32_bf16 v[116:119], v[210:213], v[162:165], v[116:119]
	v_mfma_f32_16x16x32_bf16 v[112:115], v[218:221], v[162:165], v[112:115]
	v_mfma_f32_16x16x32_bf16 v[100:103], v[210:213], v[170:173], v[100:103]
	v_mfma_f32_16x16x32_bf16 v[96:99], v[218:221], v[170:173], v[96:99]
	v_mfma_f32_16x16x32_bf16 v[84:87], v[210:213], v[178:181], v[84:87]
	v_mfma_f32_16x16x32_bf16 v[80:83], v[218:221], v[178:181], v[80:83]
	v_mfma_f32_16x16x32_bf16 v[68:71], v[210:213], v[202:205], v[68:71]
	v_mfma_f32_16x16x32_bf16 v[64:67], v[218:221], v[202:205], v[64:67]
	s_mov_b32 m0, s62
	v_lshl_add_u64 v[222:223], v[226:227], 0, s[0:1]
	s_barrier
; #define PG8_STAGE(bufoff, gbase, voff) do { _Pragma("unroll") for (int _i = 0; _i < 2; ++_i) \
;     __builtin_amdgcn_global_load_lds((const unsigned*)((const char*)(gbase) + (voff)[_i]), (LAS unsigned*)(lds + (bufoff) + ldsw + _i * 8192), 16, 0, 0); } while (0)
; #define PG8_LDA(dst, b, h) do { _Pragma("unroll") for (int m = 0; m < 4; ++m) _Pragma("unroll") for (int k = 0; k < 2; ++k) dst[m][k] = *(const LAS bf16x8*)(lds + PG8_SA(b, h) + aoff + m * 2048 + k * 1024); } while (0)
; #define PG8_WAIT_V(n) asm volatile("s_waitcnt vmcnt(" #n ")" ::: "memory")
; #define PG8_WAIT_L(n) asm volatile("s_waitcnt lgkmcnt(" #n ")" ::: "memory")
; #define PG8_BAR __builtin_amdgcn_s_barrier()
; #define PG8_SCHED __builtin_amdgcn_sched_barrier(0)
; template <class Epi, class Sched>
; DI void gemm_phase(LAS unsigned char* lds, const Gemm g, const Sched& S, const Epi& E) {
;     ...
;       PG8_LDA(At, 1, 1); PG8_STAGE(PG8_SA(1, 0), a3, voffA);
;       PG8_BAR; PG8_WAIT_L(0); PG8_MMA(1, 0, At, B0); PG8_BAR; PG8_SCHED;
;       PG8_STAGE(PG8_SB(1, 1), b3 + hstep, voffB);
;       PG8_WAIT_V(6); PG8_BAR; PG8_MMA(1, 1, At, B1); PG8_BAR;
;     }
;     E(acc, cur, wr, wc, fr, fq);
;   DI void operator()(const f32x4 (&acc)[2][2][4][2], const pg8::Unit& u, int wr, int wc, int fr_, int fq_) const {
;     ...
;             if (EPI == EPI_ABIN) {
;               if (n == 0) {
;                 const int gb = u.pn * 256 + bj * 128 + wc * 32; const int f8 = gb + 8 * fq;
;                 const f32x4 v1 = acc[ai][bj][m][1];
;                 if (gb < 384) st_bf8((u16*)(big + E_CQ) + (size_t)token * 384 + f8, v, v1, rinv);
;                 else if (gb < 640) st_bf8((u16*)(big + E_CKV) + (size_t)token * 256 + (f8 - 384), v, v1, rinv);
;                 else if (gb < 672) {
;                   f32x4 a0 = v, a1 = v1;
;                   rope_perm(a0, a1, fq, t_ & 63, tcos, tsin, token & (S_ - 1));
;                   st_bf8((u16*)(big + E_KPE) + (size_t)token * 32 + 8 * fq, a0, a1, rinv);
;                 }
;                 else if (gb < 1184) st_bf8((u16*)(big + E_QNA) + (size_t)token * 512 + (f8 - 672), v, v1, rinv * (0.125f * LOG2E));
;                 else if (gb < 1696) st_bf8((u16*)(big + E_KNA) + (size_t)token * 512 + (f8 - 1184), v, v1, rinv);
;                 else if (gb < 2208) st_bf8((u16*)(big + E_VNAT) + (size_t)token * 512 + (f8 - 1696), v, v1, rinv);
;               }
	ds_read_b128 v[158:161], v197 offset:49152
	ds_read_b128 v[162:165], v197 offset:50176
	ds_read_b128 v[166:169], v197 offset:51200
	ds_read_b128 v[170:173], v197 offset:52224
	ds_read_b128 v[174:177], v197 offset:53248
	ds_read_b128 v[178:181], v197 offset:54272
	ds_read_b128 v[198:201], v197 offset:55296
	ds_read_b128 v[202:205], v197 offset:56320
	global_load_lds_dwordx4 v[222:223], off
	v_lshl_add_u64 v[222:223], v[228:229], 0, s[0:1]
	s_mov_b32 m0, s63
	s_nop 0
	global_load_lds_dwordx4 v[222:223], off
	s_barrier
	s_waitcnt lgkmcnt(0)
	s_waitcnt lgkmcnt(0)
	v_mfma_f32_16x16x32_bf16 v[60:63], v[128:131], v[158:161], v[60:63]
	v_mfma_f32_16x16x32_bf16 v[56:59], v[150:153], v[158:161], v[56:59]
	v_mfma_f32_16x16x32_bf16 v[44:47], v[128:131], v[166:169], v[44:47]
	v_mfma_f32_16x16x32_bf16 v[40:43], v[150:153], v[166:169], v[40:43]
	v_mfma_f32_16x16x32_bf16 v[28:31], v[128:131], v[174:177], v[28:31]
	v_mfma_f32_16x16x32_bf16 v[24:27], v[150:153], v[174:177], v[24:27]
	v_mfma_f32_16x16x32_bf16 v[12:15], v[128:131], v[198:201], v[12:15]
	v_mfma_f32_16x16x32_bf16 v[8:11], v[150:153], v[198:201], v[8:11]
	v_mfma_f32_16x16x32_bf16 v[60:63], v[132:135], v[162:165], v[60:63]
	v_mfma_f32_16x16x32_bf16 v[56:59], v[154:157], v[162:165], v[56:59]
	v_mfma_f32_16x16x32_bf16 v[44:47], v[132:135], v[170:173], v[44:47]
	v_mfma_f32_16x16x32_bf16 v[40:43], v[154:157], v[170:173], v[40:43]
	v_mfma_f32_16x16x32_bf16 v[28:31], v[132:135], v[178:181], v[28:31]
	v_mfma_f32_16x16x32_bf16 v[24:27], v[154:157], v[178:181], v[24:27]
	v_mfma_f32_16x16x32_bf16 v[12:15], v[132:135], v[202:205], v[12:15]
	v_mfma_f32_16x16x32_bf16 v[8:11], v[154:157], v[202:205], v[8:11]
	s_barrier
	s_add_u32 s22, s22, 0x40080
	s_addc_u32 s23, s23, 0
	s_add_i32 s28, s28, s52
	v_lshl_add_u64 v[128:129], s[22:23], 0, v[140:141]
	s_mov_b32 m0, s28
	s_nop 0
	global_load_lds_dwordx4 v[128:129], off
	v_lshl_add_u64 v[128:129], s[22:23], 0, v[136:137]
	s_add_i32 m0, s28, 0x2000
	s_nop 0
	global_load_lds_dwordx4 v[128:129], off
	s_waitcnt vmcnt(6)
	s_barrier
	v_mfma_f32_16x16x32_bf16 v[52:55], v[206:209], v[158:161], v[52:55]
	v_mfma_f32_16x16x32_bf16 v[48:51], v[214:217], v[158:161], v[48:51]
	v_mfma_f32_16x16x32_bf16 v[36:39], v[206:209], v[166:169], v[36:39]
	v_mfma_f32_16x16x32_bf16 v[32:35], v[214:217], v[166:169], v[32:35]
	v_mfma_f32_16x16x32_bf16 v[20:23], v[206:209], v[174:177], v[20:23]
	v_mfma_f32_16x16x32_bf16 v[16:19], v[214:217], v[174:177], v[16:19]
	v_mfma_f32_16x16x32_bf16 v[4:7], v[206:209], v[198:201], v[4:7]
	v_mfma_f32_16x16x32_bf16 v[0:3], v[214:217], v[198:201], v[0:3]
	v_mfma_f32_16x16x32_bf16 v[52:55], v[210:213], v[162:165], v[52:55]
	v_mfma_f32_16x16x32_bf16 v[48:51], v[218:221], v[162:165], v[48:51]
	v_mfma_f32_16x16x32_bf16 v[36:39], v[210:213], v[170:173], v[36:39]
	v_mfma_f32_16x16x32_bf16 v[32:35], v[218:221], v[170:173], v[32:35]
	v_mfma_f32_16x16x32_bf16 v[20:23], v[210:213], v[178:181], v[20:23]
	v_mfma_f32_16x16x32_bf16 v[16:19], v[218:221], v[178:181], v[16:19]
	v_mfma_f32_16x16x32_bf16 v[4:7], v[210:213], v[202:205], v[4:7]
	v_mfma_f32_16x16x32_bf16 v[0:3], v[218:221], v[202:205], v[0:3]
	s_add_i32 s41, s41, 2
	s_add_u32 s20, s20, 0x100
	s_addc_u32 s21, s21, 0
	s_add_u32 s39, s39, 0x100
	s_addc_u32 s40, s40, 0
	s_cmp_gt_u32 s41, 13
	s_barrier
	s_cbranch_scc0 .LBB0_689
	v_mov_b32_e32 v128, v182
	s_lshl_b32 s20, s34, 10
	v_bfe_u32 v129, v128, 4, 2
	v_and_or_b32 v201, v128, 15, s60
	s_lshl_b32 s13, s35, 8
	v_lshlrev_b32_e32 v128, 2, v128
	s_movk_i32 s21, 0x80
	s_add_i32 s20, s20, 0
	s_lshl_b32 s15, s36, 8
	v_bitop3_b32 v198, v128, s21, v190 bitop3:0x6c
	v_lshl_add_u32 v128, v201, 2, s20
	s_or_b32 s20, s13, s61
	v_add_u32_e32 v200, 0x20000, v128
	s_cmpk_gt_i32 s20, 0x17f
	ds_read_b32 v156, v200
	s_cselect_b64 s[28:29], -1, 0
	s_cmpk_gt_u32 s13, 0x27f
	s_cselect_b64 s[46:47], -1, 0
	s_cmpk_gt_u32 s20, 0x29f
	s_cselect_b64 s[40:41], -1, 0
	s_cmpk_gt_u32 s20, 0x49f
	v_lshlrev_b32_e32 v144, 3, v129
	v_add_u32_e32 v154, s15, v201
	s_cselect_b64 s[34:35], -1, 0
	s_cmpk_gt_u32 s20, 0x69f
	v_ashrrev_i32_e32 v155, 31, v154
	v_lshlrev_b32_e32 v128, 4, v154
	v_or_b32_e32 v150, s20, v144
	s_cselect_b64 s[22:23], -1, 0
	s_cmpk_lt_u32 s20, 0x8a0
	v_and_b32_e32 v199, 8, v144
	v_cmp_lt_u32_e64 s[92:93], 1, v129
	v_lshlrev_b64 v[164:165], 10, v[154:155]
	s_waitcnt lgkmcnt(0)
	v_mul_f32_e32 v162, 0x3e38aa3b, v156
	v_and_b32_e32 v157, 0xfcf0, v128
	v_lshlrev_b64 v[160:161], 6, v[154:155]
	v_lshlrev_b64 v[158:159], 9, v[154:155]
	s_cselect_b64 s[20:21], -1, 0
	v_mov_b32_e32 v152, v150
	v_mov_b32_e32 v153, v145
	s_mov_b64 s[36:37], -1
	s_and_b64 vcc, exec, s[28:29]
	s_cbranch_vccz .LBB0_714
	s_and_b64 vcc, exec, s[46:47]
	s_cbranch_vccz .LBB0_711
	s_and_b64 vcc, exec, s[40:41]
	s_cbranch_vccz .LBB0_704
	s_and_b64 vcc, exec, s[34:35]
	s_cbranch_vccz .LBB0_701
	s_and_b64 vcc, exec, s[22:23]
	s_cbranch_vccz .LBB0_698
	s_andn2_b64 vcc, exec, s[20:21]
	s_cbranch_vccnz .LBB0_697
	v_lshl_add_u64 v[128:129], s[2:3], 0, v[164:165]
	v_lshl_add_u64 v[132:133], v[152:153], 1, v[128:129]
	v_pk_mul_f32 v[128:129], v[124:125], v[156:157] op_sel_hi:[1,0]
	v_pk_mul_f32 v[130:131], v[126:127], v[156:157] op_sel_hi:[1,0]
	v_cvt_pk_bf16_f32 v128, v128, v129
	v_cvt_pk_bf16_f32 v129, v130, v131
	v_pk_mul_f32 v[130:131], v[120:121], v[156:157] op_sel_hi:[1,0]
	v_pk_mul_f32 v[134:135], v[122:123], v[156:157] op_sel_hi:[1,0]
	v_add_co_u32_e32 v132, vcc, 0x69ff000, v132
	v_cvt_pk_bf16_f32 v130, v130, v131
	v_cvt_pk_bf16_f32 v131, v134, v135
	v_addc_co_u32_e32 v133, vcc, 0, v133, vcc
	global_store_dwordx4 v[132:133], v[128:131], off offset:704

; #define PG8_STAGE(bufoff, gbase, voff) do { _Pragma("unroll") for (int _i = 0; _i < 2; ++_i) \
;     __builtin_amdgcn_global_load_lds((const unsigned*)((const char*)(gbase) + (voff)[_i]), (LAS unsigned*)(lds + (bufoff) + ldsw + _i * 8192), 16, 0, 0); } while (0)
; #define PG8_LDA(dst, b, h) do { _Pragma("unroll") for (int m = 0; m < 4; ++m) _Pragma("unroll") for (int k = 0; k < 2; ++k) dst[m][k] = *(const LAS bf16x8*)(lds + PG8_SA(b, h) + aoff + m * 2048 + k * 1024); } while (0)
; #define PG8_LDB(dst, b, h) do { _Pragma("unroll") for (int n = 0; n < 2; ++n) _Pragma("unroll") for (int k = 0; k < 2; ++k) dst[n][k] = *(const LAS bf16x8*)(lds + PG8_SB(b, h) + boff + n * 2048 + k * 1024); } while (0)
; #define PG8_MMA(ai, bj, At, Bt) do { __builtin_amdgcn_s_setprio(1); _Pragma("unroll") for (int m = 0; m < 4; ++m) _Pragma("unroll") for (int n = 0; n < 2; ++n) _Pragma("unroll") for (int k = 0; k < 2; ++k) \
;     acc[ai][bj][m][n] = __builtin_amdgcn_mfma_f32_16x16x32_bf16(Bt[n][k], At[m][k], acc[ai][bj][m][n], 0, 0, 0); __builtin_amdgcn_s_setprio(0); } while (0)
; #define PG8_WAIT_V(n) asm volatile("s_waitcnt vmcnt(" #n ")" ::: "memory")
; #define PG8_WAIT_L(n) asm volatile("s_waitcnt lgkmcnt(" #n ")" ::: "memory")
; #define PG8_BAR __builtin_amdgcn_s_barrier()
; #define PG8_SCHED __builtin_amdgcn_sched_barrier(0)
; template <class Epi, class Sched>
; DI void gemm_phase(LAS unsigned char* lds, const Gemm g, const Sched& S, const Epi& E) {
;     ...
;     for (int t = 0; t < nt; t += 2) {
;       const bool last = (t == nt - 2);
;       const char* a1 = cA + (size_t)(t + 1) * kstep;
;       const char* a2 = last ? nA : cA + (size_t)(t + 2) * kstep; const char* b2 = last ? nB : cB + (size_t)(t + 2) * kstep;
;       const char* a3 = a2 + kstep; const char* b3 = b2 + kstep;
;       PG8_LDB(B0, 0, 0); PG8_SCHED; PG8_LDA(At, 0, 0); PG8_STAGE(PG8_SA(1, 1), a1 + hstep, voffA);
;       PG8_WAIT_L(8); PG8_BAR; PG8_WAIT_L(0); PG8_MMA(0, 0, At, B0); PG8_BAR; PG8_SCHED;
;       PG8_LDB(B1, 0, 1); PG8_STAGE(PG8_SB(0, 0), b2, voffB);
;       PG8_BAR; PG8_WAIT_L(0); PG8_MMA(0, 1, At, B1); PG8_BAR;
;       PG8_LDA(At, 0, 1); PG8_STAGE(PG8_SA(0, 0), a2, voffA);
;       PG8_BAR; PG8_WAIT_L(0); PG8_MMA(1, 0, At, B0); PG8_BAR; PG8_SCHED;
;       PG8_STAGE(PG8_SB(0, 1), b2 + hstep, voffB);
;       PG8_WAIT_V(6); PG8_BAR; PG8_MMA(1, 1, At, B1); PG8_BAR;
.LBB0_1202:
	s_add_u32 s20, s18, 0x100
	s_addc_u32 s21, s19, 0
	s_add_i32 s55, 0, 0x10000
	v_add_u32_e32 v144, s55, v162
	ds_read_b128 v[140:143], v144
	ds_read_b128 v[146:149], v144 offset:1024
	ds_read_b128 v[150:153], v144 offset:2048
	ds_read_b128 v[154:157], v144 offset:3072
	s_cmp_eq_u32 s54, 2
	s_cselect_b32 s29, s3, s21
	s_cselect_b32 s28, s2, s20
	s_cselect_b32 s23, s5, s53
	s_cselect_b32 s22, s4, s52
	v_lshl_add_u64 v[180:181], s[18:19], 0, v[136:137]
	s_add_i32 m0, s38, 0xc000
	ds_read_b128 v[158:161], v163
	ds_read_b128 v[164:167], v163 offset:1024
	ds_read_b128 v[168:171], v163 offset:2048
	ds_read_b128 v[172:175], v163 offset:3072
	ds_read_b128 v[176:179], v163 offset:4096
	ds_read_b128 v[196:199], v163 offset:5120
	ds_read_b128 v[200:203], v163 offset:6144
	ds_read_b128 v[204:207], v163 offset:7168
	global_load_lds_dwordx4 v[180:181], off
	v_lshl_add_u64 v[180:181], s[18:19], 0, v[138:139]
	s_add_i32 m0, s38, 0xe000
	s_nop 0
	global_load_lds_dwordx4 v[180:181], off
	s_waitcnt lgkmcnt(8)
	s_barrier
	s_waitcnt lgkmcnt(0)
	s_waitcnt lgkmcnt(0)
	v_mfma_f32_16x16x32_bf16 v[124:127], v[140:143], v[158:161], v[124:127]
	v_mfma_f32_16x16x32_bf16 v[120:123], v[150:153], v[158:161], v[120:123]
	v_mfma_f32_16x16x32_bf16 v[108:111], v[140:143], v[168:171], v[108:111]
	v_mfma_f32_16x16x32_bf16 v[104:107], v[150:153], v[168:171], v[104:107]
	v_mfma_f32_16x16x32_bf16 v[92:95], v[140:143], v[176:179], v[92:95]
	v_mfma_f32_16x16x32_bf16 v[88:91], v[150:153], v[176:179], v[88:91]
	v_mfma_f32_16x16x32_bf16 v[76:79], v[140:143], v[200:203], v[76:79]
	v_mfma_f32_16x16x32_bf16 v[72:75], v[150:153], v[200:203], v[72:75]
	v_mfma_f32_16x16x32_bf16 v[124:127], v[146:149], v[164:167], v[124:127]
	v_mfma_f32_16x16x32_bf16 v[120:123], v[154:157], v[164:167], v[120:123]
	v_mfma_f32_16x16x32_bf16 v[108:111], v[146:149], v[172:175], v[108:111]
	v_mfma_f32_16x16x32_bf16 v[104:107], v[154:157], v[172:175], v[104:107]
	v_mfma_f32_16x16x32_bf16 v[92:95], v[146:149], v[196:199], v[92:95]
	v_mfma_f32_16x16x32_bf16 v[88:91], v[154:157], v[196:199], v[88:91]
	v_mfma_f32_16x16x32_bf16 v[76:79], v[146:149], v[204:207], v[76:79]
	v_mfma_f32_16x16x32_bf16 v[72:75], v[154:157], v[204:207], v[72:75]
	s_barrier
	s_add_i32 s56, 0, 0x14000
	s_add_i32 s18, s55, s35
	v_add_u32_e32 v144, s56, v162
	v_lshl_add_u64 v[180:181], s[22:23], 0, v[130:131]
	s_mov_b32 m0, s18
	ds_read_b128 v[208:211], v144
	ds_read_b128 v[212:215], v144 offset:1024
	ds_read_b128 v[216:219], v144 offset:2048
	ds_read_b128 v[220:223], v144 offset:3072
	global_load_lds_dwordx4 v[180:181], off
	v_lshl_add_u64 v[224:225], s[22:23], 0, v[134:135]
	s_add_i32 m0, s18, 0x2000
	s_nop 0
	global_load_lds_dwordx4 v[224:225], off
	s_barrier
	s_waitcnt lgkmcnt(0)
	s_waitcnt lgkmcnt(0)
	v_mfma_f32_16x16x32_bf16 v[116:119], v[208:211], v[158:161], v[116:119]
	v_mfma_f32_16x16x32_bf16 v[112:115], v[216:219], v[158:161], v[112:115]
	v_mfma_f32_16x16x32_bf16 v[100:103], v[208:211], v[168:171], v[100:103]
	v_mfma_f32_16x16x32_bf16 v[96:99], v[216:219], v[168:171], v[96:99]
	v_mfma_f32_16x16x32_bf16 v[84:87], v[208:211], v[176:179], v[84:87]
	v_mfma_f32_16x16x32_bf16 v[80:83], v[216:219], v[176:179], v[80:83]
	v_mfma_f32_16x16x32_bf16 v[68:71], v[208:211], v[200:203], v[68:71]
	v_mfma_f32_16x16x32_bf16 v[64:67], v[216:219], v[200:203], v[64:67]
	v_mfma_f32_16x16x32_bf16 v[116:119], v[212:215], v[164:167], v[116:119]
	v_mfma_f32_16x16x32_bf16 v[112:115], v[220:223], v[164:167], v[112:115]
	v_mfma_f32_16x16x32_bf16 v[100:103], v[212:215], v[172:175], v[100:103]
	v_mfma_f32_16x16x32_bf16 v[96:99], v[220:223], v[172:175], v[96:99]
	v_mfma_f32_16x16x32_bf16 v[84:87], v[212:215], v[196:199], v[84:87]
	v_mfma_f32_16x16x32_bf16 v[80:83], v[220:223], v[196:199], v[80:83]
	v_mfma_f32_16x16x32_bf16 v[68:71], v[212:215], v[204:207], v[68:71]
	v_mfma_f32_16x16x32_bf16 v[64:67], v[220:223], v[204:207], v[64:67]
	s_mov_b32 m0, s38
	v_lshl_add_u64 v[226:227], s[28:29], 0, v[128:129]
	s_barrier
	ds_read_b128 v[158:161], v163 offset:16384
	ds_read_b128 v[164:167], v163 offset:17408
	ds_read_b128 v[168:171], v163 offset:18432
	ds_read_b128 v[172:175], v163 offset:19456
	ds_read_b128 v[176:179], v163 offset:20480
	ds_read_b128 v[196:199], v163 offset:21504
	ds_read_b128 v[200:203], v163 offset:22528
	ds_read_b128 v[204:207], v163 offset:23552
	global_load_lds_dwordx4 v[226:227], off
	v_lshl_add_u64 v[228:229], s[28:29], 0, v[132:133]
	s_mov_b32 m0, s39
	s_nop 0
	global_load_lds_dwordx4 v[228:229], off
	s_barrier
	s_waitcnt lgkmcnt(0)
	s_waitcnt lgkmcnt(0)
	v_mfma_f32_16x16x32_bf16 v[60:63], v[140:143], v[158:161], v[60:63]
	v_mfma_f32_16x16x32_bf16 v[56:59], v[150:153], v[158:161], v[56:59]
	v_mfma_f32_16x16x32_bf16 v[44:47], v[140:143], v[168:171], v[44:47]
	v_mfma_f32_16x16x32_bf16 v[40:43], v[150:153], v[168:171], v[40:43]
	v_mfma_f32_16x16x32_bf16 v[28:31], v[140:143], v[176:179], v[28:31]
	v_mfma_f32_16x16x32_bf16 v[24:27], v[150:153], v[176:179], v[24:27]
	v_mfma_f32_16x16x32_bf16 v[12:15], v[140:143], v[200:203], v[12:15]
	v_mfma_f32_16x16x32_bf16 v[8:11], v[150:153], v[200:203], v[8:11]
	v_mfma_f32_16x16x32_bf16 v[60:63], v[146:149], v[164:167], v[60:63]
	v_mfma_f32_16x16x32_bf16 v[56:59], v[154:157], v[164:167], v[56:59]
	v_mfma_f32_16x16x32_bf16 v[44:47], v[146:149], v[172:175], v[44:47]
	v_mfma_f32_16x16x32_bf16 v[40:43], v[154:157], v[172:175], v[40:43]
	v_mfma_f32_16x16x32_bf16 v[28:31], v[146:149], v[196:199], v[28:31]
	v_mfma_f32_16x16x32_bf16 v[24:27], v[154:157], v[196:199], v[24:27]
	v_mfma_f32_16x16x32_bf16 v[12:15], v[146:149], v[204:207], v[12:15]
	v_mfma_f32_16x16x32_bf16 v[8:11], v[154:157], v[204:207], v[8:11]
	s_barrier
; #define PG8_STAGE(bufoff, gbase, voff) do { _Pragma("unroll") for (int _i = 0; _i < 2; ++_i) \
;     __builtin_amdgcn_global_load_lds((const unsigned*)((const char*)(gbase) + (voff)[_i]), (LAS unsigned*)(lds + (bufoff) + ldsw + _i * 8192), 16, 0, 0); } while (0)
; #define PG8_LDA(dst, b, h) do { _Pragma("unroll") for (int m = 0; m < 4; ++m) _Pragma("unroll") for (int k = 0; k < 2; ++k) dst[m][k] = *(const LAS bf16x8*)(lds + PG8_SA(b, h) + aoff + m * 2048 + k * 1024); } while (0)
; #define PG8_LDB(dst, b, h) do { _Pragma("unroll") for (int n = 0; n < 2; ++n) _Pragma("unroll") for (int k = 0; k < 2; ++k) dst[n][k] = *(const LAS bf16x8*)(lds + PG8_SB(b, h) + boff + n * 2048 + k * 1024); } while (0)
; #define PG8_MMA(ai, bj, At, Bt) do { __builtin_amdgcn_s_setprio(1); _Pragma("unroll") for (int m = 0; m < 4; ++m) _Pragma("unroll") for (int n = 0; n < 2; ++n) _Pragma("unroll") for (int k = 0; k < 2; ++k) \
;     acc[ai][bj][m][n] = __builtin_amdgcn_mfma_f32_16x16x32_bf16(Bt[n][k], At[m][k], acc[ai][bj][m][n], 0, 0, 0); __builtin_amdgcn_s_setprio(0); } while (0)
; #define PG8_WAIT_V(n) asm volatile("s_waitcnt vmcnt(" #n ")" ::: "memory")
; #define PG8_WAIT_L(n) asm volatile("s_waitcnt lgkmcnt(" #n ")" ::: "memory")
; #define PG8_BAR __builtin_amdgcn_s_barrier()
; #define PG8_SCHED __builtin_amdgcn_sched_barrier(0)
; template <class Epi, class Sched>
; DI void gemm_phase(LAS unsigned char* lds, const Gemm g, const Sched& S, const Epi& E) {
;     ...
;       PG8_STAGE(PG8_SB(0, 1), b2 + hstep, voffB);
;       PG8_WAIT_V(6); PG8_BAR; PG8_MMA(1, 1, At, B1); PG8_BAR;
;       PG8_LDB(B0, 1, 0); PG8_SCHED; PG8_LDA(At, 1, 0); PG8_STAGE(PG8_SA(0, 1), a2 + hstep, voffA);
;       PG8_WAIT_L(8); PG8_BAR; PG8_WAIT_L(0); PG8_MMA(0, 0, At, B0); PG8_BAR; PG8_SCHED;
;       PG8_LDB(B1, 1, 1); PG8_STAGE(PG8_SB(1, 0), b3, voffB);
;       PG8_BAR; PG8_WAIT_L(0); PG8_MMA(0, 1, At, B1); PG8_BAR;
;       PG8_LDA(At, 1, 1); PG8_STAGE(PG8_SA(1, 0), a3, voffA);
;       PG8_BAR; PG8_WAIT_L(0); PG8_MMA(1, 0, At, B0); PG8_BAR; PG8_SCHED;
;       PG8_STAGE(PG8_SB(1, 1), b3 + hstep, voffB);
	s_add_u32 s18, s22, 0x18000
	s_addc_u32 s19, s23, 0
	s_add_i32 s55, s56, s35
	v_lshl_add_u64 v[140:141], s[18:19], 0, v[130:131]
	s_mov_b32 m0, s55
	s_nop 0
	global_load_lds_dwordx4 v[140:141], off
	v_lshl_add_u64 v[140:141], s[18:19], 0, v[134:135]
	s_add_i32 m0, s55, 0x2000
	s_nop 0
	global_load_lds_dwordx4 v[140:141], off
	s_waitcnt vmcnt(6)
	s_barrier
	v_mfma_f32_16x16x32_bf16 v[52:55], v[208:211], v[158:161], v[52:55]
	v_mfma_f32_16x16x32_bf16 v[48:51], v[216:219], v[158:161], v[48:51]
	v_mfma_f32_16x16x32_bf16 v[36:39], v[208:211], v[168:171], v[36:39]
	v_mfma_f32_16x16x32_bf16 v[32:35], v[216:219], v[168:171], v[32:35]
	v_mfma_f32_16x16x32_bf16 v[20:23], v[208:211], v[176:179], v[20:23]
	v_mfma_f32_16x16x32_bf16 v[16:19], v[216:219], v[176:179], v[16:19]
	v_mfma_f32_16x16x32_bf16 v[4:7], v[208:211], v[200:203], v[4:7]
	v_mfma_f32_16x16x32_bf16 v[0:3], v[216:219], v[200:203], v[0:3]
	v_mfma_f32_16x16x32_bf16 v[52:55], v[212:215], v[164:167], v[52:55]
	v_mfma_f32_16x16x32_bf16 v[48:51], v[220:223], v[164:167], v[48:51]
	v_mfma_f32_16x16x32_bf16 v[36:39], v[212:215], v[172:175], v[36:39]
	v_mfma_f32_16x16x32_bf16 v[32:35], v[220:223], v[172:175], v[32:35]
	v_mfma_f32_16x16x32_bf16 v[20:23], v[212:215], v[196:199], v[20:23]
	v_mfma_f32_16x16x32_bf16 v[16:19], v[220:223], v[196:199], v[16:19]
	v_mfma_f32_16x16x32_bf16 v[4:7], v[212:215], v[204:207], v[4:7]
	v_mfma_f32_16x16x32_bf16 v[0:3], v[220:223], v[204:207], v[0:3]
	s_add_i32 s55, 0, 0x18000
	v_add_u32_e32 v144, s55, v162
	s_barrier
	ds_read_b128 v[140:143], v144
	ds_read_b128 v[146:149], v144 offset:1024
	ds_read_b128 v[150:153], v144 offset:2048
	ds_read_b128 v[154:157], v144 offset:3072
	s_add_u32 s18, s28, 0x18000
	s_addc_u32 s19, s29, 0
	s_mov_b32 m0, s40
	v_lshl_add_u64 v[208:209], s[18:19], 0, v[128:129]
	ds_read_b128 v[158:161], v163 offset:32768
	ds_read_b128 v[164:167], v163 offset:33792
	ds_read_b128 v[168:171], v163 offset:34816
	ds_read_b128 v[172:175], v163 offset:35840
	ds_read_b128 v[176:179], v163 offset:36864
	ds_read_b128 v[196:199], v163 offset:37888
	ds_read_b128 v[200:203], v163 offset:38912
	ds_read_b128 v[204:207], v163 offset:39936
	global_load_lds_dwordx4 v[208:209], off
	v_lshl_add_u64 v[208:209], s[18:19], 0, v[132:133]
	s_mov_b32 m0, s41
	s_nop 0
	global_load_lds_dwordx4 v[208:209], off
	s_waitcnt lgkmcnt(8)
	s_barrier
	s_waitcnt lgkmcnt(0)
	s_waitcnt lgkmcnt(0)
	v_mfma_f32_16x16x32_bf16 v[124:127], v[140:143], v[158:161], v[124:127]
	v_mfma_f32_16x16x32_bf16 v[120:123], v[150:153], v[158:161], v[120:123]
	v_mfma_f32_16x16x32_bf16 v[108:111], v[140:143], v[168:171], v[108:111]
	v_mfma_f32_16x16x32_bf16 v[104:107], v[150:153], v[168:171], v[104:107]
	v_mfma_f32_16x16x32_bf16 v[92:95], v[140:143], v[176:179], v[92:95]
	v_mfma_f32_16x16x32_bf16 v[88:91], v[150:153], v[176:179], v[88:91]
	v_mfma_f32_16x16x32_bf16 v[76:79], v[140:143], v[200:203], v[76:79]
	v_mfma_f32_16x16x32_bf16 v[72:75], v[150:153], v[200:203], v[72:75]
	v_mfma_f32_16x16x32_bf16 v[124:127], v[146:149], v[164:167], v[124:127]
	v_mfma_f32_16x16x32_bf16 v[120:123], v[154:157], v[164:167], v[120:123]
	v_mfma_f32_16x16x32_bf16 v[108:111], v[146:149], v[172:175], v[108:111]
	v_mfma_f32_16x16x32_bf16 v[104:107], v[154:157], v[172:175], v[104:107]
	v_mfma_f32_16x16x32_bf16 v[92:95], v[146:149], v[196:199], v[92:95]
	v_mfma_f32_16x16x32_bf16 v[88:91], v[154:157], v[196:199], v[88:91]
	v_mfma_f32_16x16x32_bf16 v[76:79], v[146:149], v[204:207], v[76:79]
	v_mfma_f32_16x16x32_bf16 v[72:75], v[154:157], v[204:207], v[72:75]
	s_barrier
	s_add_i32 s28, 0, 0x1c000
	s_add_i32 s18, s55, s35
	v_add_u32_e32 v144, s28, v162
	v_lshl_add_u64 v[180:181], v[180:181], 0, s[0:1]
	s_mov_b32 m0, s18
	ds_read_b128 v[208:211], v144
	ds_read_b128 v[212:215], v144 offset:1024
	ds_read_b128 v[216:219], v144 offset:2048
	ds_read_b128 v[220:223], v144 offset:3072
	global_load_lds_dwordx4 v[180:181], off
	v_lshl_add_u64 v[180:181], v[224:225], 0, s[0:1]
	s_add_i32 m0, s18, 0x2000
	s_nop 0
	global_load_lds_dwordx4 v[180:181], off
	s_barrier
	s_waitcnt lgkmcnt(0)
	s_waitcnt lgkmcnt(0)
	v_mfma_f32_16x16x32_bf16 v[116:119], v[208:211], v[158:161], v[116:119]
	v_mfma_f32_16x16x32_bf16 v[112:115], v[216:219], v[158:161], v[112:115]
	v_mfma_f32_16x16x32_bf16 v[100:103], v[208:211], v[168:171], v[100:103]
	v_mfma_f32_16x16x32_bf16 v[96:99], v[216:219], v[168:171], v[96:99]
	v_mfma_f32_16x16x32_bf16 v[84:87], v[208:211], v[176:179], v[84:87]
	v_mfma_f32_16x16x32_bf16 v[80:83], v[216:219], v[176:179], v[80:83]
	v_mfma_f32_16x16x32_bf16 v[68:71], v[208:211], v[200:203], v[68:71]
	v_mfma_f32_16x16x32_bf16 v[64:67], v[216:219], v[200:203], v[64:67]
	v_mfma_f32_16x16x32_bf16 v[116:119], v[212:215], v[164:167], v[116:119]
	v_mfma_f32_16x16x32_bf16 v[112:115], v[220:223], v[164:167], v[112:115]
	v_mfma_f32_16x16x32_bf16 v[100:103], v[212:215], v[172:175], v[100:103]
	v_mfma_f32_16x16x32_bf16 v[96:99], v[220:223], v[172:175], v[96:99]
	v_mfma_f32_16x16x32_bf16 v[84:87], v[212:215], v[196:199], v[84:87]
	v_mfma_f32_16x16x32_bf16 v[80:83], v[220:223], v[196:199], v[80:83]
	v_mfma_f32_16x16x32_bf16 v[68:71], v[212:215], v[204:207], v[68:71]
	v_mfma_f32_16x16x32_bf16 v[64:67], v[220:223], v[204:207], v[64:67]
	s_mov_b32 m0, s44
	v_lshl_add_u64 v[180:181], v[226:227], 0, s[0:1]
	s_barrier
	ds_read_b128 v[158:161], v163 offset:49152
	ds_read_b128 v[164:167], v163 offset:50176
	ds_read_b128 v[168:171], v163 offset:51200
	ds_read_b128 v[172:175], v163 offset:52224
	ds_read_b128 v[176:179], v163 offset:53248
	ds_read_b128 v[196:199], v163 offset:54272
	ds_read_b128 v[200:203], v163 offset:55296
	ds_read_b128 v[204:207], v163 offset:56320
	global_load_lds_dwordx4 v[180:181], off
	v_lshl_add_u64 v[180:181], v[228:229], 0, s[0:1]
	s_mov_b32 m0, s45
	s_nop 0
	global_load_lds_dwordx4 v[180:181], off
	s_barrier
; #define PG8_STAGE(bufoff, gbase, voff) do { _Pragma("unroll") for (int _i = 0; _i < 2; ++_i) \
;     __builtin_amdgcn_global_load_lds((const unsigned*)((const char*)(gbase) + (voff)[_i]), (LAS unsigned*)(lds + (bufoff) + ldsw + _i * 8192), 16, 0, 0); } while (0)
; #define PG8_MMA(ai, bj, At, Bt) do { __builtin_amdgcn_s_setprio(1); _Pragma("unroll") for (int m = 0; m < 4; ++m) _Pragma("unroll") for (int n = 0; n < 2; ++n) _Pragma("unroll") for (int k = 0; k < 2; ++k) \
;     acc[ai][bj][m][n] = __builtin_amdgcn_mfma_f32_16x16x32_bf16(Bt[n][k], At[m][k], acc[ai][bj][m][n], 0, 0, 0); __builtin_amdgcn_s_setprio(0); } while (0)
; #define PG8_WAIT_V(n) asm volatile("s_waitcnt vmcnt(" #n ")" ::: "memory")
; #define PG8_BAR __builtin_amdgcn_s_barrier()
; template <class Epi, class Sched>
; DI void gemm_phase(LAS unsigned char* lds, const Gemm g, const Sched& S, const Epi& E) {
;     ...
;       PG8_STAGE(PG8_SB(1, 1), b3 + hstep, voffB);
;       PG8_WAIT_V(6); PG8_BAR; PG8_MMA(1, 1, At, B1); PG8_BAR;
;     }
;     E(acc, cur, wr, wc, fr, fq);
;   DI void operator()(const f32x4 (&acc)[2][2][4][2], const pg8::Unit& u, int wr, int wc, int fr_, int fq_) const {
;     ...
;             } else if (EPI == EPI_UQ) {
;               if (n == 0) {
;                 const float sc = rinv * (0.10206207261596575f * LOG2E);
;                 const int gb = u.pn * 256 + bj * 128 + wc * 32;
;                 const int hd = gb / 96; const int within = gb - hd * 96;
;                 f32x4 a0 = v, a1 = acc[ai][bj][m][1];
;                 if (within == 64) rope_perm(a0, a1, fq, t_ & 63, tcos, tsin, token & (S_ - 1));
;                 st_bf8((u16*)(big + E_QMLA) + (size_t)token * 768 + gb + 8 * fq, a0, a1, sc);
;               }
	s_waitcnt lgkmcnt(0)
	s_waitcnt lgkmcnt(0)
	v_mfma_f32_16x16x32_bf16 v[60:63], v[140:143], v[158:161], v[60:63]
	v_mfma_f32_16x16x32_bf16 v[56:59], v[150:153], v[158:161], v[56:59]
	v_mfma_f32_16x16x32_bf16 v[44:47], v[140:143], v[168:171], v[44:47]
	v_mfma_f32_16x16x32_bf16 v[40:43], v[150:153], v[168:171], v[40:43]
	v_mfma_f32_16x16x32_bf16 v[28:31], v[140:143], v[176:179], v[28:31]
	v_mfma_f32_16x16x32_bf16 v[24:27], v[150:153], v[176:179], v[24:27]
	v_mfma_f32_16x16x32_bf16 v[12:15], v[140:143], v[200:203], v[12:15]
	v_mfma_f32_16x16x32_bf16 v[8:11], v[150:153], v[200:203], v[8:11]
	v_mfma_f32_16x16x32_bf16 v[60:63], v[146:149], v[164:167], v[60:63]
	v_mfma_f32_16x16x32_bf16 v[56:59], v[154:157], v[164:167], v[56:59]
	v_mfma_f32_16x16x32_bf16 v[44:47], v[146:149], v[172:175], v[44:47]
	v_mfma_f32_16x16x32_bf16 v[40:43], v[154:157], v[172:175], v[40:43]
	v_mfma_f32_16x16x32_bf16 v[28:31], v[146:149], v[196:199], v[28:31]
	v_mfma_f32_16x16x32_bf16 v[24:27], v[154:157], v[196:199], v[24:27]
	v_mfma_f32_16x16x32_bf16 v[12:15], v[146:149], v[204:207], v[12:15]
	v_mfma_f32_16x16x32_bf16 v[8:11], v[154:157], v[204:207], v[8:11]
	s_barrier
	s_add_u32 s18, s22, 0x18080
	s_addc_u32 s19, s23, 0
	s_add_i32 s22, s28, s35
	v_lshl_add_u64 v[140:141], s[18:19], 0, v[130:131]
	s_mov_b32 m0, s22
	s_nop 0
	global_load_lds_dwordx4 v[140:141], off
	v_lshl_add_u64 v[140:141], s[18:19], 0, v[134:135]
	s_add_i32 m0, s22, 0x2000
	s_nop 0
	global_load_lds_dwordx4 v[140:141], off
	s_waitcnt vmcnt(6)
	s_barrier
	v_mfma_f32_16x16x32_bf16 v[52:55], v[208:211], v[158:161], v[52:55]
	v_mfma_f32_16x16x32_bf16 v[48:51], v[216:219], v[158:161], v[48:51]
	v_mfma_f32_16x16x32_bf16 v[36:39], v[208:211], v[168:171], v[36:39]
	v_mfma_f32_16x16x32_bf16 v[32:35], v[216:219], v[168:171], v[32:35]
	v_mfma_f32_16x16x32_bf16 v[20:23], v[208:211], v[176:179], v[20:23]
	v_mfma_f32_16x16x32_bf16 v[16:19], v[216:219], v[176:179], v[16:19]
	v_mfma_f32_16x16x32_bf16 v[4:7], v[208:211], v[200:203], v[4:7]
	v_mfma_f32_16x16x32_bf16 v[0:3], v[216:219], v[200:203], v[0:3]
	v_mfma_f32_16x16x32_bf16 v[52:55], v[212:215], v[164:167], v[52:55]
	v_mfma_f32_16x16x32_bf16 v[48:51], v[220:223], v[164:167], v[48:51]
	v_mfma_f32_16x16x32_bf16 v[36:39], v[212:215], v[172:175], v[36:39]
	v_mfma_f32_16x16x32_bf16 v[32:35], v[220:223], v[172:175], v[32:35]
	v_mfma_f32_16x16x32_bf16 v[20:23], v[212:215], v[196:199], v[20:23]
	v_mfma_f32_16x16x32_bf16 v[16:19], v[220:223], v[196:199], v[16:19]
	v_mfma_f32_16x16x32_bf16 v[4:7], v[212:215], v[204:207], v[4:7]
	v_mfma_f32_16x16x32_bf16 v[0:3], v[220:223], v[204:207], v[0:3]
	s_add_i32 s54, s54, 2
	s_add_u32 s52, s52, 0x100
	s_addc_u32 s53, s53, 0
	s_cmp_gt_u32 s54, 3
	s_mov_b64 s[18:19], s[20:21]
	s_barrier
	s_cbranch_scc0 .LBB0_1202
	v_mov_b32_e32 v140, v182
	s_lshl_b32 s19, s51, 10
	s_lshl_b32 s18, s49, 8
	s_or_b32 s18, s18, s43
	v_and_or_b32 v167, v140, 15, s42
	v_lshlrev_b32_e32 v141, 2, v140
	s_movk_i32 s20, 0x80
	s_add_i32 s19, s19, 0
	v_bitop3_b32 v164, v141, s20, v190 bitop3:0x6c
	v_lshl_add_u32 v141, v167, 2, s19
	s_mul_hi_i32 s19, s18, 0x2aaaaaab
	v_add_u32_e32 v166, 0x20000, v141
	s_lshr_b32 s20, s19, 31
	s_lshr_b32 s19, s19, 4
	s_lshl_b32 s50, s50, 8
	ds_read_b32 v144, v166
	s_add_i32 s19, s19, s20
	v_add_u32_e32 v165, s50, v167
	s_mulk_i32 s19, 0x60
	v_bfe_u32 v168, v140, 4, 2
	v_lshrrev_b32_e32 v140, 1, v140
	v_lshlrev_b32_e32 v141, 4, v165
	s_sub_i32 s19, s18, s19
	v_and_b32_e32 v140, 8, v140
	v_and_b32_e32 v141, 0xfcf0, v141
	s_cmp_eq_u32 s19, 64
	v_cmp_lt_u32_e64 s[78:79], 1, v168
	s_cselect_b64 s[20:21], -1, 0
	s_cmp_lg_u32 s19, 64
	v_lshlrev_b32_e32 v142, 2, v141
	v_lshlrev_b32_e32 v140, 2, v140
	s_cbranch_scc1 .LBB0_1209
	v_mov_b32_e32 v143, v145
	v_lshl_add_u64 v[146:147], s[12:13], 0, v[142:143]
	v_mov_b32_e32 v141, v145
	v_lshl_add_u64 v[152:153], s[14:15], 0, v[142:143]
	v_lshl_add_u64 v[146:147], v[146:147], 0, v[140:141]
	v_lshl_add_u64 v[152:153], v[152:153], 0, v[140:141]
	global_load_dwordx4 v[148:151], v[146:147], off
	global_load_dwordx4 v[154:157], v[152:153], off
	global_load_dwordx4 v[170:173], v[152:153], off offset:16
	global_load_dwordx4 v[174:177], v[146:147], off offset:16
	ds_bpermute_b32 v152, v164, v124
	ds_bpermute_b32 v160, v164, v120
	ds_bpermute_b32 v153, v164, v125
	ds_bpermute_b32 v161, v164, v121
	ds_bpermute_b32 v158, v164, v126
	ds_bpermute_b32 v178, v164, v122
	ds_bpermute_b32 v159, v164, v127
	ds_bpermute_b32 v179, v164, v123
	s_waitcnt vmcnt(0) lgkmcnt(0)
	v_pk_mul_f32 v[154:155], v[154:155], v[152:153]
	v_pk_mul_f32 v[146:147], v[126:127], v[150:151]
	v_pk_mul_f32 v[150:151], v[124:125], v[148:149]
	v_pk_mul_f32 v[158:159], v[156:157], v[158:159]
	v_pk_mul_f32 v[148:149], v[170:171], v[160:161]
	v_pk_mul_f32 v[152:153], v[172:173], v[178:179]
	v_pk_mul_f32 v[156:157], v[122:123], v[176:177]
	v_pk_mul_f32 v[160:161], v[120:121], v[174:175]
	s_and_saveexec_b64 s[22:23], s[78:79]
	s_xor_b64 s[22:23], exec, s[22:23]
	v_pk_add_f32 v[126:127], v[146:147], v[158:159]
	v_pk_add_f32 v[124:125], v[150:151], v[154:155]
	v_pk_add_f32 v[122:123], v[156:157], v[152:153]
	v_pk_add_f32 v[120:121], v[160:161], v[148:149]
	s_andn2_saveexec_b64 s[22:23], s[22:23]
	v_sub_f32_e32 v127, v147, v159
	v_sub_f32_e32 v126, v146, v158
	v_sub_f32_e32 v125, v151, v155
	v_sub_f32_e32 v124, v150, v154
	v_sub_f32_e32 v123, v157, v153
	v_sub_f32_e32 v122, v156, v152
	v_sub_f32_e32 v121, v161, v149
	v_sub_f32_e32 v120, v160, v148
	s_or_b64 exec, exec, s[22:23]

; #define PG8_STAGE(bufoff, gbase, voff) do { _Pragma("unroll") for (int _i = 0; _i < 2; ++_i) \
;     __builtin_amdgcn_global_load_lds((const unsigned*)((const char*)(gbase) + (voff)[_i]), (LAS unsigned*)(lds + (bufoff) + ldsw + _i * 8192), 16, 0, 0); } while (0)
; #define PG8_LDA(dst, b, h) do { _Pragma("unroll") for (int m = 0; m < 4; ++m) _Pragma("unroll") for (int k = 0; k < 2; ++k) dst[m][k] = *(const LAS bf16x8*)(lds + PG8_SA(b, h) + aoff + m * 2048 + k * 1024); } while (0)
; #define PG8_LDB(dst, b, h) do { _Pragma("unroll") for (int n = 0; n < 2; ++n) _Pragma("unroll") for (int k = 0; k < 2; ++k) dst[n][k] = *(const LAS bf16x8*)(lds + PG8_SB(b, h) + boff + n * 2048 + k * 1024); } while (0)
; #define PG8_MMA(ai, bj, At, Bt) do { __builtin_amdgcn_s_setprio(1); _Pragma("unroll") for (int m = 0; m < 4; ++m) _Pragma("unroll") for (int n = 0; n < 2; ++n) _Pragma("unroll") for (int k = 0; k < 2; ++k) \
;     acc[ai][bj][m][n] = __builtin_amdgcn_mfma_f32_16x16x32_bf16(Bt[n][k], At[m][k], acc[ai][bj][m][n], 0, 0, 0); __builtin_amdgcn_s_setprio(0); } while (0)
; #define PG8_WAIT_L(n) asm volatile("s_waitcnt lgkmcnt(" #n ")" ::: "memory")
; #define PG8_BAR __builtin_amdgcn_s_barrier()
; #define PG8_SCHED __builtin_amdgcn_sched_barrier(0)
; template <class Epi, class Sched>
; DI void gemm_phase(LAS unsigned char* lds, const Gemm g, const Sched& S, const Epi& E) {
;     ...
;     const bool has_next = S.next(ui + 1, nxt);
;     const char* nA = has_next ? (const char*)g.A + (size_t)nxt.pm * tstep : cA; const char* nB = has_next ? (const char*)g.Bt + (size_t)nxt.pn * tstep : cB;
; #pragma unroll 1
;     for (int t = 0; t < nt; t += 2) {
;       const bool last = (t == nt - 2);
;       const char* a1 = cA + (size_t)(t + 1) * kstep;
;       const char* a2 = last ? nA : cA + (size_t)(t + 2) * kstep; const char* b2 = last ? nB : cB + (size_t)(t + 2) * kstep;
;       const char* a3 = a2 + kstep; const char* b3 = b2 + kstep;
;       PG8_LDB(B0, 0, 0); PG8_SCHED; PG8_LDA(At, 0, 0); PG8_STAGE(PG8_SA(1, 1), a1 + hstep, voffA);
;       PG8_WAIT_L(8); PG8_BAR; PG8_WAIT_L(0); PG8_MMA(0, 0, At, B0); PG8_BAR; PG8_SCHED;
;       PG8_LDB(B1, 0, 1); PG8_STAGE(PG8_SB(0, 0), b2, voffB);
;       PG8_BAR; PG8_WAIT_L(0); PG8_MMA(0, 1, At, B1); PG8_BAR;
;       PG8_LDA(At, 0, 1); PG8_STAGE(PG8_SA(0, 0), a2, voffA);
;       PG8_BAR; PG8_WAIT_L(0); PG8_MMA(1, 0, At, B0); PG8_BAR; PG8_SCHED;
.LBB0_1346:
	s_add_u32 s48, s28, s40
	s_addc_u32 s49, s29, s41
	s_add_u32 s44, s48, 0x100
	s_addc_u32 s45, s49, 0
	s_and_b64 s[42:43], s[36:37], exec
	s_cselect_b32 s45, s15, s45
	s_cselect_b32 s44, s21, s44
	s_add_u32 s40, s22, s40
	s_addc_u32 s41, s23, s41
	s_add_u32 s40, s40, 0x100
	s_addc_u32 s41, s41, 0
	s_add_i32 s70, 0, 0x10000
	s_and_b64 s[36:37], s[36:37], exec
	s_cselect_b32 s47, s13, s41
	s_cselect_b32 s46, s24, s40
	s_add_u32 s48, s48, 0x10080
	s_addc_u32 s49, s49, 0
	s_add_i32 s74, s70, s51
	s_add_i32 m0, s56, 0xc000
	s_add_i32 s75, s56, 0xe000
	s_add_i32 s73, 0, 0x14000
	s_add_i32 s72, s74, 0x2000
	s_add_u32 s42, s46, 0x10000
	v_add_u32_e32 v140, s70, v142
	s_addc_u32 s43, s47, 0
	s_add_i32 s69, s73, s51
	ds_read_b128 v[136:139], v140
	ds_read_b128 v[146:149], v140 offset:1024
	ds_read_b128 v[150:153], v140 offset:2048
	ds_read_b128 v[154:157], v140 offset:3072
	s_add_i32 s68, s69, 0x2000
	s_add_i32 s67, 0, 0x18000
	s_add_u32 s40, s44, 0x10000
	s_addc_u32 s41, s45, 0
	s_add_i32 s66, s67, s51
	s_add_i32 s65, 0, 0x1c000
	s_add_i32 s64, s66, 0x2000
	s_add_u32 s36, s46, 0x10080
	s_addc_u32 s37, s47, 0
	s_add_i32 s71, s65, s51
	s_add_i32 s70, s71, 0x2000
	v_lshl_add_u64 v[140:141], s[48:49], 0, v[128:129]
	ds_read_b128 v[158:161], v143
	ds_read_b128 v[162:165], v143 offset:1024
	ds_read_b128 v[166:169], v143 offset:2048
	ds_read_b128 v[170:173], v143 offset:3072
	ds_read_b128 v[174:177], v143 offset:4096
	ds_read_b128 v[178:181], v143 offset:5120
	ds_read_b128 v[196:199], v143 offset:6144
	ds_read_b128 v[200:203], v143 offset:7168
	global_load_lds_dwordx4 v[140:141], off
	v_lshl_add_u64 v[140:141], s[48:49], 0, v[132:133]
	s_mov_b32 m0, s75
	s_nop 0
	global_load_lds_dwordx4 v[140:141], off
	s_waitcnt lgkmcnt(8)
	s_barrier
	s_waitcnt lgkmcnt(0)
	s_waitcnt lgkmcnt(0)
	v_mfma_f32_16x16x32_bf16 v[124:127], v[136:139], v[158:161], v[124:127]
	v_mfma_f32_16x16x32_bf16 v[120:123], v[150:153], v[158:161], v[120:123]
	v_mfma_f32_16x16x32_bf16 v[108:111], v[136:139], v[166:169], v[108:111]
	v_mfma_f32_16x16x32_bf16 v[104:107], v[150:153], v[166:169], v[104:107]
	v_mfma_f32_16x16x32_bf16 v[92:95], v[136:139], v[174:177], v[92:95]
	v_mfma_f32_16x16x32_bf16 v[88:91], v[150:153], v[174:177], v[88:91]
	v_mfma_f32_16x16x32_bf16 v[76:79], v[136:139], v[196:199], v[76:79]
	v_mfma_f32_16x16x32_bf16 v[72:75], v[150:153], v[196:199], v[72:75]
	v_mfma_f32_16x16x32_bf16 v[124:127], v[146:149], v[162:165], v[124:127]
	v_mfma_f32_16x16x32_bf16 v[120:123], v[154:157], v[162:165], v[120:123]
	v_mfma_f32_16x16x32_bf16 v[108:111], v[146:149], v[170:173], v[108:111]
	v_mfma_f32_16x16x32_bf16 v[104:107], v[154:157], v[170:173], v[104:107]
	v_mfma_f32_16x16x32_bf16 v[92:95], v[146:149], v[178:181], v[92:95]
	v_mfma_f32_16x16x32_bf16 v[88:91], v[154:157], v[178:181], v[88:91]
	v_mfma_f32_16x16x32_bf16 v[76:79], v[146:149], v[200:203], v[76:79]
	v_mfma_f32_16x16x32_bf16 v[72:75], v[154:157], v[200:203], v[72:75]
	s_barrier
	v_add_u32_e32 v140, s73, v142
	s_mov_b32 m0, s74
	ds_read_b128 v[204:207], v140
	ds_read_b128 v[208:211], v140 offset:1024
	ds_read_b128 v[212:215], v140 offset:2048
	ds_read_b128 v[216:219], v140 offset:3072
	v_lshl_add_u64 v[140:141], s[46:47], 0, v[130:131]
	global_load_lds_dwordx4 v[140:141], off
	v_lshl_add_u64 v[220:221], s[46:47], 0, v[134:135]
	s_mov_b32 m0, s72
	s_nop 0
	global_load_lds_dwordx4 v[220:221], off
	s_barrier
	s_waitcnt lgkmcnt(0)
	s_waitcnt lgkmcnt(0)
	v_mfma_f32_16x16x32_bf16 v[116:119], v[204:207], v[158:161], v[116:119]
	v_mfma_f32_16x16x32_bf16 v[112:115], v[212:215], v[158:161], v[112:115]
	v_mfma_f32_16x16x32_bf16 v[100:103], v[204:207], v[166:169], v[100:103]
	v_mfma_f32_16x16x32_bf16 v[96:99], v[212:215], v[166:169], v[96:99]
	v_mfma_f32_16x16x32_bf16 v[84:87], v[204:207], v[174:177], v[84:87]
	v_mfma_f32_16x16x32_bf16 v[80:83], v[212:215], v[174:177], v[80:83]
	v_mfma_f32_16x16x32_bf16 v[68:71], v[204:207], v[196:199], v[68:71]
	v_mfma_f32_16x16x32_bf16 v[64:67], v[212:215], v[196:199], v[64:67]
	v_mfma_f32_16x16x32_bf16 v[116:119], v[208:211], v[162:165], v[116:119]
	v_mfma_f32_16x16x32_bf16 v[112:115], v[216:219], v[162:165], v[112:115]
	v_mfma_f32_16x16x32_bf16 v[100:103], v[208:211], v[170:173], v[100:103]
	v_mfma_f32_16x16x32_bf16 v[96:99], v[216:219], v[170:173], v[96:99]
	v_mfma_f32_16x16x32_bf16 v[84:87], v[208:211], v[178:181], v[84:87]
	v_mfma_f32_16x16x32_bf16 v[80:83], v[216:219], v[178:181], v[80:83]
	v_mfma_f32_16x16x32_bf16 v[68:71], v[208:211], v[200:203], v[68:71]
	v_mfma_f32_16x16x32_bf16 v[64:67], v[216:219], v[200:203], v[64:67]
	s_mov_b32 m0, s56
	v_lshl_add_u64 v[222:223], s[44:45], 0, v[128:129]
	s_barrier
	ds_read_b128 v[158:161], v143 offset:16384
	ds_read_b128 v[162:165], v143 offset:17408
	ds_read_b128 v[166:169], v143 offset:18432
	ds_read_b128 v[170:173], v143 offset:19456
	ds_read_b128 v[174:177], v143 offset:20480
	ds_read_b128 v[178:181], v143 offset:21504
	ds_read_b128 v[196:199], v143 offset:22528
	ds_read_b128 v[200:203], v143 offset:23552
	global_load_lds_dwordx4 v[222:223], off
	v_lshl_add_u64 v[224:225], s[44:45], 0, v[132:133]
	s_mov_b32 m0, s57
	s_nop 0
	global_load_lds_dwordx4 v[224:225], off
	s_barrier
; #define PG8_STAGE(bufoff, gbase, voff) do { _Pragma("unroll") for (int _i = 0; _i < 2; ++_i) \
;     __builtin_amdgcn_global_load_lds((const unsigned*)((const char*)(gbase) + (voff)[_i]), (LAS unsigned*)(lds + (bufoff) + ldsw + _i * 8192), 16, 0, 0); } while (0)
; #define PG8_LDA(dst, b, h) do { _Pragma("unroll") for (int m = 0; m < 4; ++m) _Pragma("unroll") for (int k = 0; k < 2; ++k) dst[m][k] = *(const LAS bf16x8*)(lds + PG8_SA(b, h) + aoff + m * 2048 + k * 1024); } while (0)
; #define PG8_LDB(dst, b, h) do { _Pragma("unroll") for (int n = 0; n < 2; ++n) _Pragma("unroll") for (int k = 0; k < 2; ++k) dst[n][k] = *(const LAS bf16x8*)(lds + PG8_SB(b, h) + boff + n * 2048 + k * 1024); } while (0)
; #define PG8_WAIT_V(n) asm volatile("s_waitcnt vmcnt(" #n ")" ::: "memory")
; template <class Epi, class Sched>
; DI void gemm_phase(LAS unsigned char* lds, const Gemm g, const Sched& S, const Epi& E) {
;     ...
;     for (int t = 0; t < nt; t += 2) {
;       const bool last = (t == nt - 2);
;       const char* a1 = cA + (size_t)(t + 1) * kstep;
;       const char* a2 = last ? nA : cA + (size_t)(t + 2) * kstep; const char* b2 = last ? nB : cB + (size_t)(t + 2) * kstep;
;       const char* a3 = a2 + kstep; const char* b3 = b2 + kstep;
;       PG8_LDB(B0, 0, 0); PG8_SCHED; PG8_LDA(At, 0, 0); PG8_STAGE(PG8_SA(1, 1), a1 + hstep, voffA);
;       PG8_WAIT_L(8); PG8_BAR; PG8_WAIT_L(0); PG8_MMA(0, 0, At, B0); PG8_BAR; PG8_SCHED;
;       PG8_LDB(B1, 0, 1); PG8_STAGE(PG8_SB(0, 0), b2, voffB);
;       PG8_BAR; PG8_WAIT_L(0); PG8_MMA(0, 1, At, B1); PG8_BAR;
;       PG8_LDA(At, 0, 1); PG8_STAGE(PG8_SA(0, 0), a2, voffA);
;       PG8_BAR; PG8_WAIT_L(0); PG8_MMA(1, 0, At, B0); PG8_BAR; PG8_SCHED;
;       PG8_STAGE(PG8_SB(0, 1), b2 + hstep, voffB);
;       PG8_WAIT_V(6); PG8_BAR; PG8_MMA(1, 1, At, B1); PG8_BAR;
;       PG8_LDB(B0, 1, 0); PG8_SCHED; PG8_LDA(At, 1, 0); PG8_STAGE(PG8_SA(0, 1), a2 + hstep, voffA);
;       PG8_WAIT_L(8); PG8_BAR; PG8_WAIT_L(0); PG8_MMA(0, 0, At, B0); PG8_BAR; PG8_SCHED;
;       PG8_LDB(B1, 1, 1); PG8_STAGE(PG8_SB(1, 0), b3, voffB);
;       PG8_BAR; PG8_WAIT_L(0); PG8_MMA(0, 1, At, B1); PG8_BAR;
;       PG8_LDA(At, 1, 1); PG8_STAGE(PG8_SA(1, 0), a3, voffA);
;       PG8_BAR; PG8_WAIT_L(0); PG8_MMA(1, 0, At, B0); PG8_BAR; PG8_SCHED;
;       PG8_STAGE(PG8_SB(1, 1), b3 + hstep, voffB);
;       PG8_WAIT_V(6); PG8_BAR; PG8_MMA(1, 1, At, B1); PG8_BAR;
;     }
	s_waitcnt lgkmcnt(0)
	s_waitcnt lgkmcnt(0)
	v_mfma_f32_16x16x32_bf16 v[60:63], v[136:139], v[158:161], v[60:63]
	v_mfma_f32_16x16x32_bf16 v[56:59], v[150:153], v[158:161], v[56:59]
	v_mfma_f32_16x16x32_bf16 v[44:47], v[136:139], v[166:169], v[44:47]
	v_mfma_f32_16x16x32_bf16 v[40:43], v[150:153], v[166:169], v[40:43]
	v_mfma_f32_16x16x32_bf16 v[28:31], v[136:139], v[174:177], v[28:31]
	v_mfma_f32_16x16x32_bf16 v[24:27], v[150:153], v[174:177], v[24:27]
	v_mfma_f32_16x16x32_bf16 v[12:15], v[136:139], v[196:199], v[12:15]
	v_mfma_f32_16x16x32_bf16 v[8:11], v[150:153], v[196:199], v[8:11]
	v_mfma_f32_16x16x32_bf16 v[60:63], v[146:149], v[162:165], v[60:63]
	v_mfma_f32_16x16x32_bf16 v[56:59], v[154:157], v[162:165], v[56:59]
	v_mfma_f32_16x16x32_bf16 v[44:47], v[146:149], v[170:173], v[44:47]
	v_mfma_f32_16x16x32_bf16 v[40:43], v[154:157], v[170:173], v[40:43]
	v_mfma_f32_16x16x32_bf16 v[28:31], v[146:149], v[178:181], v[28:31]
	v_mfma_f32_16x16x32_bf16 v[24:27], v[154:157], v[178:181], v[24:27]
	v_mfma_f32_16x16x32_bf16 v[12:15], v[146:149], v[200:203], v[12:15]
	v_mfma_f32_16x16x32_bf16 v[8:11], v[154:157], v[200:203], v[8:11]
	s_barrier
	s_mov_b32 m0, s69
	v_lshl_add_u64 v[136:137], s[42:43], 0, v[130:131]
	global_load_lds_dwordx4 v[136:137], off
	v_lshl_add_u64 v[136:137], s[42:43], 0, v[134:135]
	s_mov_b32 m0, s68
	s_nop 0
	global_load_lds_dwordx4 v[136:137], off
	s_waitcnt vmcnt(6)
	s_barrier
	v_mfma_f32_16x16x32_bf16 v[52:55], v[204:207], v[158:161], v[52:55]
	v_mfma_f32_16x16x32_bf16 v[48:51], v[212:215], v[158:161], v[48:51]
	v_mfma_f32_16x16x32_bf16 v[36:39], v[204:207], v[166:169], v[36:39]
	v_mfma_f32_16x16x32_bf16 v[32:35], v[212:215], v[166:169], v[32:35]
	v_mfma_f32_16x16x32_bf16 v[20:23], v[204:207], v[174:177], v[20:23]
	v_mfma_f32_16x16x32_bf16 v[16:19], v[212:215], v[174:177], v[16:19]
	v_mfma_f32_16x16x32_bf16 v[4:7], v[204:207], v[196:199], v[4:7]
	v_mfma_f32_16x16x32_bf16 v[0:3], v[212:215], v[196:199], v[0:3]
	v_mfma_f32_16x16x32_bf16 v[52:55], v[208:211], v[162:165], v[52:55]
	v_mfma_f32_16x16x32_bf16 v[48:51], v[216:219], v[162:165], v[48:51]
	v_mfma_f32_16x16x32_bf16 v[36:39], v[208:211], v[170:173], v[36:39]
	v_mfma_f32_16x16x32_bf16 v[32:35], v[216:219], v[170:173], v[32:35]
	v_mfma_f32_16x16x32_bf16 v[20:23], v[208:211], v[178:181], v[20:23]
	v_mfma_f32_16x16x32_bf16 v[16:19], v[216:219], v[178:181], v[16:19]
	v_mfma_f32_16x16x32_bf16 v[4:7], v[208:211], v[200:203], v[4:7]
	v_mfma_f32_16x16x32_bf16 v[0:3], v[216:219], v[200:203], v[0:3]
	v_add_u32_e32 v144, s67, v142
	s_barrier
	ds_read_b128 v[136:139], v144
	ds_read_b128 v[146:149], v144 offset:1024
	ds_read_b128 v[150:153], v144 offset:2048
	ds_read_b128 v[154:157], v144 offset:3072
	s_mov_b32 m0, s58
	v_lshl_add_u64 v[204:205], s[40:41], 0, v[128:129]
	ds_read_b128 v[158:161], v143 offset:32768
	ds_read_b128 v[162:165], v143 offset:33792
	ds_read_b128 v[166:169], v143 offset:34816
	ds_read_b128 v[170:173], v143 offset:35840
	ds_read_b128 v[174:177], v143 offset:36864
	ds_read_b128 v[178:181], v143 offset:37888
	ds_read_b128 v[196:199], v143 offset:38912
	ds_read_b128 v[200:203], v143 offset:39936
	global_load_lds_dwordx4 v[204:205], off
	v_lshl_add_u64 v[204:205], s[40:41], 0, v[132:133]
	s_mov_b32 m0, s59
	s_nop 0
	global_load_lds_dwordx4 v[204:205], off
	s_waitcnt lgkmcnt(8)
	s_barrier
	s_waitcnt lgkmcnt(0)
	s_waitcnt lgkmcnt(0)
	v_mfma_f32_16x16x32_bf16 v[124:127], v[136:139], v[158:161], v[124:127]
	v_mfma_f32_16x16x32_bf16 v[120:123], v[150:153], v[158:161], v[120:123]
	v_mfma_f32_16x16x32_bf16 v[108:111], v[136:139], v[166:169], v[108:111]
	v_mfma_f32_16x16x32_bf16 v[104:107], v[150:153], v[166:169], v[104:107]
	v_mfma_f32_16x16x32_bf16 v[92:95], v[136:139], v[174:177], v[92:95]
	v_mfma_f32_16x16x32_bf16 v[88:91], v[150:153], v[174:177], v[88:91]
	v_mfma_f32_16x16x32_bf16 v[76:79], v[136:139], v[196:199], v[76:79]
	v_mfma_f32_16x16x32_bf16 v[72:75], v[150:153], v[196:199], v[72:75]
	v_mfma_f32_16x16x32_bf16 v[124:127], v[146:149], v[162:165], v[124:127]
	v_mfma_f32_16x16x32_bf16 v[120:123], v[154:157], v[162:165], v[120:123]
	v_mfma_f32_16x16x32_bf16 v[108:111], v[146:149], v[170:173], v[108:111]
	v_mfma_f32_16x16x32_bf16 v[104:107], v[154:157], v[170:173], v[104:107]
	v_mfma_f32_16x16x32_bf16 v[92:95], v[146:149], v[178:181], v[92:95]
	v_mfma_f32_16x16x32_bf16 v[88:91], v[154:157], v[178:181], v[88:91]
	v_mfma_f32_16x16x32_bf16 v[76:79], v[146:149], v[200:203], v[76:79]
	v_mfma_f32_16x16x32_bf16 v[72:75], v[154:157], v[200:203], v[72:75]
	s_barrier
	s_mov_b32 m0, s66
	v_add_u32_e32 v144, s65, v142
	v_lshl_add_u64 v[140:141], v[140:141], 0, s[0:1]
	ds_read_b128 v[204:207], v144
	ds_read_b128 v[208:211], v144 offset:1024
	ds_read_b128 v[212:215], v144 offset:2048
	ds_read_b128 v[216:219], v144 offset:3072
	global_load_lds_dwordx4 v[140:141], off
	v_lshl_add_u64 v[140:141], v[220:221], 0, s[0:1]
	s_mov_b32 m0, s64
	s_nop 0
	global_load_lds_dwordx4 v[140:141], off
	s_barrier
; #define PG8_WAIT_V(n) asm volatile("s_waitcnt vmcnt(" #n ")" ::: "memory")
; #define PG8_WAIT_L(n) asm volatile("s_waitcnt lgkmcnt(" #n ")" ::: "memory")
; template <class Epi, class Sched>
; DI void gemm_phase(LAS unsigned char* lds, const Gemm g, const Sched& S, const Epi& E) {
;     ...
;     for (int t = 0; t < nt; t += 2) {
;       const bool last = (t == nt - 2);
;       const char* a1 = cA + (size_t)(t + 1) * kstep;
;       const char* a2 = last ? nA : cA + (size_t)(t + 2) * kstep; const char* b2 = last ? nB : cB + (size_t)(t + 2) * kstep;
;       const char* a3 = a2 + kstep; const char* b3 = b2 + kstep;
;       PG8_LDB(B0, 0, 0); PG8_SCHED; PG8_LDA(At, 0, 0); PG8_STAGE(PG8_SA(1, 1), a1 + hstep, voffA);
;       PG8_WAIT_L(8); PG8_BAR; PG8_WAIT_L(0); PG8_MMA(0, 0, At, B0); PG8_BAR; PG8_SCHED;
;       PG8_LDB(B1, 0, 1); PG8_STAGE(PG8_SB(0, 0), b2, voffB);
;       PG8_BAR; PG8_WAIT_L(0); PG8_MMA(0, 1, At, B1); PG8_BAR;
;       PG8_LDA(At, 0, 1); PG8_STAGE(PG8_SA(0, 0), a2, voffA);
;       PG8_BAR; PG8_WAIT_L(0); PG8_MMA(1, 0, At, B0); PG8_BAR; PG8_SCHED;
;       PG8_STAGE(PG8_SB(0, 1), b2 + hstep, voffB);
;       PG8_WAIT_V(6); PG8_BAR; PG8_MMA(1, 1, At, B1); PG8_BAR;
;       PG8_LDB(B0, 1, 0); PG8_SCHED; PG8_LDA(At, 1, 0); PG8_STAGE(PG8_SA(0, 1), a2 + hstep, voffA);
;       PG8_WAIT_L(8); PG8_BAR; PG8_WAIT_L(0); PG8_MMA(0, 0, At, B0); PG8_BAR; PG8_SCHED;
;       PG8_LDB(B1, 1, 1); PG8_STAGE(PG8_SB(1, 0), b3, voffB);
;       PG8_BAR; PG8_WAIT_L(0); PG8_MMA(0, 1, At, B1); PG8_BAR;
;       PG8_LDA(At, 1, 1); PG8_STAGE(PG8_SA(1, 0), a3, voffA);
;       PG8_BAR; PG8_WAIT_L(0); PG8_MMA(1, 0, At, B0); PG8_BAR; PG8_SCHED;
;       PG8_STAGE(PG8_SB(1, 1), b3 + hstep, voffB);
;       PG8_WAIT_V(6); PG8_BAR; PG8_MMA(1, 1, At, B1); PG8_BAR;
;     }
;   DI void operator()(const f32x4 (&acc)[2][2][4][2], const pg8::Unit& u, int wr, int wc, int fr_, int fq_) const {
;     ...
;             } else if (EPI == EPI_UKV) {
;               if (n == 0) {
;                 const int gb = u.pn * 256 + bj * 128 + wc * 32;
;                 const int hd = gb >> 7, within = (gb & 127) + 8 * fq;
;                 const f32x4 v1 = acc[ai][bj][m][1];
;                 if (within < 64) st_bf8((u16*)(big + E_KNOPE) + (size_t)token * 512 + hd * 64 + within, v, v1, rinv);
;                 else st_bf8((u16*)(big + E_VMLAT) + (size_t)token * 512 + hd * 64 + (within - 64), v, v1, rinv);
;               }
	s_waitcnt lgkmcnt(0)
	s_waitcnt lgkmcnt(0)
	v_mfma_f32_16x16x32_bf16 v[116:119], v[204:207], v[158:161], v[116:119]
	v_mfma_f32_16x16x32_bf16 v[112:115], v[212:215], v[158:161], v[112:115]
	v_mfma_f32_16x16x32_bf16 v[100:103], v[204:207], v[166:169], v[100:103]
	v_mfma_f32_16x16x32_bf16 v[96:99], v[212:215], v[166:169], v[96:99]
	v_mfma_f32_16x16x32_bf16 v[84:87], v[204:207], v[174:177], v[84:87]
	v_mfma_f32_16x16x32_bf16 v[80:83], v[212:215], v[174:177], v[80:83]
	v_mfma_f32_16x16x32_bf16 v[68:71], v[204:207], v[196:199], v[68:71]
	v_mfma_f32_16x16x32_bf16 v[64:67], v[212:215], v[196:199], v[64:67]
	v_mfma_f32_16x16x32_bf16 v[116:119], v[208:211], v[162:165], v[116:119]
	v_mfma_f32_16x16x32_bf16 v[112:115], v[216:219], v[162:165], v[112:115]
	v_mfma_f32_16x16x32_bf16 v[100:103], v[208:211], v[170:173], v[100:103]
	v_mfma_f32_16x16x32_bf16 v[96:99], v[216:219], v[170:173], v[96:99]
	v_mfma_f32_16x16x32_bf16 v[84:87], v[208:211], v[178:181], v[84:87]
	v_mfma_f32_16x16x32_bf16 v[80:83], v[216:219], v[178:181], v[80:83]
	v_mfma_f32_16x16x32_bf16 v[68:71], v[208:211], v[200:203], v[68:71]
	v_mfma_f32_16x16x32_bf16 v[64:67], v[216:219], v[200:203], v[64:67]
	s_mov_b32 m0, s62
	v_lshl_add_u64 v[140:141], v[222:223], 0, s[0:1]
	s_barrier
	ds_read_b128 v[158:161], v143 offset:49152
	ds_read_b128 v[162:165], v143 offset:50176
	ds_read_b128 v[166:169], v143 offset:51200
	ds_read_b128 v[170:173], v143 offset:52224
	ds_read_b128 v[174:177], v143 offset:53248
	ds_read_b128 v[178:181], v143 offset:54272
	ds_read_b128 v[196:199], v143 offset:55296
	ds_read_b128 v[200:203], v143 offset:56320
	global_load_lds_dwordx4 v[140:141], off
	v_lshl_add_u64 v[140:141], v[224:225], 0, s[0:1]
	s_mov_b32 m0, s63
	s_nop 0
	global_load_lds_dwordx4 v[140:141], off
	s_barrier
	s_waitcnt lgkmcnt(0)
	s_waitcnt lgkmcnt(0)
	v_mfma_f32_16x16x32_bf16 v[60:63], v[136:139], v[158:161], v[60:63]
	v_mfma_f32_16x16x32_bf16 v[56:59], v[150:153], v[158:161], v[56:59]
	v_mfma_f32_16x16x32_bf16 v[44:47], v[136:139], v[166:169], v[44:47]
	v_mfma_f32_16x16x32_bf16 v[40:43], v[150:153], v[166:169], v[40:43]
	v_mfma_f32_16x16x32_bf16 v[28:31], v[136:139], v[174:177], v[28:31]
	v_mfma_f32_16x16x32_bf16 v[24:27], v[150:153], v[174:177], v[24:27]
	v_mfma_f32_16x16x32_bf16 v[12:15], v[136:139], v[196:199], v[12:15]
	v_mfma_f32_16x16x32_bf16 v[8:11], v[150:153], v[196:199], v[8:11]
	v_mfma_f32_16x16x32_bf16 v[60:63], v[146:149], v[162:165], v[60:63]
	v_mfma_f32_16x16x32_bf16 v[56:59], v[154:157], v[162:165], v[56:59]
	v_mfma_f32_16x16x32_bf16 v[44:47], v[146:149], v[170:173], v[44:47]
	v_mfma_f32_16x16x32_bf16 v[40:43], v[154:157], v[170:173], v[40:43]
	v_mfma_f32_16x16x32_bf16 v[28:31], v[146:149], v[178:181], v[28:31]
	v_mfma_f32_16x16x32_bf16 v[24:27], v[154:157], v[178:181], v[24:27]
	v_mfma_f32_16x16x32_bf16 v[12:15], v[146:149], v[200:203], v[12:15]
	v_mfma_f32_16x16x32_bf16 v[8:11], v[154:157], v[200:203], v[8:11]
	s_barrier
	s_mov_b32 m0, s71
	v_lshl_add_u64 v[136:137], s[36:37], 0, v[130:131]
	global_load_lds_dwordx4 v[136:137], off
	v_lshl_add_u64 v[136:137], s[36:37], 0, v[134:135]
	s_mov_b32 m0, s70
	s_nop 0
	global_load_lds_dwordx4 v[136:137], off
	s_waitcnt vmcnt(6)
	s_barrier
	v_mfma_f32_16x16x32_bf16 v[52:55], v[204:207], v[158:161], v[52:55]
	v_mfma_f32_16x16x32_bf16 v[48:51], v[212:215], v[158:161], v[48:51]
	v_mfma_f32_16x16x32_bf16 v[36:39], v[204:207], v[166:169], v[36:39]
	v_mfma_f32_16x16x32_bf16 v[32:35], v[212:215], v[166:169], v[32:35]
	v_mfma_f32_16x16x32_bf16 v[20:23], v[204:207], v[174:177], v[20:23]
	v_mfma_f32_16x16x32_bf16 v[16:19], v[212:215], v[174:177], v[16:19]
	v_mfma_f32_16x16x32_bf16 v[4:7], v[204:207], v[196:199], v[4:7]
	v_mfma_f32_16x16x32_bf16 v[0:3], v[212:215], v[196:199], v[0:3]
	v_mfma_f32_16x16x32_bf16 v[52:55], v[208:211], v[162:165], v[52:55]
	v_mfma_f32_16x16x32_bf16 v[48:51], v[216:219], v[162:165], v[48:51]
	v_mfma_f32_16x16x32_bf16 v[36:39], v[208:211], v[170:173], v[36:39]
	v_mfma_f32_16x16x32_bf16 v[32:35], v[216:219], v[170:173], v[32:35]
	v_mfma_f32_16x16x32_bf16 v[20:23], v[208:211], v[178:181], v[20:23]
	v_mfma_f32_16x16x32_bf16 v[16:19], v[216:219], v[178:181], v[16:19]
	v_mfma_f32_16x16x32_bf16 v[4:7], v[208:211], v[200:203], v[4:7]
	v_mfma_f32_16x16x32_bf16 v[0:3], v[216:219], v[200:203], v[0:3]
	s_andn2_b64 vcc, exec, s[34:35]
	s_mov_b64 s[36:37], -1
	s_mov_b64 s[34:35], 0
	s_mov_b64 s[40:41], 0x100
	s_barrier
	s_cbranch_vccz .LBB0_1346
	v_mov_b32_e32 v136, v182
	s_lshl_b32 s3, s3, 10
	s_add_i32 s3, s3, 0
	v_and_or_b32 v147, v136, 15, s60
	v_lshl_add_u32 v137, v147, 2, s3
	v_add_u32_e32 v146, 0x20000, v137
	ds_read_b32 v138, v146
	s_lshl_b32 s13, s20, 8
	v_lshrrev_b32_e32 v136, 1, v136
	v_and_or_b32 v139, v136, 24, s61
	v_add_u32_e32 v136, s13, v147
	v_ashrrev_i32_e32 v137, 31, v136
	s_waitcnt lgkmcnt(0)
	v_pk_mul_f32 v[124:125], v[124:125], v[138:139] op_sel_hi:[1,0]
	v_pk_mul_f32 v[126:127], v[126:127], v[138:139] op_sel_hi:[1,0]
	v_pk_mul_f32 v[120:121], v[120:121], v[138:139] op_sel_hi:[1,0]
	v_lshlrev_b64 v[140:141], 10, v[136:137]
	s_lshl_b32 s20, s2, 7
	v_cvt_pk_bf16_f32 v124, v124, v125
	v_cvt_pk_bf16_f32 v125, v126, v127
	v_cvt_pk_bf16_f32 v126, v120, v121
	v_pk_mul_f32 v[120:121], v[122:123], v[138:139] op_sel_hi:[1,0]
	s_ashr_i32 s21, s20, 31
	v_cvt_pk_bf16_f32 v127, v120, v121
	v_lshl_add_u64 v[120:121], s[6:7], 0, v[140:141]
	s_mov_b64 s[2:3], -1
	s_and_b64 vcc, exec, s[4:5]
	v_lshl_add_u64 v[120:121], s[20:21], 1, v[120:121]
	v_lshlrev_b32_e32 v144, 1, v139
	s_cbranch_vccz .LBB0_1349
	v_lshl_add_u64 v[122:123], v[120:121], 0, v[144:145]
	v_add_co_u32_e32 v122, vcc, 0xd9ff000, v122
	s_mov_b64 s[2:3], 0
	s_nop 0
	v_addc_co_u32_e32 v123, vcc, 0, v123, vcc
	global_store_dwordx4 v[122:123], v[124:127], off offset:3968

; #define PG8_STAGE(bufoff, gbase, voff) do { _Pragma("unroll") for (int _i = 0; _i < 2; ++_i) \
;     __builtin_amdgcn_global_load_lds((const unsigned*)((const char*)(gbase) + (voff)[_i]), (LAS unsigned*)(lds + (bufoff) + ldsw + _i * 8192), 16, 0, 0); } while (0)
; #define PG8_LDA(dst, b, h) do { _Pragma("unroll") for (int m = 0; m < 4; ++m) _Pragma("unroll") for (int k = 0; k < 2; ++k) dst[m][k] = *(const LAS bf16x8*)(lds + PG8_SA(b, h) + aoff + m * 2048 + k * 1024); } while (0)
; #define PG8_LDB(dst, b, h) do { _Pragma("unroll") for (int n = 0; n < 2; ++n) _Pragma("unroll") for (int k = 0; k < 2; ++k) dst[n][k] = *(const LAS bf16x8*)(lds + PG8_SB(b, h) + boff + n * 2048 + k * 1024); } while (0)
; #define PG8_WAIT_V(n) asm volatile("s_waitcnt vmcnt(" #n ")" ::: "memory")
; template <class Epi, class Sched>
; DI void gemm_phase(LAS unsigned char* lds, const Gemm g, const Sched& S, const Epi& E) {
;     ...
;     for (int t = 0; t < nt; t += 2) {
;       const bool last = (t == nt - 2);
;       const char* a1 = cA + (size_t)(t + 1) * kstep;
;       const char* a2 = last ? nA : cA + (size_t)(t + 2) * kstep; const char* b2 = last ? nB : cB + (size_t)(t + 2) * kstep;
;       const char* a3 = a2 + kstep; const char* b3 = b2 + kstep;
;       PG8_LDB(B0, 0, 0); PG8_SCHED; PG8_LDA(At, 0, 0); PG8_STAGE(PG8_SA(1, 1), a1 + hstep, voffA);
;       PG8_WAIT_L(8); PG8_BAR; PG8_WAIT_L(0); PG8_MMA(0, 0, At, B0); PG8_BAR; PG8_SCHED;
;       PG8_LDB(B1, 0, 1); PG8_STAGE(PG8_SB(0, 0), b2, voffB);
;       PG8_BAR; PG8_WAIT_L(0); PG8_MMA(0, 1, At, B1); PG8_BAR;
;       PG8_LDA(At, 0, 1); PG8_STAGE(PG8_SA(0, 0), a2, voffA);
;       PG8_BAR; PG8_WAIT_L(0); PG8_MMA(1, 0, At, B0); PG8_BAR; PG8_SCHED;
;       PG8_STAGE(PG8_SB(0, 1), b2 + hstep, voffB);
;       PG8_WAIT_V(6); PG8_BAR; PG8_MMA(1, 1, At, B1); PG8_BAR;
;       PG8_LDB(B0, 1, 0); PG8_SCHED; PG8_LDA(At, 1, 0); PG8_STAGE(PG8_SA(0, 1), a2 + hstep, voffA);
;       PG8_WAIT_L(8); PG8_BAR; PG8_WAIT_L(0); PG8_MMA(0, 0, At, B0); PG8_BAR; PG8_SCHED;
;       PG8_LDB(B1, 1, 1); PG8_STAGE(PG8_SB(1, 0), b3, voffB);
;       PG8_BAR; PG8_WAIT_L(0); PG8_MMA(0, 1, At, B1); PG8_BAR;
;       PG8_LDA(At, 1, 1); PG8_STAGE(PG8_SA(1, 0), a3, voffA);
;       PG8_BAR; PG8_WAIT_L(0); PG8_MMA(1, 0, At, B0); PG8_BAR; PG8_SCHED;
;       PG8_STAGE(PG8_SB(1, 1), b3 + hstep, voffB);
;       PG8_WAIT_V(6); PG8_BAR; PG8_MMA(1, 1, At, B1); PG8_BAR;
;     }
.LBB0_1644:
	s_add_u32 s4, s2, 0xfffc0080
	s_addc_u32 s5, s3, -1
	s_add_i32 s55, 0, 0x10000
	v_add_u32_e32 v152, s55, v158
	ds_read_b128 v[128:131], v152
	ds_read_b128 v[132:135], v152 offset:1024
	ds_read_b128 v[148:151], v152 offset:2048
	ds_read_b128 v[152:155], v152 offset:3072
	s_cmp_eq_u32 s54, 12
	s_cselect_b32 s29, s19, s5
	s_cselect_b32 s28, s35, s4
	s_cselect_b32 s5, s17, s53
	s_cselect_b32 s4, s51, s52
	v_lshl_add_u64 v[156:157], s[2:3], 0, v[142:143]
	s_add_i32 m0, s41, 0xc000
	ds_read_b128 v[160:163], v159
	ds_read_b128 v[164:167], v159 offset:1024
	ds_read_b128 v[168:171], v159 offset:2048
	ds_read_b128 v[172:175], v159 offset:3072
	ds_read_b128 v[176:179], v159 offset:4096
	ds_read_b128 v[196:199], v159 offset:5120
	ds_read_b128 v[200:203], v159 offset:6144
	ds_read_b128 v[204:207], v159 offset:7168
	global_load_lds_dwordx4 v[156:157], off
	v_lshl_add_u64 v[156:157], s[2:3], 0, v[146:147]
	s_add_i32 m0, s41, 0xe000
	s_nop 0
	global_load_lds_dwordx4 v[156:157], off
	s_waitcnt lgkmcnt(8)
	s_barrier
	s_waitcnt lgkmcnt(0)
	s_waitcnt lgkmcnt(0)
	v_mfma_f32_16x16x32_bf16 v[124:127], v[128:131], v[160:163], v[124:127]
	v_mfma_f32_16x16x32_bf16 v[120:123], v[148:151], v[160:163], v[120:123]
	v_mfma_f32_16x16x32_bf16 v[108:111], v[128:131], v[168:171], v[108:111]
	v_mfma_f32_16x16x32_bf16 v[104:107], v[148:151], v[168:171], v[104:107]
	v_mfma_f32_16x16x32_bf16 v[92:95], v[128:131], v[176:179], v[92:95]
	v_mfma_f32_16x16x32_bf16 v[88:91], v[148:151], v[176:179], v[88:91]
	v_mfma_f32_16x16x32_bf16 v[76:79], v[128:131], v[200:203], v[76:79]
	v_mfma_f32_16x16x32_bf16 v[72:75], v[148:151], v[200:203], v[72:75]
	v_mfma_f32_16x16x32_bf16 v[124:127], v[132:135], v[164:167], v[124:127]
	v_mfma_f32_16x16x32_bf16 v[120:123], v[152:155], v[164:167], v[120:123]
	v_mfma_f32_16x16x32_bf16 v[108:111], v[132:135], v[172:175], v[108:111]
	v_mfma_f32_16x16x32_bf16 v[104:107], v[152:155], v[172:175], v[104:107]
	v_mfma_f32_16x16x32_bf16 v[92:95], v[132:135], v[196:199], v[92:95]
	v_mfma_f32_16x16x32_bf16 v[88:91], v[152:155], v[196:199], v[88:91]
	v_mfma_f32_16x16x32_bf16 v[76:79], v[132:135], v[204:207], v[76:79]
	v_mfma_f32_16x16x32_bf16 v[72:75], v[152:155], v[204:207], v[72:75]
	s_barrier
	s_add_i32 s58, 0, 0x14000
	v_add_u32_e32 v156, s58, v158
	s_add_i32 s55, s55, s40
	ds_read_b128 v[208:211], v156
	ds_read_b128 v[212:215], v156 offset:1024
	ds_read_b128 v[216:219], v156 offset:2048
	ds_read_b128 v[220:223], v156 offset:3072
	v_lshl_add_u64 v[156:157], s[4:5], 0, v[144:145]
	s_mov_b32 m0, s55
	v_lshl_add_u64 v[180:181], s[4:5], 0, v[136:137]
	global_load_lds_dwordx4 v[156:157], off
	s_add_i32 m0, s55, 0x2000
	s_nop 0
	global_load_lds_dwordx4 v[180:181], off
	s_barrier
	s_waitcnt lgkmcnt(0)
	s_waitcnt lgkmcnt(0)
	v_mfma_f32_16x16x32_bf16 v[116:119], v[208:211], v[160:163], v[116:119]
	v_mfma_f32_16x16x32_bf16 v[112:115], v[216:219], v[160:163], v[112:115]
	v_mfma_f32_16x16x32_bf16 v[100:103], v[208:211], v[168:171], v[100:103]
	v_mfma_f32_16x16x32_bf16 v[96:99], v[216:219], v[168:171], v[96:99]
	v_mfma_f32_16x16x32_bf16 v[84:87], v[208:211], v[176:179], v[84:87]
	v_mfma_f32_16x16x32_bf16 v[80:83], v[216:219], v[176:179], v[80:83]
	v_mfma_f32_16x16x32_bf16 v[68:71], v[208:211], v[200:203], v[68:71]
	v_mfma_f32_16x16x32_bf16 v[64:67], v[216:219], v[200:203], v[64:67]
	v_mfma_f32_16x16x32_bf16 v[116:119], v[212:215], v[164:167], v[116:119]
	v_mfma_f32_16x16x32_bf16 v[112:115], v[220:223], v[164:167], v[112:115]
	v_mfma_f32_16x16x32_bf16 v[100:103], v[212:215], v[172:175], v[100:103]
	v_mfma_f32_16x16x32_bf16 v[96:99], v[220:223], v[172:175], v[96:99]
	v_mfma_f32_16x16x32_bf16 v[84:87], v[212:215], v[196:199], v[84:87]
	v_mfma_f32_16x16x32_bf16 v[80:83], v[220:223], v[196:199], v[80:83]
	v_mfma_f32_16x16x32_bf16 v[68:71], v[212:215], v[204:207], v[68:71]
	v_mfma_f32_16x16x32_bf16 v[64:67], v[220:223], v[204:207], v[64:67]
	s_mov_b32 m0, s41
	v_lshl_add_u64 v[224:225], s[28:29], 0, v[140:141]
	s_barrier
	ds_read_b128 v[160:163], v159 offset:16384
	ds_read_b128 v[164:167], v159 offset:17408
	ds_read_b128 v[168:171], v159 offset:18432
	ds_read_b128 v[172:175], v159 offset:19456
	ds_read_b128 v[176:179], v159 offset:20480
	ds_read_b128 v[196:199], v159 offset:21504
	ds_read_b128 v[200:203], v159 offset:22528
	ds_read_b128 v[204:207], v159 offset:23552
	global_load_lds_dwordx4 v[224:225], off
	v_lshl_add_u64 v[226:227], s[28:29], 0, v[138:139]
	s_mov_b32 m0, s42
	s_nop 0
	global_load_lds_dwordx4 v[226:227], off
	s_barrier
	s_waitcnt lgkmcnt(0)
	s_waitcnt lgkmcnt(0)
	v_mfma_f32_16x16x32_bf16 v[60:63], v[128:131], v[160:163], v[60:63]
	v_mfma_f32_16x16x32_bf16 v[56:59], v[148:151], v[160:163], v[56:59]
	v_mfma_f32_16x16x32_bf16 v[44:47], v[128:131], v[168:171], v[44:47]
	v_mfma_f32_16x16x32_bf16 v[40:43], v[148:151], v[168:171], v[40:43]
	v_mfma_f32_16x16x32_bf16 v[28:31], v[128:131], v[176:179], v[28:31]
	v_mfma_f32_16x16x32_bf16 v[24:27], v[148:151], v[176:179], v[24:27]
	v_mfma_f32_16x16x32_bf16 v[12:15], v[128:131], v[200:203], v[12:15]
	v_mfma_f32_16x16x32_bf16 v[8:11], v[148:151], v[200:203], v[8:11]
	v_mfma_f32_16x16x32_bf16 v[60:63], v[132:135], v[164:167], v[60:63]
	v_mfma_f32_16x16x32_bf16 v[56:59], v[152:155], v[164:167], v[56:59]
	v_mfma_f32_16x16x32_bf16 v[44:47], v[132:135], v[172:175], v[44:47]
	v_mfma_f32_16x16x32_bf16 v[40:43], v[152:155], v[172:175], v[40:43]
	v_mfma_f32_16x16x32_bf16 v[28:31], v[132:135], v[196:199], v[28:31]
	v_mfma_f32_16x16x32_bf16 v[24:27], v[152:155], v[196:199], v[24:27]
	v_mfma_f32_16x16x32_bf16 v[12:15], v[132:135], v[204:207], v[12:15]
	v_mfma_f32_16x16x32_bf16 v[8:11], v[152:155], v[204:207], v[8:11]
	s_barrier
; #define PG8_STAGE(bufoff, gbase, voff) do { _Pragma("unroll") for (int _i = 0; _i < 2; ++_i) \
;     __builtin_amdgcn_global_load_lds((const unsigned*)((const char*)(gbase) + (voff)[_i]), (LAS unsigned*)(lds + (bufoff) + ldsw + _i * 8192), 16, 0, 0); } while (0)
; #define PG8_LDA(dst, b, h) do { _Pragma("unroll") for (int m = 0; m < 4; ++m) _Pragma("unroll") for (int k = 0; k < 2; ++k) dst[m][k] = *(const LAS bf16x8*)(lds + PG8_SA(b, h) + aoff + m * 2048 + k * 1024); } while (0)
; #define PG8_LDB(dst, b, h) do { _Pragma("unroll") for (int n = 0; n < 2; ++n) _Pragma("unroll") for (int k = 0; k < 2; ++k) dst[n][k] = *(const LAS bf16x8*)(lds + PG8_SB(b, h) + boff + n * 2048 + k * 1024); } while (0)
; #define PG8_WAIT_V(n) asm volatile("s_waitcnt vmcnt(" #n ")" ::: "memory")
; template <class Epi, class Sched>
; DI void gemm_phase(LAS unsigned char* lds, const Gemm g, const Sched& S, const Epi& E) {
;     ...
;     for (int t = 0; t < nt; t += 2) {
;       const bool last = (t == nt - 2);
;       const char* a1 = cA + (size_t)(t + 1) * kstep;
;       const char* a2 = last ? nA : cA + (size_t)(t + 2) * kstep; const char* b2 = last ? nB : cB + (size_t)(t + 2) * kstep;
;       const char* a3 = a2 + kstep; const char* b3 = b2 + kstep;
;       PG8_LDB(B0, 0, 0); PG8_SCHED; PG8_LDA(At, 0, 0); PG8_STAGE(PG8_SA(1, 1), a1 + hstep, voffA);
;       PG8_WAIT_L(8); PG8_BAR; PG8_WAIT_L(0); PG8_MMA(0, 0, At, B0); PG8_BAR; PG8_SCHED;
;       PG8_LDB(B1, 0, 1); PG8_STAGE(PG8_SB(0, 0), b2, voffB);
;       PG8_BAR; PG8_WAIT_L(0); PG8_MMA(0, 1, At, B1); PG8_BAR;
;       PG8_LDA(At, 0, 1); PG8_STAGE(PG8_SA(0, 0), a2, voffA);
;       PG8_BAR; PG8_WAIT_L(0); PG8_MMA(1, 0, At, B0); PG8_BAR; PG8_SCHED;
;       PG8_STAGE(PG8_SB(0, 1), b2 + hstep, voffB);
;       PG8_WAIT_V(6); PG8_BAR; PG8_MMA(1, 1, At, B1); PG8_BAR;
;       PG8_LDB(B0, 1, 0); PG8_SCHED; PG8_LDA(At, 1, 0); PG8_STAGE(PG8_SA(0, 1), a2 + hstep, voffA);
;       PG8_WAIT_L(8); PG8_BAR; PG8_WAIT_L(0); PG8_MMA(0, 0, At, B0); PG8_BAR; PG8_SCHED;
;       PG8_LDB(B1, 1, 1); PG8_STAGE(PG8_SB(1, 0), b3, voffB);
;       PG8_BAR; PG8_WAIT_L(0); PG8_MMA(0, 1, At, B1); PG8_BAR;
;       PG8_LDA(At, 1, 1); PG8_STAGE(PG8_SA(1, 0), a3, voffA);
;       PG8_BAR; PG8_WAIT_L(0); PG8_MMA(1, 0, At, B0); PG8_BAR; PG8_SCHED;
;       PG8_STAGE(PG8_SB(1, 1), b3 + hstep, voffB);
;       PG8_WAIT_V(6); PG8_BAR; PG8_MMA(1, 1, At, B1); PG8_BAR;
;     }
	s_add_u32 s56, s4, 0x40000
	s_addc_u32 s57, s5, 0
	s_add_i32 s55, s58, s40
	v_lshl_add_u64 v[128:129], s[56:57], 0, v[144:145]
	s_mov_b32 m0, s55
	s_nop 0
	global_load_lds_dwordx4 v[128:129], off
	v_lshl_add_u64 v[128:129], s[56:57], 0, v[136:137]
	s_add_i32 m0, s55, 0x2000
	s_nop 0
	global_load_lds_dwordx4 v[128:129], off
	s_waitcnt vmcnt(6)
	s_barrier
	v_mfma_f32_16x16x32_bf16 v[52:55], v[208:211], v[160:163], v[52:55]
	v_mfma_f32_16x16x32_bf16 v[48:51], v[216:219], v[160:163], v[48:51]
	v_mfma_f32_16x16x32_bf16 v[36:39], v[208:211], v[168:171], v[36:39]
	v_mfma_f32_16x16x32_bf16 v[32:35], v[216:219], v[168:171], v[32:35]
	v_mfma_f32_16x16x32_bf16 v[20:23], v[208:211], v[176:179], v[20:23]
	v_mfma_f32_16x16x32_bf16 v[16:19], v[216:219], v[176:179], v[16:19]
	v_mfma_f32_16x16x32_bf16 v[4:7], v[208:211], v[200:203], v[4:7]
	v_mfma_f32_16x16x32_bf16 v[0:3], v[216:219], v[200:203], v[0:3]
	v_mfma_f32_16x16x32_bf16 v[52:55], v[212:215], v[164:167], v[52:55]
	v_mfma_f32_16x16x32_bf16 v[48:51], v[220:223], v[164:167], v[48:51]
	v_mfma_f32_16x16x32_bf16 v[36:39], v[212:215], v[172:175], v[36:39]
	v_mfma_f32_16x16x32_bf16 v[32:35], v[220:223], v[172:175], v[32:35]
	v_mfma_f32_16x16x32_bf16 v[20:23], v[212:215], v[196:199], v[20:23]
	v_mfma_f32_16x16x32_bf16 v[16:19], v[220:223], v[196:199], v[16:19]
	v_mfma_f32_16x16x32_bf16 v[4:7], v[212:215], v[204:207], v[4:7]
	v_mfma_f32_16x16x32_bf16 v[0:3], v[220:223], v[204:207], v[0:3]
	s_add_i32 s55, 0, 0x18000
	v_add_u32_e32 v152, s55, v158
	s_barrier
	ds_read_b128 v[128:131], v152
	ds_read_b128 v[132:135], v152 offset:1024
	ds_read_b128 v[148:151], v152 offset:2048
	ds_read_b128 v[152:155], v152 offset:3072
	s_add_u32 s28, s28, 0x40000
	s_addc_u32 s29, s29, 0
	s_mov_b32 m0, s43
	v_lshl_add_u64 v[208:209], s[28:29], 0, v[140:141]
	ds_read_b128 v[160:163], v159 offset:32768
	ds_read_b128 v[164:167], v159 offset:33792
	ds_read_b128 v[168:171], v159 offset:34816
	ds_read_b128 v[172:175], v159 offset:35840
	ds_read_b128 v[176:179], v159 offset:36864
	ds_read_b128 v[196:199], v159 offset:37888
	ds_read_b128 v[200:203], v159 offset:38912
	ds_read_b128 v[204:207], v159 offset:39936
	global_load_lds_dwordx4 v[208:209], off
	v_lshl_add_u64 v[208:209], s[28:29], 0, v[138:139]
	s_mov_b32 m0, s44
	s_nop 0
	global_load_lds_dwordx4 v[208:209], off
	s_waitcnt lgkmcnt(8)
	s_barrier
	s_waitcnt lgkmcnt(0)
	s_waitcnt lgkmcnt(0)
	v_mfma_f32_16x16x32_bf16 v[124:127], v[128:131], v[160:163], v[124:127]
	v_mfma_f32_16x16x32_bf16 v[120:123], v[148:151], v[160:163], v[120:123]
	v_mfma_f32_16x16x32_bf16 v[108:111], v[128:131], v[168:171], v[108:111]
	v_mfma_f32_16x16x32_bf16 v[104:107], v[148:151], v[168:171], v[104:107]
	v_mfma_f32_16x16x32_bf16 v[92:95], v[128:131], v[176:179], v[92:95]
	v_mfma_f32_16x16x32_bf16 v[88:91], v[148:151], v[176:179], v[88:91]
	v_mfma_f32_16x16x32_bf16 v[76:79], v[128:131], v[200:203], v[76:79]
	v_mfma_f32_16x16x32_bf16 v[72:75], v[148:151], v[200:203], v[72:75]
	v_mfma_f32_16x16x32_bf16 v[124:127], v[132:135], v[164:167], v[124:127]
	v_mfma_f32_16x16x32_bf16 v[120:123], v[152:155], v[164:167], v[120:123]
	v_mfma_f32_16x16x32_bf16 v[108:111], v[132:135], v[172:175], v[108:111]
	v_mfma_f32_16x16x32_bf16 v[104:107], v[152:155], v[172:175], v[104:107]
	v_mfma_f32_16x16x32_bf16 v[92:95], v[132:135], v[196:199], v[92:95]
	v_mfma_f32_16x16x32_bf16 v[88:91], v[152:155], v[196:199], v[88:91]
	v_mfma_f32_16x16x32_bf16 v[76:79], v[132:135], v[204:207], v[76:79]
	v_mfma_f32_16x16x32_bf16 v[72:75], v[152:155], v[204:207], v[72:75]
	s_barrier
	s_add_i32 s28, 0, 0x1c000
	s_add_i32 s29, s55, s40
	v_add_u32_e32 v220, s28, v158
	v_lshl_add_u64 v[156:157], v[156:157], 0, s[0:1]
	s_mov_b32 m0, s29
	ds_read_b128 v[208:211], v220
	ds_read_b128 v[212:215], v220 offset:1024
	ds_read_b128 v[216:219], v220 offset:2048
	ds_read_b128 v[220:223], v220 offset:3072
	global_load_lds_dwordx4 v[156:157], off
	v_lshl_add_u64 v[156:157], v[180:181], 0, s[0:1]
	s_add_i32 m0, s29, 0x2000
	s_nop 0
	global_load_lds_dwordx4 v[156:157], off
	s_barrier
; #define PG8_BAR __builtin_amdgcn_s_barrier()
; template <class Epi, class Sched>
; DI void gemm_phase(LAS unsigned char* lds, const Gemm g, const Sched& S, const Epi& E) {
;     ...
;     for (int t = 0; t < nt; t += 2) {
;       const bool last = (t == nt - 2);
;       const char* a1 = cA + (size_t)(t + 1) * kstep;
;       const char* a2 = last ? nA : cA + (size_t)(t + 2) * kstep; const char* b2 = last ? nB : cB + (size_t)(t + 2) * kstep;
;       const char* a3 = a2 + kstep; const char* b3 = b2 + kstep;
;       PG8_LDB(B0, 0, 0); PG8_SCHED; PG8_LDA(At, 0, 0); PG8_STAGE(PG8_SA(1, 1), a1 + hstep, voffA);
;       PG8_WAIT_L(8); PG8_BAR; PG8_WAIT_L(0); PG8_MMA(0, 0, At, B0); PG8_BAR; PG8_SCHED;
;       PG8_LDB(B1, 0, 1); PG8_STAGE(PG8_SB(0, 0), b2, voffB);
;       PG8_BAR; PG8_WAIT_L(0); PG8_MMA(0, 1, At, B1); PG8_BAR;
;       PG8_LDA(At, 0, 1); PG8_STAGE(PG8_SA(0, 0), a2, voffA);
;       PG8_BAR; PG8_WAIT_L(0); PG8_MMA(1, 0, At, B0); PG8_BAR; PG8_SCHED;
;       PG8_STAGE(PG8_SB(0, 1), b2 + hstep, voffB);
;       PG8_WAIT_V(6); PG8_BAR; PG8_MMA(1, 1, At, B1); PG8_BAR;
;       PG8_LDB(B0, 1, 0); PG8_SCHED; PG8_LDA(At, 1, 0); PG8_STAGE(PG8_SA(0, 1), a2 + hstep, voffA);
;       PG8_WAIT_L(8); PG8_BAR; PG8_WAIT_L(0); PG8_MMA(0, 0, At, B0); PG8_BAR; PG8_SCHED;
;       PG8_LDB(B1, 1, 1); PG8_STAGE(PG8_SB(1, 0), b3, voffB);
;       PG8_BAR; PG8_WAIT_L(0); PG8_MMA(0, 1, At, B1); PG8_BAR;
;       PG8_LDA(At, 1, 1); PG8_STAGE(PG8_SA(1, 0), a3, voffA);
;       PG8_BAR; PG8_WAIT_L(0); PG8_MMA(1, 0, At, B0); PG8_BAR; PG8_SCHED;
;       PG8_STAGE(PG8_SB(1, 1), b3 + hstep, voffB);
;       PG8_WAIT_V(6); PG8_BAR; PG8_MMA(1, 1, At, B1); PG8_BAR;
;     }
;   DI void operator()(const f32x4 (&acc)[2][2][4][2], const pg8::Unit& u, int wr, int wc, int fr_, int fq_) const {
;     ...
;             } else if (EPI == EPI_RESID) {
;               if (n == 0) {
;                 const int f8 = u.pn * 256 + bj * 128 + wc * 32 + 8 * fq;
;                 const f32x4 v1 = acc[ai][bj][m][1];
;                 f32x4 r0, r1;
;                 if (rsrc) {
;                   r0 = *(const f32x4*)(rsrc + (size_t)token * 1024 + f8); r1 = *(const f32x4*)(rsrc + (size_t)token * 1024 + f8 + 4);
;                 } else {
;                   const u32x4 xu = *(const u32x4*)(xr + (size_t)token * 1024 + f8);
;                   r0 = (f32x4){bf2f(xu.x & 0xffffu), bf2f(xu.x >> 16), bf2f(xu.y & 0xffffu), bf2f(xu.y >> 16)};
	s_waitcnt lgkmcnt(0)
	s_waitcnt lgkmcnt(0)
	v_mfma_f32_16x16x32_bf16 v[116:119], v[208:211], v[160:163], v[116:119]
	v_mfma_f32_16x16x32_bf16 v[112:115], v[216:219], v[160:163], v[112:115]
	v_mfma_f32_16x16x32_bf16 v[100:103], v[208:211], v[168:171], v[100:103]
	v_mfma_f32_16x16x32_bf16 v[96:99], v[216:219], v[168:171], v[96:99]
	v_mfma_f32_16x16x32_bf16 v[84:87], v[208:211], v[176:179], v[84:87]
	v_mfma_f32_16x16x32_bf16 v[80:83], v[216:219], v[176:179], v[80:83]
	v_mfma_f32_16x16x32_bf16 v[68:71], v[208:211], v[200:203], v[68:71]
	v_mfma_f32_16x16x32_bf16 v[64:67], v[216:219], v[200:203], v[64:67]
	v_mfma_f32_16x16x32_bf16 v[116:119], v[212:215], v[164:167], v[116:119]
	v_mfma_f32_16x16x32_bf16 v[112:115], v[220:223], v[164:167], v[112:115]
	v_mfma_f32_16x16x32_bf16 v[100:103], v[212:215], v[172:175], v[100:103]
	v_mfma_f32_16x16x32_bf16 v[96:99], v[220:223], v[172:175], v[96:99]
	v_mfma_f32_16x16x32_bf16 v[84:87], v[212:215], v[196:199], v[84:87]
	v_mfma_f32_16x16x32_bf16 v[80:83], v[220:223], v[196:199], v[80:83]
	v_mfma_f32_16x16x32_bf16 v[68:71], v[212:215], v[204:207], v[68:71]
	v_mfma_f32_16x16x32_bf16 v[64:67], v[220:223], v[204:207], v[64:67]
	s_mov_b32 m0, s49
	v_lshl_add_u64 v[156:157], v[224:225], 0, s[0:1]
	s_barrier
	ds_read_b128 v[160:163], v159 offset:49152
	ds_read_b128 v[164:167], v159 offset:50176
	ds_read_b128 v[168:171], v159 offset:51200
	ds_read_b128 v[172:175], v159 offset:52224
	ds_read_b128 v[176:179], v159 offset:53248
	ds_read_b128 v[196:199], v159 offset:54272
	ds_read_b128 v[200:203], v159 offset:55296
	ds_read_b128 v[204:207], v159 offset:56320
	global_load_lds_dwordx4 v[156:157], off
	v_lshl_add_u64 v[156:157], v[226:227], 0, s[0:1]
	s_mov_b32 m0, s50
	s_nop 0
	global_load_lds_dwordx4 v[156:157], off
	s_barrier
	s_waitcnt lgkmcnt(0)
	s_waitcnt lgkmcnt(0)
	v_mfma_f32_16x16x32_bf16 v[60:63], v[128:131], v[160:163], v[60:63]
	v_mfma_f32_16x16x32_bf16 v[56:59], v[148:151], v[160:163], v[56:59]
	v_mfma_f32_16x16x32_bf16 v[44:47], v[128:131], v[168:171], v[44:47]
	v_mfma_f32_16x16x32_bf16 v[40:43], v[148:151], v[168:171], v[40:43]
	v_mfma_f32_16x16x32_bf16 v[28:31], v[128:131], v[176:179], v[28:31]
	v_mfma_f32_16x16x32_bf16 v[24:27], v[148:151], v[176:179], v[24:27]
	v_mfma_f32_16x16x32_bf16 v[12:15], v[128:131], v[200:203], v[12:15]
	v_mfma_f32_16x16x32_bf16 v[8:11], v[148:151], v[200:203], v[8:11]
	v_mfma_f32_16x16x32_bf16 v[60:63], v[132:135], v[164:167], v[60:63]
	v_mfma_f32_16x16x32_bf16 v[56:59], v[152:155], v[164:167], v[56:59]
	v_mfma_f32_16x16x32_bf16 v[44:47], v[132:135], v[172:175], v[44:47]
	v_mfma_f32_16x16x32_bf16 v[40:43], v[152:155], v[172:175], v[40:43]
	v_mfma_f32_16x16x32_bf16 v[28:31], v[132:135], v[196:199], v[28:31]
	v_mfma_f32_16x16x32_bf16 v[24:27], v[152:155], v[196:199], v[24:27]
	v_mfma_f32_16x16x32_bf16 v[12:15], v[132:135], v[204:207], v[12:15]
	v_mfma_f32_16x16x32_bf16 v[8:11], v[152:155], v[204:207], v[8:11]
	s_barrier
	s_add_u32 s4, s4, 0x40080
	s_addc_u32 s5, s5, 0
	s_add_i32 s28, s28, s40
	v_lshl_add_u64 v[128:129], s[4:5], 0, v[144:145]
	s_mov_b32 m0, s28
	s_nop 0
	global_load_lds_dwordx4 v[128:129], off
	v_lshl_add_u64 v[128:129], s[4:5], 0, v[136:137]
	s_add_i32 m0, s28, 0x2000
	s_nop 0
	global_load_lds_dwordx4 v[128:129], off
	s_waitcnt vmcnt(6)
	s_barrier
	v_mfma_f32_16x16x32_bf16 v[52:55], v[208:211], v[160:163], v[52:55]
	v_mfma_f32_16x16x32_bf16 v[48:51], v[216:219], v[160:163], v[48:51]
	v_mfma_f32_16x16x32_bf16 v[36:39], v[208:211], v[168:171], v[36:39]
	v_mfma_f32_16x16x32_bf16 v[32:35], v[216:219], v[168:171], v[32:35]
	v_mfma_f32_16x16x32_bf16 v[20:23], v[208:211], v[176:179], v[20:23]
	v_mfma_f32_16x16x32_bf16 v[16:19], v[216:219], v[176:179], v[16:19]
	v_mfma_f32_16x16x32_bf16 v[4:7], v[208:211], v[200:203], v[4:7]
	v_mfma_f32_16x16x32_bf16 v[0:3], v[216:219], v[200:203], v[0:3]
	v_mfma_f32_16x16x32_bf16 v[52:55], v[212:215], v[164:167], v[52:55]
	v_mfma_f32_16x16x32_bf16 v[48:51], v[220:223], v[164:167], v[48:51]
	v_mfma_f32_16x16x32_bf16 v[36:39], v[212:215], v[172:175], v[36:39]
	v_mfma_f32_16x16x32_bf16 v[32:35], v[220:223], v[172:175], v[32:35]
	v_mfma_f32_16x16x32_bf16 v[20:23], v[212:215], v[196:199], v[20:23]
	v_mfma_f32_16x16x32_bf16 v[16:19], v[220:223], v[196:199], v[16:19]
	v_mfma_f32_16x16x32_bf16 v[4:7], v[212:215], v[204:207], v[4:7]
	v_mfma_f32_16x16x32_bf16 v[0:3], v[220:223], v[204:207], v[0:3]
	s_add_i32 s54, s54, 2
	s_add_u32 s2, s2, 0x100
	s_addc_u32 s3, s3, 0
	s_add_u32 s52, s52, 0x100
	s_addc_u32 s53, s53, 0
	s_cmp_gt_u32 s54, 13
	s_barrier
	s_cbranch_scc0 .LBB0_1644
	s_lshl_b32 s2, s34, 8
	v_mov_b32_e32 v161, v182
	s_add_i32 s2, s2, s47
	v_cndmask_b32_e64 v130, 0, 1, s[14:15]
	v_and_or_b32 v150, v161, 15, s2
	s_lshl_b32 s2, s24, 8
	v_bfe_u32 v160, v161, 4, 2
	s_or_b32 s2, s2, s48
	v_ashrrev_i32_e32 v151, 31, v150
	v_lshl_or_b32 v148, v160, 3, s2
	v_lshlrev_b64 v[128:129], 12, v[150:151]
	v_ashrrev_i32_e32 v149, 31, v148
	v_lshl_add_u64 v[128:129], s[6:7], 0, v[128:129]
	v_cmp_ne_u32_e64 s[2:3], 1, v130
	s_andn2_b64 vcc, exec, s[14:15]
	v_lshl_add_u64 v[154:155], v[148:149], 2, v[128:129]
	s_cbranch_vccnz .LBB0_1647
	global_load_dwordx4 v[132:135], v[154:155], off offset:16
	global_load_dwordx4 v[128:131], v[154:155], off
	s_mov_b64 s[4:5], 0
	s_branch .LBB0_1648

; #define PG8_STAGE(bufoff, gbase, voff) do { _Pragma("unroll") for (int _i = 0; _i < 2; ++_i) \
;     __builtin_amdgcn_global_load_lds((const unsigned*)((const char*)(gbase) + (voff)[_i]), (LAS unsigned*)(lds + (bufoff) + ldsw + _i * 8192), 16, 0, 0); } while (0)
; #define PG8_LDA(dst, b, h) do { _Pragma("unroll") for (int m = 0; m < 4; ++m) _Pragma("unroll") for (int k = 0; k < 2; ++k) dst[m][k] = *(const LAS bf16x8*)(lds + PG8_SA(b, h) + aoff + m * 2048 + k * 1024); } while (0)
; #define PG8_LDB(dst, b, h) do { _Pragma("unroll") for (int n = 0; n < 2; ++n) _Pragma("unroll") for (int k = 0; k < 2; ++k) dst[n][k] = *(const LAS bf16x8*)(lds + PG8_SB(b, h) + boff + n * 2048 + k * 1024); } while (0)
; #define PG8_WAIT_V(n) asm volatile("s_waitcnt vmcnt(" #n ")" ::: "memory")
; template <class Epi, class Sched>
; DI void gemm_phase(LAS unsigned char* lds, const Gemm g, const Sched& S, const Epi& E) {
;     ...
;     for (int t = 0; t < nt; t += 2) {
;       const bool last = (t == nt - 2);
;       const char* a1 = cA + (size_t)(t + 1) * kstep;
;       const char* a2 = last ? nA : cA + (size_t)(t + 2) * kstep; const char* b2 = last ? nB : cB + (size_t)(t + 2) * kstep;
;       const char* a3 = a2 + kstep; const char* b3 = b2 + kstep;
;       PG8_LDB(B0, 0, 0); PG8_SCHED; PG8_LDA(At, 0, 0); PG8_STAGE(PG8_SA(1, 1), a1 + hstep, voffA);
;       PG8_WAIT_L(8); PG8_BAR; PG8_WAIT_L(0); PG8_MMA(0, 0, At, B0); PG8_BAR; PG8_SCHED;
;       PG8_LDB(B1, 0, 1); PG8_STAGE(PG8_SB(0, 0), b2, voffB);
;       PG8_BAR; PG8_WAIT_L(0); PG8_MMA(0, 1, At, B1); PG8_BAR;
;       PG8_LDA(At, 0, 1); PG8_STAGE(PG8_SA(0, 0), a2, voffA);
;       PG8_BAR; PG8_WAIT_L(0); PG8_MMA(1, 0, At, B0); PG8_BAR; PG8_SCHED;
;       PG8_STAGE(PG8_SB(0, 1), b2 + hstep, voffB);
;       PG8_WAIT_V(6); PG8_BAR; PG8_MMA(1, 1, At, B1); PG8_BAR;
;       PG8_LDB(B0, 1, 0); PG8_SCHED; PG8_LDA(At, 1, 0); PG8_STAGE(PG8_SA(0, 1), a2 + hstep, voffA);
;       PG8_WAIT_L(8); PG8_BAR; PG8_WAIT_L(0); PG8_MMA(0, 0, At, B0); PG8_BAR; PG8_SCHED;
;       PG8_LDB(B1, 1, 1); PG8_STAGE(PG8_SB(1, 0), b3, voffB);
;       PG8_BAR; PG8_WAIT_L(0); PG8_MMA(0, 1, At, B1); PG8_BAR;
;       PG8_LDA(At, 1, 1); PG8_STAGE(PG8_SA(1, 0), a3, voffA);
;       PG8_BAR; PG8_WAIT_L(0); PG8_MMA(1, 0, At, B0); PG8_BAR; PG8_SCHED;
;       PG8_STAGE(PG8_SB(1, 1), b3 + hstep, voffB);
;       PG8_WAIT_V(6); PG8_BAR; PG8_MMA(1, 1, At, B1); PG8_BAR;
;     }
.LBB0_1829:
	s_add_u32 s16, s14, 0xfffc0080
	s_addc_u32 s17, s15, -1
	s_add_i32 s51, 0, 0x10000
	v_add_u32_e32 v140, s51, v142
	ds_read_b128 v[146:149], v140
	ds_read_b128 v[150:153], v140 offset:1024
	ds_read_b128 v[154:157], v140 offset:2048
	ds_read_b128 v[158:161], v140 offset:3072
	s_cmp_eq_u32 s50, 12
	s_cselect_b32 s19, s7, s17
	s_cselect_b32 s18, s46, s16
	s_cselect_b32 s17, s5, s49
	s_cselect_b32 s16, s47, s48
	v_lshl_add_u64 v[140:141], s[14:15], 0, v[136:137]
	s_add_i32 m0, s29, 0xc000
	ds_read_b128 v[162:165], v143
	ds_read_b128 v[166:169], v143 offset:1024
	ds_read_b128 v[170:173], v143 offset:2048
	ds_read_b128 v[174:177], v143 offset:3072
	ds_read_b128 v[178:181], v143 offset:4096
	ds_read_b128 v[196:199], v143 offset:5120
	ds_read_b128 v[200:203], v143 offset:6144
	ds_read_b128 v[204:207], v143 offset:7168
	global_load_lds_dwordx4 v[140:141], off
	v_lshl_add_u64 v[140:141], s[14:15], 0, v[138:139]
	s_add_i32 m0, s29, 0xe000
	s_nop 0
	global_load_lds_dwordx4 v[140:141], off
	s_waitcnt lgkmcnt(8)
	s_barrier
	s_waitcnt lgkmcnt(0)
	s_waitcnt lgkmcnt(0)
	v_mfma_f32_16x16x32_bf16 v[124:127], v[146:149], v[162:165], v[124:127]
	v_mfma_f32_16x16x32_bf16 v[120:123], v[154:157], v[162:165], v[120:123]
	v_mfma_f32_16x16x32_bf16 v[112:115], v[146:149], v[170:173], v[112:115]
	v_mfma_f32_16x16x32_bf16 v[104:107], v[154:157], v[170:173], v[104:107]
	v_mfma_f32_16x16x32_bf16 v[92:95], v[146:149], v[178:181], v[92:95]
	v_mfma_f32_16x16x32_bf16 v[88:91], v[154:157], v[178:181], v[88:91]
	v_mfma_f32_16x16x32_bf16 v[80:83], v[146:149], v[200:203], v[80:83]
	v_mfma_f32_16x16x32_bf16 v[72:75], v[154:157], v[200:203], v[72:75]
	v_mfma_f32_16x16x32_bf16 v[124:127], v[150:153], v[166:169], v[124:127]
	v_mfma_f32_16x16x32_bf16 v[120:123], v[158:161], v[166:169], v[120:123]
	v_mfma_f32_16x16x32_bf16 v[112:115], v[150:153], v[174:177], v[112:115]
	v_mfma_f32_16x16x32_bf16 v[104:107], v[158:161], v[174:177], v[104:107]
	v_mfma_f32_16x16x32_bf16 v[92:95], v[150:153], v[196:199], v[92:95]
	v_mfma_f32_16x16x32_bf16 v[88:91], v[158:161], v[196:199], v[88:91]
	v_mfma_f32_16x16x32_bf16 v[80:83], v[150:153], v[204:207], v[80:83]
	v_mfma_f32_16x16x32_bf16 v[72:75], v[158:161], v[204:207], v[72:75]
	s_barrier
	s_add_i32 s54, 0, 0x14000
	v_add_u32_e32 v140, s54, v142
	s_add_i32 s51, s51, s20
	ds_read_b128 v[208:211], v140
	ds_read_b128 v[212:215], v140 offset:1024
	ds_read_b128 v[216:219], v140 offset:2048
	ds_read_b128 v[220:223], v140 offset:3072
	v_lshl_add_u64 v[140:141], s[16:17], 0, v[132:133]
	s_mov_b32 m0, s51
	v_lshl_add_u64 v[224:225], s[16:17], 0, v[128:129]
	global_load_lds_dwordx4 v[140:141], off
	s_add_i32 m0, s51, 0x2000
	s_nop 0
	global_load_lds_dwordx4 v[224:225], off
	s_barrier
	s_waitcnt lgkmcnt(0)
	s_waitcnt lgkmcnt(0)
	v_mfma_f32_16x16x32_bf16 v[116:119], v[208:211], v[162:165], v[116:119]
	v_mfma_f32_16x16x32_bf16 v[108:111], v[216:219], v[162:165], v[108:111]
	v_mfma_f32_16x16x32_bf16 v[100:103], v[208:211], v[170:173], v[100:103]
	v_mfma_f32_16x16x32_bf16 v[96:99], v[216:219], v[170:173], v[96:99]
	v_mfma_f32_16x16x32_bf16 v[84:87], v[208:211], v[178:181], v[84:87]
	v_mfma_f32_16x16x32_bf16 v[76:79], v[216:219], v[178:181], v[76:79]
	v_mfma_f32_16x16x32_bf16 v[68:71], v[208:211], v[200:203], v[68:71]
	v_mfma_f32_16x16x32_bf16 v[64:67], v[216:219], v[200:203], v[64:67]
	v_mfma_f32_16x16x32_bf16 v[116:119], v[212:215], v[166:169], v[116:119]
	v_mfma_f32_16x16x32_bf16 v[108:111], v[220:223], v[166:169], v[108:111]
	v_mfma_f32_16x16x32_bf16 v[100:103], v[212:215], v[174:177], v[100:103]
	v_mfma_f32_16x16x32_bf16 v[96:99], v[220:223], v[174:177], v[96:99]
	v_mfma_f32_16x16x32_bf16 v[84:87], v[212:215], v[196:199], v[84:87]
	v_mfma_f32_16x16x32_bf16 v[76:79], v[220:223], v[196:199], v[76:79]
	v_mfma_f32_16x16x32_bf16 v[68:71], v[212:215], v[204:207], v[68:71]
	v_mfma_f32_16x16x32_bf16 v[64:67], v[220:223], v[204:207], v[64:67]
	s_mov_b32 m0, s29
	v_lshl_add_u64 v[226:227], s[18:19], 0, v[134:135]
	s_barrier
	ds_read_b128 v[162:165], v143 offset:16384
	ds_read_b128 v[166:169], v143 offset:17408
	ds_read_b128 v[170:173], v143 offset:18432
	ds_read_b128 v[174:177], v143 offset:19456
	ds_read_b128 v[178:181], v143 offset:20480
	ds_read_b128 v[196:199], v143 offset:21504
	ds_read_b128 v[200:203], v143 offset:22528
	ds_read_b128 v[204:207], v143 offset:23552
	global_load_lds_dwordx4 v[226:227], off
	v_lshl_add_u64 v[228:229], s[18:19], 0, v[130:131]
	s_mov_b32 m0, s34
	s_nop 0
	global_load_lds_dwordx4 v[228:229], off
	s_barrier
	s_waitcnt lgkmcnt(0)
	s_waitcnt lgkmcnt(0)
	v_mfma_f32_16x16x32_bf16 v[60:63], v[146:149], v[162:165], v[60:63]
	v_mfma_f32_16x16x32_bf16 v[56:59], v[154:157], v[162:165], v[56:59]
	v_mfma_f32_16x16x32_bf16 v[48:51], v[146:149], v[170:173], v[48:51]
	v_mfma_f32_16x16x32_bf16 v[40:43], v[154:157], v[170:173], v[40:43]
	v_mfma_f32_16x16x32_bf16 v[28:31], v[146:149], v[178:181], v[28:31]
	v_mfma_f32_16x16x32_bf16 v[24:27], v[154:157], v[178:181], v[24:27]
	v_mfma_f32_16x16x32_bf16 v[16:19], v[146:149], v[200:203], v[16:19]
	v_mfma_f32_16x16x32_bf16 v[8:11], v[154:157], v[200:203], v[8:11]
	v_mfma_f32_16x16x32_bf16 v[60:63], v[150:153], v[166:169], v[60:63]
	v_mfma_f32_16x16x32_bf16 v[56:59], v[158:161], v[166:169], v[56:59]
	v_mfma_f32_16x16x32_bf16 v[48:51], v[150:153], v[174:177], v[48:51]
	v_mfma_f32_16x16x32_bf16 v[40:43], v[158:161], v[174:177], v[40:43]
	v_mfma_f32_16x16x32_bf16 v[28:31], v[150:153], v[196:199], v[28:31]
	v_mfma_f32_16x16x32_bf16 v[24:27], v[158:161], v[196:199], v[24:27]
	v_mfma_f32_16x16x32_bf16 v[16:19], v[150:153], v[204:207], v[16:19]
	v_mfma_f32_16x16x32_bf16 v[8:11], v[158:161], v[204:207], v[8:11]
	s_barrier
; #define PG8_STAGE(bufoff, gbase, voff) do { _Pragma("unroll") for (int _i = 0; _i < 2; ++_i) \
;     __builtin_amdgcn_global_load_lds((const unsigned*)((const char*)(gbase) + (voff)[_i]), (LAS unsigned*)(lds + (bufoff) + ldsw + _i * 8192), 16, 0, 0); } while (0)
; #define PG8_LDA(dst, b, h) do { _Pragma("unroll") for (int m = 0; m < 4; ++m) _Pragma("unroll") for (int k = 0; k < 2; ++k) dst[m][k] = *(const LAS bf16x8*)(lds + PG8_SA(b, h) + aoff + m * 2048 + k * 1024); } while (0)
; #define PG8_LDB(dst, b, h) do { _Pragma("unroll") for (int n = 0; n < 2; ++n) _Pragma("unroll") for (int k = 0; k < 2; ++k) dst[n][k] = *(const LAS bf16x8*)(lds + PG8_SB(b, h) + boff + n * 2048 + k * 1024); } while (0)
; #define PG8_WAIT_V(n) asm volatile("s_waitcnt vmcnt(" #n ")" ::: "memory")
; template <class Epi, class Sched>
; DI void gemm_phase(LAS unsigned char* lds, const Gemm g, const Sched& S, const Epi& E) {
;     ...
;     for (int t = 0; t < nt; t += 2) {
;       const bool last = (t == nt - 2);
;       const char* a1 = cA + (size_t)(t + 1) * kstep;
;       const char* a2 = last ? nA : cA + (size_t)(t + 2) * kstep; const char* b2 = last ? nB : cB + (size_t)(t + 2) * kstep;
;       const char* a3 = a2 + kstep; const char* b3 = b2 + kstep;
;       PG8_LDB(B0, 0, 0); PG8_SCHED; PG8_LDA(At, 0, 0); PG8_STAGE(PG8_SA(1, 1), a1 + hstep, voffA);
;       PG8_WAIT_L(8); PG8_BAR; PG8_WAIT_L(0); PG8_MMA(0, 0, At, B0); PG8_BAR; PG8_SCHED;
;       PG8_LDB(B1, 0, 1); PG8_STAGE(PG8_SB(0, 0), b2, voffB);
;       PG8_BAR; PG8_WAIT_L(0); PG8_MMA(0, 1, At, B1); PG8_BAR;
;       PG8_LDA(At, 0, 1); PG8_STAGE(PG8_SA(0, 0), a2, voffA);
;       PG8_BAR; PG8_WAIT_L(0); PG8_MMA(1, 0, At, B0); PG8_BAR; PG8_SCHED;
;       PG8_STAGE(PG8_SB(0, 1), b2 + hstep, voffB);
;       PG8_WAIT_V(6); PG8_BAR; PG8_MMA(1, 1, At, B1); PG8_BAR;
;       PG8_LDB(B0, 1, 0); PG8_SCHED; PG8_LDA(At, 1, 0); PG8_STAGE(PG8_SA(0, 1), a2 + hstep, voffA);
;       PG8_WAIT_L(8); PG8_BAR; PG8_WAIT_L(0); PG8_MMA(0, 0, At, B0); PG8_BAR; PG8_SCHED;
;       PG8_LDB(B1, 1, 1); PG8_STAGE(PG8_SB(1, 0), b3, voffB);
;       PG8_BAR; PG8_WAIT_L(0); PG8_MMA(0, 1, At, B1); PG8_BAR;
;       PG8_LDA(At, 1, 1); PG8_STAGE(PG8_SA(1, 0), a3, voffA);
;       PG8_BAR; PG8_WAIT_L(0); PG8_MMA(1, 0, At, B0); PG8_BAR; PG8_SCHED;
;       PG8_STAGE(PG8_SB(1, 1), b3 + hstep, voffB);
;       PG8_WAIT_V(6); PG8_BAR; PG8_MMA(1, 1, At, B1); PG8_BAR;
;     }
	s_add_u32 s52, s16, 0x40000
	s_addc_u32 s53, s17, 0
	s_add_i32 s51, s54, s20
	v_lshl_add_u64 v[146:147], s[52:53], 0, v[132:133]
	s_mov_b32 m0, s51
	s_nop 0
	global_load_lds_dwordx4 v[146:147], off
	v_lshl_add_u64 v[146:147], s[52:53], 0, v[128:129]
	s_add_i32 m0, s51, 0x2000
	s_nop 0
	global_load_lds_dwordx4 v[146:147], off
	s_waitcnt vmcnt(6)
	s_barrier
	v_mfma_f32_16x16x32_bf16 v[52:55], v[208:211], v[162:165], v[52:55]
	v_mfma_f32_16x16x32_bf16 v[44:47], v[216:219], v[162:165], v[44:47]
	v_mfma_f32_16x16x32_bf16 v[36:39], v[208:211], v[170:173], v[36:39]
	v_mfma_f32_16x16x32_bf16 v[32:35], v[216:219], v[170:173], v[32:35]
	v_mfma_f32_16x16x32_bf16 v[20:23], v[208:211], v[178:181], v[20:23]
	v_mfma_f32_16x16x32_bf16 v[12:15], v[216:219], v[178:181], v[12:15]
	v_mfma_f32_16x16x32_bf16 v[4:7], v[208:211], v[200:203], v[4:7]
	v_mfma_f32_16x16x32_bf16 v[0:3], v[216:219], v[200:203], v[0:3]
	v_mfma_f32_16x16x32_bf16 v[52:55], v[212:215], v[166:169], v[52:55]
	v_mfma_f32_16x16x32_bf16 v[44:47], v[220:223], v[166:169], v[44:47]
	v_mfma_f32_16x16x32_bf16 v[36:39], v[212:215], v[174:177], v[36:39]
	v_mfma_f32_16x16x32_bf16 v[32:35], v[220:223], v[174:177], v[32:35]
	v_mfma_f32_16x16x32_bf16 v[20:23], v[212:215], v[196:199], v[20:23]
	v_mfma_f32_16x16x32_bf16 v[12:15], v[220:223], v[196:199], v[12:15]
	v_mfma_f32_16x16x32_bf16 v[4:7], v[212:215], v[204:207], v[4:7]
	v_mfma_f32_16x16x32_bf16 v[0:3], v[220:223], v[204:207], v[0:3]
	s_add_i32 s51, 0, 0x18000
	v_add_u32_e32 v144, s51, v142
	s_barrier
	ds_read_b128 v[146:149], v144
	ds_read_b128 v[150:153], v144 offset:1024
	ds_read_b128 v[154:157], v144 offset:2048
	ds_read_b128 v[158:161], v144 offset:3072
	s_add_u32 s18, s18, 0x40000
	s_addc_u32 s19, s19, 0
	s_mov_b32 m0, s35
	v_lshl_add_u64 v[208:209], s[18:19], 0, v[134:135]
	ds_read_b128 v[162:165], v143 offset:32768
	ds_read_b128 v[166:169], v143 offset:33792
	ds_read_b128 v[170:173], v143 offset:34816
	ds_read_b128 v[174:177], v143 offset:35840
	ds_read_b128 v[178:181], v143 offset:36864
	ds_read_b128 v[196:199], v143 offset:37888
	ds_read_b128 v[200:203], v143 offset:38912
	ds_read_b128 v[204:207], v143 offset:39936
	global_load_lds_dwordx4 v[208:209], off
	v_lshl_add_u64 v[208:209], s[18:19], 0, v[130:131]
	s_mov_b32 m0, s38
	s_nop 0
	global_load_lds_dwordx4 v[208:209], off
	s_waitcnt lgkmcnt(8)
	s_barrier
	s_waitcnt lgkmcnt(0)
	s_waitcnt lgkmcnt(0)
	v_mfma_f32_16x16x32_bf16 v[124:127], v[146:149], v[162:165], v[124:127]
	v_mfma_f32_16x16x32_bf16 v[120:123], v[154:157], v[162:165], v[120:123]
	v_mfma_f32_16x16x32_bf16 v[112:115], v[146:149], v[170:173], v[112:115]
	v_mfma_f32_16x16x32_bf16 v[104:107], v[154:157], v[170:173], v[104:107]
	v_mfma_f32_16x16x32_bf16 v[92:95], v[146:149], v[178:181], v[92:95]
	v_mfma_f32_16x16x32_bf16 v[88:91], v[154:157], v[178:181], v[88:91]
	v_mfma_f32_16x16x32_bf16 v[80:83], v[146:149], v[200:203], v[80:83]
	v_mfma_f32_16x16x32_bf16 v[72:75], v[154:157], v[200:203], v[72:75]
	v_mfma_f32_16x16x32_bf16 v[124:127], v[150:153], v[166:169], v[124:127]
	v_mfma_f32_16x16x32_bf16 v[120:123], v[158:161], v[166:169], v[120:123]
	v_mfma_f32_16x16x32_bf16 v[112:115], v[150:153], v[174:177], v[112:115]
	v_mfma_f32_16x16x32_bf16 v[104:107], v[158:161], v[174:177], v[104:107]
	v_mfma_f32_16x16x32_bf16 v[92:95], v[150:153], v[196:199], v[92:95]
	v_mfma_f32_16x16x32_bf16 v[88:91], v[158:161], v[196:199], v[88:91]
	v_mfma_f32_16x16x32_bf16 v[80:83], v[150:153], v[204:207], v[80:83]
	v_mfma_f32_16x16x32_bf16 v[72:75], v[158:161], v[204:207], v[72:75]
	s_barrier
	s_add_i32 s18, 0, 0x1c000
	s_add_i32 s19, s51, s20
	v_add_u32_e32 v144, s18, v142
	v_lshl_add_u64 v[140:141], v[140:141], 0, s[0:1]
	s_mov_b32 m0, s19
	ds_read_b128 v[208:211], v144
	ds_read_b128 v[212:215], v144 offset:1024
	ds_read_b128 v[216:219], v144 offset:2048
	ds_read_b128 v[220:223], v144 offset:3072
	global_load_lds_dwordx4 v[140:141], off
	v_lshl_add_u64 v[140:141], v[224:225], 0, s[0:1]
	s_add_i32 m0, s19, 0x2000
	s_nop 0
	global_load_lds_dwordx4 v[140:141], off
	s_barrier
	s_waitcnt lgkmcnt(0)
	s_waitcnt lgkmcnt(0)
	v_mfma_f32_16x16x32_bf16 v[116:119], v[208:211], v[162:165], v[116:119]
	v_mfma_f32_16x16x32_bf16 v[108:111], v[216:219], v[162:165], v[108:111]
	v_mfma_f32_16x16x32_bf16 v[100:103], v[208:211], v[170:173], v[100:103]
	v_mfma_f32_16x16x32_bf16 v[96:99], v[216:219], v[170:173], v[96:99]
	v_mfma_f32_16x16x32_bf16 v[84:87], v[208:211], v[178:181], v[84:87]
	v_mfma_f32_16x16x32_bf16 v[76:79], v[216:219], v[178:181], v[76:79]
	v_mfma_f32_16x16x32_bf16 v[68:71], v[208:211], v[200:203], v[68:71]
	v_mfma_f32_16x16x32_bf16 v[64:67], v[216:219], v[200:203], v[64:67]
	v_mfma_f32_16x16x32_bf16 v[116:119], v[212:215], v[166:169], v[116:119]
	v_mfma_f32_16x16x32_bf16 v[108:111], v[220:223], v[166:169], v[108:111]
	v_mfma_f32_16x16x32_bf16 v[100:103], v[212:215], v[174:177], v[100:103]
	v_mfma_f32_16x16x32_bf16 v[96:99], v[220:223], v[174:177], v[96:99]
	v_mfma_f32_16x16x32_bf16 v[84:87], v[212:215], v[196:199], v[84:87]
	v_mfma_f32_16x16x32_bf16 v[76:79], v[220:223], v[196:199], v[76:79]
	v_mfma_f32_16x16x32_bf16 v[68:71], v[212:215], v[204:207], v[68:71]
	v_mfma_f32_16x16x32_bf16 v[64:67], v[220:223], v[204:207], v[64:67]
	s_mov_b32 m0, s40
	v_lshl_add_u64 v[140:141], v[226:227], 0, s[0:1]
	s_barrier
	ds_read_b128 v[162:165], v143 offset:49152
	ds_read_b128 v[166:169], v143 offset:50176
	ds_read_b128 v[170:173], v143 offset:51200
	ds_read_b128 v[174:177], v143 offset:52224
	ds_read_b128 v[178:181], v143 offset:53248
	ds_read_b128 v[196:199], v143 offset:54272
	ds_read_b128 v[200:203], v143 offset:55296
	ds_read_b128 v[204:207], v143 offset:56320
	global_load_lds_dwordx4 v[140:141], off
	v_lshl_add_u64 v[140:141], v[228:229], 0, s[0:1]
	s_mov_b32 m0, s41
	s_nop 0
	global_load_lds_dwordx4 v[140:141], off
	s_barrier
; #define PG8_BAR __builtin_amdgcn_s_barrier()
; template <class Epi, class Sched>
; DI void gemm_phase(LAS unsigned char* lds, const Gemm g, const Sched& S, const Epi& E) {
;     ...
;     for (int t = 0; t < nt; t += 2) {
;       const bool last = (t == nt - 2);
;       const char* a1 = cA + (size_t)(t + 1) * kstep;
;       const char* a2 = last ? nA : cA + (size_t)(t + 2) * kstep; const char* b2 = last ? nB : cB + (size_t)(t + 2) * kstep;
;       const char* a3 = a2 + kstep; const char* b3 = b2 + kstep;
;       PG8_LDB(B0, 0, 0); PG8_SCHED; PG8_LDA(At, 0, 0); PG8_STAGE(PG8_SA(1, 1), a1 + hstep, voffA);
;       PG8_WAIT_L(8); PG8_BAR; PG8_WAIT_L(0); PG8_MMA(0, 0, At, B0); PG8_BAR; PG8_SCHED;
;       PG8_LDB(B1, 0, 1); PG8_STAGE(PG8_SB(0, 0), b2, voffB);
;       PG8_BAR; PG8_WAIT_L(0); PG8_MMA(0, 1, At, B1); PG8_BAR;
;       PG8_LDA(At, 0, 1); PG8_STAGE(PG8_SA(0, 0), a2, voffA);
;       PG8_BAR; PG8_WAIT_L(0); PG8_MMA(1, 0, At, B0); PG8_BAR; PG8_SCHED;
;       PG8_STAGE(PG8_SB(0, 1), b2 + hstep, voffB);
;       PG8_WAIT_V(6); PG8_BAR; PG8_MMA(1, 1, At, B1); PG8_BAR;
;       PG8_LDB(B0, 1, 0); PG8_SCHED; PG8_LDA(At, 1, 0); PG8_STAGE(PG8_SA(0, 1), a2 + hstep, voffA);
;       PG8_WAIT_L(8); PG8_BAR; PG8_WAIT_L(0); PG8_MMA(0, 0, At, B0); PG8_BAR; PG8_SCHED;
;       PG8_LDB(B1, 1, 1); PG8_STAGE(PG8_SB(1, 0), b3, voffB);
;       PG8_BAR; PG8_WAIT_L(0); PG8_MMA(0, 1, At, B1); PG8_BAR;
;       PG8_LDA(At, 1, 1); PG8_STAGE(PG8_SA(1, 0), a3, voffA);
;       PG8_BAR; PG8_WAIT_L(0); PG8_MMA(1, 0, At, B0); PG8_BAR; PG8_SCHED;
;       PG8_STAGE(PG8_SB(1, 1), b3 + hstep, voffB);
;       PG8_WAIT_V(6); PG8_BAR; PG8_MMA(1, 1, At, B1); PG8_BAR;
;     }
;   DI void operator()(const f32x4 (&acc)[2][2][4][2], const pg8::Unit& u, int wr, int wc, int fr_, int fq_) const {
;     ...
;             } else {
;               if (n == 0) {
;                 const f32x4 v1 = acc[ai][bj][m][1];
;                 u32x4 o4;
;                 { const float t0 = fmaxf(v[0], 0.f) * rinv, t1 = fmaxf(v[1], 0.f) * rinv, t2 = fmaxf(v[2], 0.f) * rinv, t3 = fmaxf(v[3], 0.f) * rinv;
;                   o4.x = pack2(t0 * t0, t1 * t1); o4.y = pack2(t2 * t2, t3 * t3); }
;                 { const float t0 = fmaxf(v1[0], 0.f) * rinv, t1 = fmaxf(v1[1], 0.f) * rinv, t2 = fmaxf(v1[2], 0.f) * rinv, t3 = fmaxf(v1[3], 0.f) * rinv;
;                   o4.z = pack2(t0 * t0, t1 * t1); o4.w = pack2(t2 * t2, t3 * t3); }
	s_waitcnt lgkmcnt(0)
	s_waitcnt lgkmcnt(0)
	v_mfma_f32_16x16x32_bf16 v[60:63], v[146:149], v[162:165], v[60:63]
	v_mfma_f32_16x16x32_bf16 v[56:59], v[154:157], v[162:165], v[56:59]
	v_mfma_f32_16x16x32_bf16 v[48:51], v[146:149], v[170:173], v[48:51]
	v_mfma_f32_16x16x32_bf16 v[40:43], v[154:157], v[170:173], v[40:43]
	v_mfma_f32_16x16x32_bf16 v[28:31], v[146:149], v[178:181], v[28:31]
	v_mfma_f32_16x16x32_bf16 v[24:27], v[154:157], v[178:181], v[24:27]
	v_mfma_f32_16x16x32_bf16 v[16:19], v[146:149], v[200:203], v[16:19]
	v_mfma_f32_16x16x32_bf16 v[8:11], v[154:157], v[200:203], v[8:11]
	v_mfma_f32_16x16x32_bf16 v[60:63], v[150:153], v[166:169], v[60:63]
	v_mfma_f32_16x16x32_bf16 v[56:59], v[158:161], v[166:169], v[56:59]
	v_mfma_f32_16x16x32_bf16 v[48:51], v[150:153], v[174:177], v[48:51]
	v_mfma_f32_16x16x32_bf16 v[40:43], v[158:161], v[174:177], v[40:43]
	v_mfma_f32_16x16x32_bf16 v[28:31], v[150:153], v[196:199], v[28:31]
	v_mfma_f32_16x16x32_bf16 v[24:27], v[158:161], v[196:199], v[24:27]
	v_mfma_f32_16x16x32_bf16 v[16:19], v[150:153], v[204:207], v[16:19]
	v_mfma_f32_16x16x32_bf16 v[8:11], v[158:161], v[204:207], v[8:11]
	s_barrier
	s_add_u32 s16, s16, 0x40080
	s_addc_u32 s17, s17, 0
	s_add_i32 s18, s18, s20
	v_lshl_add_u64 v[140:141], s[16:17], 0, v[132:133]
	s_mov_b32 m0, s18
	s_nop 0
	global_load_lds_dwordx4 v[140:141], off
	v_lshl_add_u64 v[140:141], s[16:17], 0, v[128:129]
	s_add_i32 m0, s18, 0x2000
	s_nop 0
	global_load_lds_dwordx4 v[140:141], off
	s_waitcnt vmcnt(6)
	s_barrier
	v_mfma_f32_16x16x32_bf16 v[52:55], v[208:211], v[162:165], v[52:55]
	v_mfma_f32_16x16x32_bf16 v[44:47], v[216:219], v[162:165], v[44:47]
	v_mfma_f32_16x16x32_bf16 v[36:39], v[208:211], v[170:173], v[36:39]
	v_mfma_f32_16x16x32_bf16 v[32:35], v[216:219], v[170:173], v[32:35]
	v_mfma_f32_16x16x32_bf16 v[20:23], v[208:211], v[178:181], v[20:23]
	v_mfma_f32_16x16x32_bf16 v[12:15], v[216:219], v[178:181], v[12:15]
	v_mfma_f32_16x16x32_bf16 v[4:7], v[208:211], v[200:203], v[4:7]
	v_mfma_f32_16x16x32_bf16 v[0:3], v[216:219], v[200:203], v[0:3]
	v_mfma_f32_16x16x32_bf16 v[52:55], v[212:215], v[166:169], v[52:55]
	v_mfma_f32_16x16x32_bf16 v[44:47], v[220:223], v[166:169], v[44:47]
	v_mfma_f32_16x16x32_bf16 v[36:39], v[212:215], v[174:177], v[36:39]
	v_mfma_f32_16x16x32_bf16 v[32:35], v[220:223], v[174:177], v[32:35]
	v_mfma_f32_16x16x32_bf16 v[20:23], v[212:215], v[196:199], v[20:23]
	v_mfma_f32_16x16x32_bf16 v[12:15], v[220:223], v[196:199], v[12:15]
	v_mfma_f32_16x16x32_bf16 v[4:7], v[212:215], v[204:207], v[4:7]
	v_mfma_f32_16x16x32_bf16 v[0:3], v[220:223], v[204:207], v[0:3]
	s_add_i32 s50, s50, 2
	s_add_u32 s14, s14, 0x100
	s_addc_u32 s15, s15, 0
	s_add_u32 s48, s48, 0x100
	s_addc_u32 s49, s49, 0
	s_cmp_gt_u32 s50, 13
	s_barrier
	s_cbranch_scc0 .LBB0_1829
	v_mov_b32_e32 v144, v182
	s_lshl_b32 s5, s43, 10
	s_add_i32 s5, s5, 0
	v_and_or_b32 v141, v144, 15, s39
	v_lshl_add_u32 v140, s44, 8, v141
	v_lshl_add_u32 v141, v141, 2, s5
	v_add_u32_e32 v146, 0x20000, v141
	ds_read2_b32 v[148:149], v146 offset1:16
	v_max_f32_e32 v124, 0, v124
	v_max_f32_e32 v125, 0, v125
	v_max_f32_e32 v126, 0, v126
	v_max_f32_e32 v127, 0, v127
	v_max_f32_e32 v120, 0, v120
	v_max_f32_e32 v121, 0, v121
	s_waitcnt lgkmcnt(0)
	v_pk_mul_f32 v[124:125], v[124:125], v[148:149] op_sel_hi:[1,0]
	v_pk_mul_f32 v[126:127], v[126:127], v[148:149] op_sel_hi:[1,0]
	v_pk_mul_f32 v[120:121], v[120:121], v[148:149] op_sel_hi:[1,0]
	v_pk_mul_f32 v[124:125], v[124:125], v[124:125]
	v_pk_mul_f32 v[126:127], v[126:127], v[126:127]
	v_max_f32_e32 v122, 0, v122
	v_max_f32_e32 v123, 0, v123
	v_pk_mul_f32 v[120:121], v[120:121], v[120:121]
	v_max_f32_e32 v116, 0, v116
	v_max_f32_e32 v117, 0, v117
	v_max_f32_e32 v118, 0, v118
	v_max_f32_e32 v119, 0, v119
	v_max_f32_e32 v108, 0, v108
	v_max_f32_e32 v109, 0, v109
	s_lshl_b32 s14, s45, 8
	v_ashrrev_i32_e32 v141, 31, v140
	v_cvt_pk_bf16_f32 v124, v124, v125
	v_cvt_pk_bf16_f32 v125, v126, v127
	v_cvt_pk_bf16_f32 v126, v120, v121
	v_pk_mul_f32 v[120:121], v[122:123], v[148:149] op_sel_hi:[1,0]
	v_pk_mul_f32 v[116:117], v[116:117], v[148:149] op_sel_hi:[1,0]
	v_pk_mul_f32 v[118:119], v[118:119], v[148:149] op_sel_hi:[1,0]
	v_pk_mul_f32 v[108:109], v[108:109], v[148:149] op_sel_hi:[1,0]
	s_ashr_i32 s15, s14, 31
	v_lshlrev_b64 v[150:151], 13, v[140:141]
	v_pk_mul_f32 v[120:121], v[120:121], v[120:121]
	v_pk_mul_f32 v[116:117], v[116:117], v[116:117]
	v_pk_mul_f32 v[118:119], v[118:119], v[118:119]
	v_max_f32_e32 v110, 0, v110
	v_max_f32_e32 v111, 0, v111
	v_pk_mul_f32 v[108:109], v[108:109], v[108:109]
	v_cvt_pk_bf16_f32 v127, v120, v121
	v_lshl_add_u64 v[120:121], s[2:3], 0, v[150:151]
	s_lshl_b64 s[14:15], s[14:15], 1
	v_cvt_pk_bf16_f32 v116, v116, v117
	v_cvt_pk_bf16_f32 v117, v118, v119
	v_cvt_pk_bf16_f32 v118, v108, v109
	v_pk_mul_f32 v[108:109], v[110:111], v[148:149] op_sel_hi:[1,0]
	v_lshl_add_u64 v[120:121], v[120:121], 0, s[14:15]
	v_pk_mul_f32 v[108:109], v[108:109], v[108:109]
	v_lshl_add_u64 v[120:121], v[120:121], 0, s[24:25]
	v_and_b32_e32 v144, 48, v144
	v_cvt_pk_bf16_f32 v119, v108, v109
	v_add_u32_e32 v108, 16, v140
	v_lshl_add_u64 v[120:121], v[120:121], 0, v[144:145]
	v_ashrrev_i32_e32 v109, 31, v108
	global_store_dwordx4 v[120:121], v[116:119], off offset:256
	v_max_f32_e32 v100, 0, v100
	v_max_f32_e32 v101, 0, v101
	v_lshlrev_b64 v[116:117], 13, v[108:109]
	v_max_f32_e32 v108, v112, v112
	v_mov_b32_e32 v112, v149
	v_max_f32_e32 v102, 0, v102
	v_max_f32_e32 v103, 0, v103
	v_max_f32_e32 v96, 0, v96
	v_max_f32_e32 v97, 0, v97
	v_pk_mul_f32 v[100:101], v[100:101], v[112:113] op_sel_hi:[1,0]
	v_pk_mul_f32 v[102:103], v[102:103], v[112:113] op_sel_hi:[1,0]
	v_pk_mul_f32 v[96:97], v[96:97], v[112:113] op_sel_hi:[1,0]
	v_pk_mul_f32 v[100:101], v[100:101], v[100:101]
	v_pk_mul_f32 v[102:103], v[102:103], v[102:103]
	v_max_f32_e32 v98, 0, v98
	v_max_f32_e32 v99, 0, v99
	v_pk_mul_f32 v[96:97], v[96:97], v[96:97]
	v_cvt_pk_bf16_f32 v100, v100, v101
	v_cvt_pk_bf16_f32 v101, v102, v103
	v_cvt_pk_bf16_f32 v102, v96, v97
	v_pk_mul_f32 v[96:97], v[98:99], v[112:113] op_sel_hi:[1,0]
	ds_read2_b32 v[98:99], v146 offset0:32 offset1:48
	v_max_f32_e32 v92, 0, v92
	v_max_f32_e32 v93, 0, v93
	v_max_f32_e32 v94, 0, v94
	v_max_f32_e32 v95, 0, v95
	v_max_f32_e32 v88, 0, v88
	v_max_f32_e32 v89, 0, v89
	v_pk_mul_f32 v[96:97], v[96:97], v[96:97]
	s_waitcnt lgkmcnt(0)
;   DI void operator()(const f32x4 (&acc)[2][2][4][2], const pg8::Unit& u, int wr, int wc, int fr_, int fq_) const {
;     ...
;             } else {
;               if (n == 0) {
;                 const f32x4 v1 = acc[ai][bj][m][1];
;                 u32x4 o4;
;                 { const float t0 = fmaxf(v[0], 0.f) * rinv, t1 = fmaxf(v[1], 0.f) * rinv, t2 = fmaxf(v[2], 0.f) * rinv, t3 = fmaxf(v[3], 0.f) * rinv;
;                   o4.x = pack2(t0 * t0, t1 * t1); o4.y = pack2(t2 * t2, t3 * t3); }
;                 { const float t0 = fmaxf(v1[0], 0.f) * rinv, t1 = fmaxf(v1[1], 0.f) * rinv, t2 = fmaxf(v1[2], 0.f) * rinv, t3 = fmaxf(v1[3], 0.f) * rinv;
;                   o4.z = pack2(t0 * t0, t1 * t1); o4.w = pack2(t2 * t2, t3 * t3); }
;                 *(u32x4*)((u16*)big + (size_t)token * 4096 + u.pn * 256 + bj * 128 + wc * 32 + 8 * fq) = o4;
;               }
	v_pk_mul_f32 v[92:93], v[92:93], v[98:99] op_sel_hi:[1,0]
	v_pk_mul_f32 v[94:95], v[94:95], v[98:99] op_sel_hi:[1,0]
	v_pk_mul_f32 v[88:89], v[88:89], v[98:99] op_sel_hi:[1,0]
	v_cvt_pk_bf16_f32 v103, v96, v97
	v_add_u32_e32 v96, 32, v140
	v_pk_mul_f32 v[92:93], v[92:93], v[92:93]
	v_pk_mul_f32 v[94:95], v[94:95], v[94:95]
	v_max_f32_e32 v90, 0, v90
	v_max_f32_e32 v91, 0, v91
	v_pk_mul_f32 v[88:89], v[88:89], v[88:89]
	v_max_f32_e32 v84, 0, v84
	v_max_f32_e32 v85, 0, v85
	v_max_f32_e32 v86, 0, v86
	v_max_f32_e32 v87, 0, v87
	v_max_f32_e32 v76, 0, v76
	v_max_f32_e32 v77, 0, v77
	v_ashrrev_i32_e32 v97, 31, v96
	v_cvt_pk_bf16_f32 v92, v92, v93
	v_cvt_pk_bf16_f32 v93, v94, v95
	v_cvt_pk_bf16_f32 v94, v88, v89
	v_pk_mul_f32 v[88:89], v[90:91], v[98:99] op_sel_hi:[1,0]
	v_pk_mul_f32 v[84:85], v[84:85], v[98:99] op_sel_hi:[1,0]
	v_pk_mul_f32 v[86:87], v[86:87], v[98:99] op_sel_hi:[1,0]
	v_pk_mul_f32 v[76:77], v[76:77], v[98:99] op_sel_hi:[1,0]
	v_lshlrev_b64 v[96:97], 13, v[96:97]
	v_pk_mul_f32 v[88:89], v[88:89], v[88:89]
	v_pk_mul_f32 v[84:85], v[84:85], v[84:85]
	v_pk_mul_f32 v[86:87], v[86:87], v[86:87]
	v_max_f32_e32 v78, 0, v78
	v_max_f32_e32 v79, 0, v79
	v_pk_mul_f32 v[76:77], v[76:77], v[76:77]
	v_cvt_pk_bf16_f32 v95, v88, v89
	v_lshl_add_u64 v[88:89], s[2:3], 0, v[96:97]
	v_cvt_pk_bf16_f32 v84, v84, v85
	v_cvt_pk_bf16_f32 v85, v86, v87
	v_cvt_pk_bf16_f32 v86, v76, v77
	v_pk_mul_f32 v[76:77], v[78:79], v[98:99] op_sel_hi:[1,0]
	v_lshl_add_u64 v[88:89], v[88:89], 0, s[14:15]
	v_pk_mul_f32 v[76:77], v[76:77], v[76:77]
	v_lshl_add_u64 v[88:89], v[88:89], 0, s[24:25]
	v_cvt_pk_bf16_f32 v87, v76, v77
	v_add_u32_e32 v76, 48, v140
	v_lshl_add_u64 v[88:89], v[88:89], 0, v[144:145]
	v_ashrrev_i32_e32 v77, 31, v76
	global_store_dwordx4 v[88:89], v[84:87], off offset:256
	v_max_f32_e32 v68, 0, v68
	v_max_f32_e32 v69, 0, v69
	v_lshlrev_b64 v[84:85], 13, v[76:77]
	v_max_f32_e32 v76, v80, v80
	v_mov_b32_e32 v80, v99
	v_max_f32_e32 v70, 0, v70
	v_max_f32_e32 v71, 0, v71
	v_max_f32_e32 v64, 0, v64
	v_max_f32_e32 v65, 0, v65
	v_pk_mul_f32 v[68:69], v[68:69], v[80:81] op_sel_hi:[1,0]
	v_pk_mul_f32 v[70:71], v[70:71], v[80:81] op_sel_hi:[1,0]
	v_pk_mul_f32 v[64:65], v[64:65], v[80:81] op_sel_hi:[1,0]
	v_pk_mul_f32 v[68:69], v[68:69], v[68:69]
	v_pk_mul_f32 v[70:71], v[70:71], v[70:71]
	v_max_f32_e32 v66, 0, v66
	v_max_f32_e32 v67, 0, v67
	v_pk_mul_f32 v[64:65], v[64:65], v[64:65]
	v_cvt_pk_bf16_f32 v68, v68, v69
	v_cvt_pk_bf16_f32 v69, v70, v71
	v_cvt_pk_bf16_f32 v70, v64, v65
	v_pk_mul_f32 v[64:65], v[66:67], v[80:81] op_sel_hi:[1,0]
	ds_read2_b32 v[66:67], v146 offset0:128 offset1:144
	v_max_f32_e32 v60, 0, v60
	v_max_f32_e32 v61, 0, v61
	v_max_f32_e32 v62, 0, v62
	v_max_f32_e32 v63, 0, v63
	v_max_f32_e32 v56, 0, v56
	v_max_f32_e32 v57, 0, v57
	v_pk_mul_f32 v[64:65], v[64:65], v[64:65]
	s_waitcnt lgkmcnt(0)
	v_pk_mul_f32 v[60:61], v[60:61], v[66:67] op_sel_hi:[1,0]
	v_pk_mul_f32 v[62:63], v[62:63], v[66:67] op_sel_hi:[1,0]
	v_pk_mul_f32 v[56:57], v[56:57], v[66:67] op_sel_hi:[1,0]
	v_cvt_pk_bf16_f32 v71, v64, v65
	v_add_u32_e32 v64, 0x80, v140
	v_pk_mul_f32 v[60:61], v[60:61], v[60:61]
	v_pk_mul_f32 v[62:63], v[62:63], v[62:63]
	v_max_f32_e32 v58, 0, v58
	v_max_f32_e32 v59, 0, v59
	v_pk_mul_f32 v[56:57], v[56:57], v[56:57]
	v_max_f32_e32 v52, 0, v52
	v_max_f32_e32 v53, 0, v53
	v_max_f32_e32 v54, 0, v54
	v_max_f32_e32 v55, 0, v55
	v_max_f32_e32 v44, 0, v44
	v_max_f32_e32 v45, 0, v45
	v_ashrrev_i32_e32 v65, 31, v64
	v_cvt_pk_bf16_f32 v60, v60, v61
	v_cvt_pk_bf16_f32 v61, v62, v63
	v_cvt_pk_bf16_f32 v62, v56, v57
	v_pk_mul_f32 v[56:57], v[58:59], v[66:67] op_sel_hi:[1,0]
	v_pk_mul_f32 v[52:53], v[52:53], v[66:67] op_sel_hi:[1,0]
	v_pk_mul_f32 v[54:55], v[54:55], v[66:67] op_sel_hi:[1,0]
	v_pk_mul_f32 v[44:45], v[44:45], v[66:67] op_sel_hi:[1,0]
	v_lshlrev_b64 v[64:65], 13, v[64:65]
	v_pk_mul_f32 v[56:57], v[56:57], v[56:57]
	v_pk_mul_f32 v[52:53], v[52:53], v[52:53]
	v_pk_mul_f32 v[54:55], v[54:55], v[54:55]
	v_max_f32_e32 v46, 0, v46
	v_max_f32_e32 v47, 0, v47
	v_pk_mul_f32 v[44:45], v[44:45], v[44:45]
	v_cvt_pk_bf16_f32 v63, v56, v57
	v_lshl_add_u64 v[56:57], s[2:3], 0, v[64:65]
	v_cvt_pk_bf16_f32 v52, v52, v53
	v_cvt_pk_bf16_f32 v53, v54, v55
	v_cvt_pk_bf16_f32 v54, v44, v45
	v_pk_mul_f32 v[44:45], v[46:47], v[66:67] op_sel_hi:[1,0]
	v_lshl_add_u64 v[56:57], v[56:57], 0, s[14:15]
	v_pk_mul_f32 v[44:45], v[44:45], v[44:45]
	v_lshl_add_u64 v[56:57], v[56:57], 0, s[24:25]
	v_cvt_pk_bf16_f32 v55, v44, v45
	v_add_u32_e32 v44, 0x90, v140
	v_lshl_add_u64 v[56:57], v[56:57], 0, v[144:145]
	v_ashrrev_i32_e32 v45, 31, v44
	global_store_dwordx4 v[56:57], v[52:55], off offset:256
	v_max_f32_e32 v36, 0, v36
	v_max_f32_e32 v37, 0, v37
	v_lshlrev_b64 v[52:53], 13, v[44:45]
	v_max_f32_e32 v44, v48, v48
	v_mov_b32_e32 v48, v67
	v_max_f32_e32 v38, 0, v38
	v_max_f32_e32 v39, 0, v39
	v_max_f32_e32 v32, 0, v32
	v_max_f32_e32 v33, 0, v33
	v_pk_mul_f32 v[36:37], v[36:37], v[48:49] op_sel_hi:[1,0]
	v_pk_mul_f32 v[38:39], v[38:39], v[48:49] op_sel_hi:[1,0]
	v_pk_mul_f32 v[32:33], v[32:33], v[48:49] op_sel_hi:[1,0]
	v_pk_mul_f32 v[36:37], v[36:37], v[36:37]
	v_pk_mul_f32 v[38:39], v[38:39], v[38:39]
	v_max_f32_e32 v34, 0, v34
	v_max_f32_e32 v35, 0, v35
	v_pk_mul_f32 v[32:33], v[32:33], v[32:33]
	v_cvt_pk_bf16_f32 v36, v36, v37
	v_cvt_pk_bf16_f32 v37, v38, v39
	v_cvt_pk_bf16_f32 v38, v32, v33
	v_pk_mul_f32 v[32:33], v[34:35], v[48:49] op_sel_hi:[1,0]
	ds_read2_b32 v[34:35], v146 offset0:160 offset1:176
	v_max_f32_e32 v28, 0, v28
	v_max_f32_e32 v29, 0, v29
	v_max_f32_e32 v30, 0, v30
	v_max_f32_e32 v31, 0, v31
	v_max_f32_e32 v24, 0, v24
	v_max_f32_e32 v25, 0, v25
	v_pk_mul_f32 v[32:33], v[32:33], v[32:33]
	s_waitcnt lgkmcnt(0)
;   DI void operator()(const f32x4 (&acc)[2][2][4][2], const pg8::Unit& u, int wr, int wc, int fr_, int fq_) const {
;     ...
;             } else {
;               if (n == 0) {
;                 const f32x4 v1 = acc[ai][bj][m][1];
;                 u32x4 o4;
;                 { const float t0 = fmaxf(v[0], 0.f) * rinv, t1 = fmaxf(v[1], 0.f) * rinv, t2 = fmaxf(v[2], 0.f) * rinv, t3 = fmaxf(v[3], 0.f) * rinv;
;                   o4.x = pack2(t0 * t0, t1 * t1); o4.y = pack2(t2 * t2, t3 * t3); }
;                 { const float t0 = fmaxf(v1[0], 0.f) * rinv, t1 = fmaxf(v1[1], 0.f) * rinv, t2 = fmaxf(v1[2], 0.f) * rinv, t3 = fmaxf(v1[3], 0.f) * rinv;
;                   o4.z = pack2(t0 * t0, t1 * t1); o4.w = pack2(t2 * t2, t3 * t3); }
;                 *(u32x4*)((u16*)big + (size_t)token * 4096 + u.pn * 256 + bj * 128 + wc * 32 + 8 * fq) = o4;
;               }
	v_pk_mul_f32 v[28:29], v[28:29], v[34:35] op_sel_hi:[1,0]
	v_pk_mul_f32 v[30:31], v[30:31], v[34:35] op_sel_hi:[1,0]
	v_pk_mul_f32 v[24:25], v[24:25], v[34:35] op_sel_hi:[1,0]
	v_cvt_pk_bf16_f32 v39, v32, v33
	v_add_u32_e32 v32, 0xa0, v140
	v_pk_mul_f32 v[28:29], v[28:29], v[28:29]
	v_pk_mul_f32 v[30:31], v[30:31], v[30:31]
	v_max_f32_e32 v26, 0, v26
	v_max_f32_e32 v27, 0, v27
	v_pk_mul_f32 v[24:25], v[24:25], v[24:25]
	v_max_f32_e32 v20, 0, v20
	v_max_f32_e32 v21, 0, v21
	v_max_f32_e32 v22, 0, v22
	v_max_f32_e32 v23, 0, v23
	v_max_f32_e32 v12, 0, v12
	v_max_f32_e32 v13, 0, v13
	v_ashrrev_i32_e32 v33, 31, v32
	v_cvt_pk_bf16_f32 v28, v28, v29
	v_cvt_pk_bf16_f32 v29, v30, v31
	v_cvt_pk_bf16_f32 v30, v24, v25
	v_pk_mul_f32 v[24:25], v[26:27], v[34:35] op_sel_hi:[1,0]
	v_pk_mul_f32 v[20:21], v[20:21], v[34:35] op_sel_hi:[1,0]
	v_pk_mul_f32 v[22:23], v[22:23], v[34:35] op_sel_hi:[1,0]
	v_pk_mul_f32 v[12:13], v[12:13], v[34:35] op_sel_hi:[1,0]
	v_lshlrev_b64 v[32:33], 13, v[32:33]
	v_pk_mul_f32 v[24:25], v[24:25], v[24:25]
	v_pk_mul_f32 v[20:21], v[20:21], v[20:21]
	v_pk_mul_f32 v[22:23], v[22:23], v[22:23]
	v_max_f32_e32 v14, 0, v14
	v_max_f32_e32 v15, 0, v15
	v_pk_mul_f32 v[12:13], v[12:13], v[12:13]
	v_cvt_pk_bf16_f32 v31, v24, v25
	v_lshl_add_u64 v[24:25], s[2:3], 0, v[32:33]
	v_cvt_pk_bf16_f32 v20, v20, v21
	v_cvt_pk_bf16_f32 v21, v22, v23
	v_cvt_pk_bf16_f32 v22, v12, v13
	v_pk_mul_f32 v[12:13], v[14:15], v[34:35] op_sel_hi:[1,0]
	v_lshl_add_u64 v[24:25], v[24:25], 0, s[14:15]
	v_pk_mul_f32 v[12:13], v[12:13], v[12:13]
	v_lshl_add_u64 v[24:25], v[24:25], 0, s[24:25]
	v_cvt_pk_bf16_f32 v23, v12, v13
	v_add_u32_e32 v12, 0xb0, v140
	v_lshl_add_u64 v[24:25], v[24:25], 0, v[144:145]
	v_ashrrev_i32_e32 v13, 31, v12
	v_max_f32_e32 v109, v113, v113
	v_max_f32_e32 v110, v114, v114
	v_max_f32_e32 v111, v115, v115
	v_max_f32_e32 v77, v81, v81
	v_max_f32_e32 v78, v82, v82
	v_max_f32_e32 v79, v83, v83
	v_max_f32_e32 v45, v49, v49
	v_max_f32_e32 v46, v50, v50
	v_max_f32_e32 v47, v51, v51
	global_store_dwordx4 v[24:25], v[20:23], off offset:256
	v_max_f32_e32 v14, v18, v18
	v_max_f32_e32 v15, v19, v19
	v_lshlrev_b64 v[20:21], 13, v[12:13]
	v_max_f32_e32 v12, v16, v16
	v_max_f32_e32 v13, v17, v17
	v_max_f32_e32 v108, 0, v108
	v_max_f32_e32 v109, 0, v109
	v_max_f32_e32 v110, 0, v110
	v_max_f32_e32 v111, 0, v111
	v_max_f32_e32 v104, 0, v104
	v_max_f32_e32 v105, 0, v105
	v_max_f32_e32 v76, 0, v76
	v_max_f32_e32 v77, 0, v77
	v_max_f32_e32 v78, 0, v78
	v_max_f32_e32 v79, 0, v79
	v_max_f32_e32 v72, 0, v72
	v_max_f32_e32 v73, 0, v73
	v_max_f32_e32 v44, 0, v44
	v_max_f32_e32 v45, 0, v45
	v_max_f32_e32 v46, 0, v46
	v_max_f32_e32 v47, 0, v47
	v_max_f32_e32 v40, 0, v40
	v_max_f32_e32 v41, 0, v41
	v_max_f32_e32 v12, 0, v12
	v_max_f32_e32 v13, 0, v13
	v_max_f32_e32 v14, 0, v14
	v_max_f32_e32 v15, 0, v15
	v_mov_b32_e32 v16, v35
	v_max_f32_e32 v8, 0, v8
	v_max_f32_e32 v9, 0, v9
	v_pk_mul_f32 v[108:109], v[108:109], v[112:113] op_sel_hi:[1,0]
	v_pk_mul_f32 v[110:111], v[110:111], v[112:113] op_sel_hi:[1,0]
	v_pk_mul_f32 v[104:105], v[104:105], v[112:113] op_sel_hi:[1,0]
	v_pk_mul_f32 v[76:77], v[76:77], v[80:81] op_sel_hi:[1,0]
	v_pk_mul_f32 v[78:79], v[78:79], v[80:81] op_sel_hi:[1,0]
	v_pk_mul_f32 v[72:73], v[72:73], v[80:81] op_sel_hi:[1,0]
	v_pk_mul_f32 v[44:45], v[44:45], v[48:49] op_sel_hi:[1,0]
	v_pk_mul_f32 v[46:47], v[46:47], v[48:49] op_sel_hi:[1,0]
	v_pk_mul_f32 v[40:41], v[40:41], v[48:49] op_sel_hi:[1,0]
	v_pk_mul_f32 v[12:13], v[12:13], v[16:17] op_sel_hi:[1,0]
	v_pk_mul_f32 v[14:15], v[14:15], v[16:17] op_sel_hi:[1,0]
	v_pk_mul_f32 v[8:9], v[8:9], v[16:17] op_sel_hi:[1,0]
	v_pk_mul_f32 v[108:109], v[108:109], v[108:109]
	v_pk_mul_f32 v[110:111], v[110:111], v[110:111]
	v_max_f32_e32 v106, 0, v106
	v_max_f32_e32 v107, 0, v107
	v_pk_mul_f32 v[104:105], v[104:105], v[104:105]
; #define PG8_WAIT_V(n) asm volatile("s_waitcnt vmcnt(" #n ")" ::: "memory")
; #define PG8_BAR __builtin_amdgcn_s_barrier()
; template <class Epi, class Sched>
; DI void gemm_phase(LAS unsigned char* lds, const Gemm g, const Sched& S, const Epi& E) {
;     ...
;     cur = nxt; cA = nA; cB = nB; ++ui;
;   }
;   PG8_WAIT_V(0);
;   if (wr == 0) PG8_BAR;
;   PG8_BAR;
;   DI void operator()(const f32x4 (&acc)[2][2][4][2], const pg8::Unit& u, int wr, int wc, int fr_, int fq_) const {
;     ...
;             } else {
;               if (n == 0) {
;                 const f32x4 v1 = acc[ai][bj][m][1];
;                 u32x4 o4;
;                 { const float t0 = fmaxf(v[0], 0.f) * rinv, t1 = fmaxf(v[1], 0.f) * rinv, t2 = fmaxf(v[2], 0.f) * rinv, t3 = fmaxf(v[3], 0.f) * rinv;
;                   o4.x = pack2(t0 * t0, t1 * t1); o4.y = pack2(t2 * t2, t3 * t3); }
;                 { const float t0 = fmaxf(v1[0], 0.f) * rinv, t1 = fmaxf(v1[1], 0.f) * rinv, t2 = fmaxf(v1[2], 0.f) * rinv, t3 = fmaxf(v1[3], 0.f) * rinv;
;                   o4.z = pack2(t0 * t0, t1 * t1); o4.w = pack2(t2 * t2, t3 * t3); }
;                 *(u32x4*)((u16*)big + (size_t)token * 4096 + u.pn * 256 + bj * 128 + wc * 32 + 8 * fq) = o4;
;               }
	v_pk_mul_f32 v[76:77], v[76:77], v[76:77]
	v_pk_mul_f32 v[78:79], v[78:79], v[78:79]
	v_max_f32_e32 v74, 0, v74
	v_max_f32_e32 v75, 0, v75
	v_pk_mul_f32 v[72:73], v[72:73], v[72:73]
	v_pk_mul_f32 v[44:45], v[44:45], v[44:45]
	v_pk_mul_f32 v[46:47], v[46:47], v[46:47]
	v_max_f32_e32 v42, 0, v42
	v_max_f32_e32 v43, 0, v43
	v_pk_mul_f32 v[40:41], v[40:41], v[40:41]
	v_pk_mul_f32 v[12:13], v[12:13], v[12:13]
	v_pk_mul_f32 v[14:15], v[14:15], v[14:15]
	v_max_f32_e32 v10, 0, v10
	v_max_f32_e32 v11, 0, v11
	v_pk_mul_f32 v[8:9], v[8:9], v[8:9]
	v_cvt_pk_bf16_f32 v108, v108, v109
	v_cvt_pk_bf16_f32 v109, v110, v111
	v_cvt_pk_bf16_f32 v110, v104, v105
	v_pk_mul_f32 v[104:105], v[106:107], v[112:113] op_sel_hi:[1,0]
	v_cvt_pk_bf16_f32 v76, v76, v77
	v_cvt_pk_bf16_f32 v77, v78, v79
	v_cvt_pk_bf16_f32 v78, v72, v73
	v_pk_mul_f32 v[72:73], v[74:75], v[80:81] op_sel_hi:[1,0]
	v_cvt_pk_bf16_f32 v44, v44, v45
	v_cvt_pk_bf16_f32 v45, v46, v47
	v_cvt_pk_bf16_f32 v46, v40, v41
	v_pk_mul_f32 v[40:41], v[42:43], v[48:49] op_sel_hi:[1,0]
	v_cvt_pk_bf16_f32 v12, v12, v13
	v_cvt_pk_bf16_f32 v13, v14, v15
	v_cvt_pk_bf16_f32 v14, v8, v9
	v_pk_mul_f32 v[8:9], v[10:11], v[16:17] op_sel_hi:[1,0]
	v_max_f32_e32 v4, 0, v4
	v_max_f32_e32 v5, 0, v5
	v_max_f32_e32 v6, 0, v6
	v_max_f32_e32 v7, 0, v7
	v_max_f32_e32 v0, 0, v0
	v_max_f32_e32 v1, 0, v1
	v_pk_mul_f32 v[104:105], v[104:105], v[104:105]
	v_pk_mul_f32 v[72:73], v[72:73], v[72:73]
	v_pk_mul_f32 v[40:41], v[40:41], v[40:41]
	v_pk_mul_f32 v[8:9], v[8:9], v[8:9]
	v_pk_mul_f32 v[4:5], v[4:5], v[16:17] op_sel_hi:[1,0]
	v_pk_mul_f32 v[6:7], v[6:7], v[16:17] op_sel_hi:[1,0]
	v_pk_mul_f32 v[0:1], v[0:1], v[16:17] op_sel_hi:[1,0]
	v_cvt_pk_bf16_f32 v111, v104, v105
	v_lshl_add_u64 v[104:105], s[2:3], 0, v[116:117]
	v_cvt_pk_bf16_f32 v79, v72, v73
	v_lshl_add_u64 v[72:73], s[2:3], 0, v[84:85]
	v_cvt_pk_bf16_f32 v47, v40, v41
	v_lshl_add_u64 v[40:41], s[2:3], 0, v[52:53]
	v_cvt_pk_bf16_f32 v15, v8, v9
	v_lshl_add_u64 v[8:9], s[2:3], 0, v[20:21]
	v_pk_mul_f32 v[4:5], v[4:5], v[4:5]
	v_pk_mul_f32 v[6:7], v[6:7], v[6:7]
	v_max_f32_e32 v2, 0, v2
	v_max_f32_e32 v3, 0, v3
	v_pk_mul_f32 v[0:1], v[0:1], v[0:1]
	v_lshl_add_u64 v[104:105], v[104:105], 0, s[14:15]
	v_lshl_add_u64 v[72:73], v[72:73], 0, s[14:15]
	v_lshl_add_u64 v[40:41], v[40:41], 0, s[14:15]
	v_lshl_add_u64 v[8:9], v[8:9], 0, s[14:15]
	v_cvt_pk_bf16_f32 v4, v4, v5
	v_cvt_pk_bf16_f32 v5, v6, v7
	v_cvt_pk_bf16_f32 v6, v0, v1
	v_pk_mul_f32 v[0:1], v[2:3], v[16:17] op_sel_hi:[1,0]
	v_lshl_add_u64 v[104:105], v[104:105], 0, s[24:25]
	v_lshl_add_u64 v[72:73], v[72:73], 0, s[24:25]
	v_lshl_add_u64 v[40:41], v[40:41], 0, s[24:25]
	v_lshl_add_u64 v[8:9], v[8:9], 0, s[24:25]
	v_pk_mul_f32 v[0:1], v[0:1], v[0:1]
	v_lshl_add_u64 v[104:105], v[104:105], 0, v[144:145]
	v_lshl_add_u64 v[72:73], v[72:73], 0, v[144:145]
	v_lshl_add_u64 v[40:41], v[40:41], 0, v[144:145]
	v_lshl_add_u64 v[8:9], v[8:9], 0, v[144:145]
	v_cvt_pk_bf16_f32 v7, v0, v1
	s_and_b64 vcc, exec, s[36:37]
	s_mov_b32 s43, s42
	s_mov_b32 s45, s4
	s_mov_b32 s44, s6
	s_mov_b64 s[16:17], s[12:13]
	s_mov_b64 s[14:15], s[10:11]
	v_readlane_b32 s51, v237, 11
	global_store_dwordx4 v[120:121], v[124:127], off
	global_store_dwordx4 v[104:105], v[108:111], off
	global_store_dwordx4 v[104:105], v[100:103], off offset:256
	global_store_dwordx4 v[88:89], v[92:95], off
	global_store_dwordx4 v[72:73], v[76:79], off
	global_store_dwordx4 v[72:73], v[68:71], off offset:256
	global_store_dwordx4 v[56:57], v[60:63], off
	global_store_dwordx4 v[40:41], v[44:47], off
	global_store_dwordx4 v[40:41], v[36:39], off offset:256
	global_store_dwordx4 v[24:25], v[28:31], off
	global_store_dwordx4 v[8:9], v[12:15], off
	global_store_dwordx4 v[8:9], v[4:7], off offset:256
	s_cbranch_vccz .LBB0_1822
	s_waitcnt vmcnt(0)
	s_cmpk_gt_u32 s9, 0xff
	s_cbranch_scc1 .LBB0_1833
	s_barrier

; #define PG8_STAGE(bufoff, gbase, voff) do { _Pragma("unroll") for (int _i = 0; _i < 2; ++_i) \
;     __builtin_amdgcn_global_load_lds((const unsigned*)((const char*)(gbase) + (voff)[_i]), (LAS unsigned*)(lds + (bufoff) + ldsw + _i * 8192), 16, 0, 0); } while (0)
; #define PG8_LDA(dst, b, h) do { _Pragma("unroll") for (int m = 0; m < 4; ++m) _Pragma("unroll") for (int k = 0; k < 2; ++k) dst[m][k] = *(const LAS bf16x8*)(lds + PG8_SA(b, h) + aoff + m * 2048 + k * 1024); } while (0)
; #define PG8_LDB(dst, b, h) do { _Pragma("unroll") for (int n = 0; n < 2; ++n) _Pragma("unroll") for (int k = 0; k < 2; ++k) dst[n][k] = *(const LAS bf16x8*)(lds + PG8_SB(b, h) + boff + n * 2048 + k * 1024); } while (0)
; #define PG8_WAIT_V(n) asm volatile("s_waitcnt vmcnt(" #n ")" ::: "memory")
; template <class Epi, class Sched>
; DI void gemm_phase(LAS unsigned char* lds, const Gemm g, const Sched& S, const Epi& E) {
;     ...
;     for (int t = 0; t < nt; t += 2) {
;       const bool last = (t == nt - 2);
;       const char* a1 = cA + (size_t)(t + 1) * kstep;
;       const char* a2 = last ? nA : cA + (size_t)(t + 2) * kstep; const char* b2 = last ? nB : cB + (size_t)(t + 2) * kstep;
;       const char* a3 = a2 + kstep; const char* b3 = b2 + kstep;
;       PG8_LDB(B0, 0, 0); PG8_SCHED; PG8_LDA(At, 0, 0); PG8_STAGE(PG8_SA(1, 1), a1 + hstep, voffA);
;       PG8_WAIT_L(8); PG8_BAR; PG8_WAIT_L(0); PG8_MMA(0, 0, At, B0); PG8_BAR; PG8_SCHED;
;       PG8_LDB(B1, 0, 1); PG8_STAGE(PG8_SB(0, 0), b2, voffB);
;       PG8_BAR; PG8_WAIT_L(0); PG8_MMA(0, 1, At, B1); PG8_BAR;
;       PG8_LDA(At, 0, 1); PG8_STAGE(PG8_SA(0, 0), a2, voffA);
;       PG8_BAR; PG8_WAIT_L(0); PG8_MMA(1, 0, At, B0); PG8_BAR; PG8_SCHED;
;       PG8_STAGE(PG8_SB(0, 1), b2 + hstep, voffB);
;       PG8_WAIT_V(6); PG8_BAR; PG8_MMA(1, 1, At, B1); PG8_BAR;
;       PG8_LDB(B0, 1, 0); PG8_SCHED; PG8_LDA(At, 1, 0); PG8_STAGE(PG8_SA(0, 1), a2 + hstep, voffA);
;       PG8_WAIT_L(8); PG8_BAR; PG8_WAIT_L(0); PG8_MMA(0, 0, At, B0); PG8_BAR; PG8_SCHED;
;       PG8_LDB(B1, 1, 1); PG8_STAGE(PG8_SB(1, 0), b3, voffB);
;       PG8_BAR; PG8_WAIT_L(0); PG8_MMA(0, 1, At, B1); PG8_BAR;
;       PG8_LDA(At, 1, 1); PG8_STAGE(PG8_SA(1, 0), a3, voffA);
;       PG8_BAR; PG8_WAIT_L(0); PG8_MMA(1, 0, At, B0); PG8_BAR; PG8_SCHED;
;       PG8_STAGE(PG8_SB(1, 1), b3 + hstep, voffB);
;       PG8_WAIT_V(6); PG8_BAR; PG8_MMA(1, 1, At, B1); PG8_BAR;
;     }
.LBB0_1905:
	s_add_u32 s22, s20, 0xfff00080
	s_addc_u32 s23, s21, -1
	s_add_i32 s51, 0, 0x10000
	v_add_u32_e32 v142, s51, v146
	ds_read_b128 v[138:141], v142
	ds_read_b128 v[148:151], v142 offset:1024
	ds_read_b128 v[152:155], v142 offset:2048
	ds_read_b128 v[156:159], v142 offset:3072
	s_cmp_eq_u32 s50, 60
	s_cselect_b32 s29, s11, s23
	s_cselect_b32 s28, s17, s22
	s_cselect_b32 s23, s7, s49
	s_cselect_b32 s22, s19, s24
	v_lshl_add_u64 v[142:143], s[20:21], 0, v[134:135]
	s_add_i32 m0, s39, 0xc000
	ds_read_b128 v[160:163], v147
	ds_read_b128 v[164:167], v147 offset:1024
	ds_read_b128 v[168:171], v147 offset:2048
	ds_read_b128 v[172:175], v147 offset:3072
	ds_read_b128 v[176:179], v147 offset:4096
	ds_read_b128 v[196:199], v147 offset:5120
	ds_read_b128 v[200:203], v147 offset:6144
	ds_read_b128 v[204:207], v147 offset:7168
	global_load_lds_dwordx4 v[142:143], off
	v_lshl_add_u64 v[142:143], s[20:21], 0, v[136:137]
	s_add_i32 m0, s39, 0xe000
	s_nop 0
	global_load_lds_dwordx4 v[142:143], off
	s_waitcnt lgkmcnt(8)
	s_barrier
	s_waitcnt lgkmcnt(0)
	s_waitcnt lgkmcnt(0)
	v_mfma_f32_16x16x32_bf16 v[124:127], v[138:141], v[160:163], v[124:127]
	v_mfma_f32_16x16x32_bf16 v[120:123], v[152:155], v[160:163], v[120:123]
	v_mfma_f32_16x16x32_bf16 v[108:111], v[138:141], v[168:171], v[108:111]
	v_mfma_f32_16x16x32_bf16 v[104:107], v[152:155], v[168:171], v[104:107]
	v_mfma_f32_16x16x32_bf16 v[92:95], v[138:141], v[176:179], v[92:95]
	v_mfma_f32_16x16x32_bf16 v[88:91], v[152:155], v[176:179], v[88:91]
	v_mfma_f32_16x16x32_bf16 v[76:79], v[138:141], v[200:203], v[76:79]
	v_mfma_f32_16x16x32_bf16 v[72:75], v[152:155], v[200:203], v[72:75]
	v_mfma_f32_16x16x32_bf16 v[124:127], v[148:151], v[164:167], v[124:127]
	v_mfma_f32_16x16x32_bf16 v[120:123], v[156:159], v[164:167], v[120:123]
	v_mfma_f32_16x16x32_bf16 v[108:111], v[148:151], v[172:175], v[108:111]
	v_mfma_f32_16x16x32_bf16 v[104:107], v[156:159], v[172:175], v[104:107]
	v_mfma_f32_16x16x32_bf16 v[92:95], v[148:151], v[196:199], v[92:95]
	v_mfma_f32_16x16x32_bf16 v[88:91], v[156:159], v[196:199], v[88:91]
	v_mfma_f32_16x16x32_bf16 v[76:79], v[148:151], v[204:207], v[76:79]
	v_mfma_f32_16x16x32_bf16 v[72:75], v[156:159], v[204:207], v[72:75]
	s_barrier
	s_add_i32 s54, 0, 0x14000
	v_add_u32_e32 v142, s54, v146
	s_add_i32 s51, s51, s38
	ds_read_b128 v[208:211], v142
	ds_read_b128 v[212:215], v142 offset:1024
	ds_read_b128 v[216:219], v142 offset:2048
	ds_read_b128 v[220:223], v142 offset:3072
	v_lshl_add_u64 v[142:143], s[22:23], 0, v[144:145]
	s_mov_b32 m0, s51
	v_lshl_add_u64 v[180:181], s[22:23], 0, v[132:133]
	global_load_lds_dwordx4 v[142:143], off
	s_add_i32 m0, s51, 0x2000
	s_nop 0
	global_load_lds_dwordx4 v[180:181], off
	s_barrier
	s_waitcnt lgkmcnt(0)
	s_waitcnt lgkmcnt(0)
	v_mfma_f32_16x16x32_bf16 v[116:119], v[208:211], v[160:163], v[116:119]
	v_mfma_f32_16x16x32_bf16 v[112:115], v[216:219], v[160:163], v[112:115]
	v_mfma_f32_16x16x32_bf16 v[100:103], v[208:211], v[168:171], v[100:103]
	v_mfma_f32_16x16x32_bf16 v[96:99], v[216:219], v[168:171], v[96:99]
	v_mfma_f32_16x16x32_bf16 v[84:87], v[208:211], v[176:179], v[84:87]
	v_mfma_f32_16x16x32_bf16 v[80:83], v[216:219], v[176:179], v[80:83]
	v_mfma_f32_16x16x32_bf16 v[68:71], v[208:211], v[200:203], v[68:71]
	v_mfma_f32_16x16x32_bf16 v[64:67], v[216:219], v[200:203], v[64:67]
	v_mfma_f32_16x16x32_bf16 v[116:119], v[212:215], v[164:167], v[116:119]
	v_mfma_f32_16x16x32_bf16 v[112:115], v[220:223], v[164:167], v[112:115]
	v_mfma_f32_16x16x32_bf16 v[100:103], v[212:215], v[172:175], v[100:103]
	v_mfma_f32_16x16x32_bf16 v[96:99], v[220:223], v[172:175], v[96:99]
	v_mfma_f32_16x16x32_bf16 v[84:87], v[212:215], v[196:199], v[84:87]
	v_mfma_f32_16x16x32_bf16 v[80:83], v[220:223], v[196:199], v[80:83]
	v_mfma_f32_16x16x32_bf16 v[68:71], v[212:215], v[204:207], v[68:71]
	v_mfma_f32_16x16x32_bf16 v[64:67], v[220:223], v[204:207], v[64:67]
	s_mov_b32 m0, s39
	v_lshl_add_u64 v[224:225], s[28:29], 0, v[128:129]
	s_barrier
	ds_read_b128 v[160:163], v147 offset:16384
	ds_read_b128 v[164:167], v147 offset:17408
	ds_read_b128 v[168:171], v147 offset:18432
	ds_read_b128 v[172:175], v147 offset:19456
	ds_read_b128 v[176:179], v147 offset:20480
	ds_read_b128 v[196:199], v147 offset:21504
	ds_read_b128 v[200:203], v147 offset:22528
	ds_read_b128 v[204:207], v147 offset:23552
	global_load_lds_dwordx4 v[224:225], off
	v_lshl_add_u64 v[226:227], s[28:29], 0, v[130:131]
	s_mov_b32 m0, s40
	s_nop 0
	global_load_lds_dwordx4 v[226:227], off
	s_barrier
	s_waitcnt lgkmcnt(0)
	s_waitcnt lgkmcnt(0)
	v_mfma_f32_16x16x32_bf16 v[60:63], v[138:141], v[160:163], v[60:63]
	v_mfma_f32_16x16x32_bf16 v[56:59], v[152:155], v[160:163], v[56:59]
	v_mfma_f32_16x16x32_bf16 v[44:47], v[138:141], v[168:171], v[44:47]
	v_mfma_f32_16x16x32_bf16 v[40:43], v[152:155], v[168:171], v[40:43]
	v_mfma_f32_16x16x32_bf16 v[28:31], v[138:141], v[176:179], v[28:31]
	v_mfma_f32_16x16x32_bf16 v[24:27], v[152:155], v[176:179], v[24:27]
	v_mfma_f32_16x16x32_bf16 v[12:15], v[138:141], v[200:203], v[12:15]
	v_mfma_f32_16x16x32_bf16 v[8:11], v[152:155], v[200:203], v[8:11]
	v_mfma_f32_16x16x32_bf16 v[60:63], v[148:151], v[164:167], v[60:63]
	v_mfma_f32_16x16x32_bf16 v[56:59], v[156:159], v[164:167], v[56:59]
	v_mfma_f32_16x16x32_bf16 v[44:47], v[148:151], v[172:175], v[44:47]
	v_mfma_f32_16x16x32_bf16 v[40:43], v[156:159], v[172:175], v[40:43]
	v_mfma_f32_16x16x32_bf16 v[28:31], v[148:151], v[196:199], v[28:31]
	v_mfma_f32_16x16x32_bf16 v[24:27], v[156:159], v[196:199], v[24:27]
	v_mfma_f32_16x16x32_bf16 v[12:15], v[148:151], v[204:207], v[12:15]
	v_mfma_f32_16x16x32_bf16 v[8:11], v[156:159], v[204:207], v[8:11]
	s_barrier
; #define PG8_STAGE(bufoff, gbase, voff) do { _Pragma("unroll") for (int _i = 0; _i < 2; ++_i) \
;     __builtin_amdgcn_global_load_lds((const unsigned*)((const char*)(gbase) + (voff)[_i]), (LAS unsigned*)(lds + (bufoff) + ldsw + _i * 8192), 16, 0, 0); } while (0)
; #define PG8_LDA(dst, b, h) do { _Pragma("unroll") for (int m = 0; m < 4; ++m) _Pragma("unroll") for (int k = 0; k < 2; ++k) dst[m][k] = *(const LAS bf16x8*)(lds + PG8_SA(b, h) + aoff + m * 2048 + k * 1024); } while (0)
; #define PG8_LDB(dst, b, h) do { _Pragma("unroll") for (int n = 0; n < 2; ++n) _Pragma("unroll") for (int k = 0; k < 2; ++k) dst[n][k] = *(const LAS bf16x8*)(lds + PG8_SB(b, h) + boff + n * 2048 + k * 1024); } while (0)
; #define PG8_WAIT_V(n) asm volatile("s_waitcnt vmcnt(" #n ")" ::: "memory")
; template <class Epi, class Sched>
; DI void gemm_phase(LAS unsigned char* lds, const Gemm g, const Sched& S, const Epi& E) {
;     ...
;     for (int t = 0; t < nt; t += 2) {
;       const bool last = (t == nt - 2);
;       const char* a1 = cA + (size_t)(t + 1) * kstep;
;       const char* a2 = last ? nA : cA + (size_t)(t + 2) * kstep; const char* b2 = last ? nB : cB + (size_t)(t + 2) * kstep;
;       const char* a3 = a2 + kstep; const char* b3 = b2 + kstep;
;       PG8_LDB(B0, 0, 0); PG8_SCHED; PG8_LDA(At, 0, 0); PG8_STAGE(PG8_SA(1, 1), a1 + hstep, voffA);
;       PG8_WAIT_L(8); PG8_BAR; PG8_WAIT_L(0); PG8_MMA(0, 0, At, B0); PG8_BAR; PG8_SCHED;
;       PG8_LDB(B1, 0, 1); PG8_STAGE(PG8_SB(0, 0), b2, voffB);
;       PG8_BAR; PG8_WAIT_L(0); PG8_MMA(0, 1, At, B1); PG8_BAR;
;       PG8_LDA(At, 0, 1); PG8_STAGE(PG8_SA(0, 0), a2, voffA);
;       PG8_BAR; PG8_WAIT_L(0); PG8_MMA(1, 0, At, B0); PG8_BAR; PG8_SCHED;
;       PG8_STAGE(PG8_SB(0, 1), b2 + hstep, voffB);
;       PG8_WAIT_V(6); PG8_BAR; PG8_MMA(1, 1, At, B1); PG8_BAR;
;       PG8_LDB(B0, 1, 0); PG8_SCHED; PG8_LDA(At, 1, 0); PG8_STAGE(PG8_SA(0, 1), a2 + hstep, voffA);
;       PG8_WAIT_L(8); PG8_BAR; PG8_WAIT_L(0); PG8_MMA(0, 0, At, B0); PG8_BAR; PG8_SCHED;
;       PG8_LDB(B1, 1, 1); PG8_STAGE(PG8_SB(1, 0), b3, voffB);
;       PG8_BAR; PG8_WAIT_L(0); PG8_MMA(0, 1, At, B1); PG8_BAR;
;       PG8_LDA(At, 1, 1); PG8_STAGE(PG8_SA(1, 0), a3, voffA);
;       PG8_BAR; PG8_WAIT_L(0); PG8_MMA(1, 0, At, B0); PG8_BAR; PG8_SCHED;
;       PG8_STAGE(PG8_SB(1, 1), b3 + hstep, voffB);
;       PG8_WAIT_V(6); PG8_BAR; PG8_MMA(1, 1, At, B1); PG8_BAR;
;     }
	s_add_u32 s52, s22, 0x100000
	s_addc_u32 s53, s23, 0
	s_add_i32 s51, s54, s38
	v_lshl_add_u64 v[138:139], s[52:53], 0, v[144:145]
	s_mov_b32 m0, s51
	s_nop 0
	global_load_lds_dwordx4 v[138:139], off
	v_lshl_add_u64 v[138:139], s[52:53], 0, v[132:133]
	s_add_i32 m0, s51, 0x2000
	s_nop 0
	global_load_lds_dwordx4 v[138:139], off
	s_waitcnt vmcnt(6)
	s_barrier
	v_mfma_f32_16x16x32_bf16 v[52:55], v[208:211], v[160:163], v[52:55]
	v_mfma_f32_16x16x32_bf16 v[48:51], v[216:219], v[160:163], v[48:51]
	v_mfma_f32_16x16x32_bf16 v[36:39], v[208:211], v[168:171], v[36:39]
	v_mfma_f32_16x16x32_bf16 v[32:35], v[216:219], v[168:171], v[32:35]
	v_mfma_f32_16x16x32_bf16 v[20:23], v[208:211], v[176:179], v[20:23]
	v_mfma_f32_16x16x32_bf16 v[16:19], v[216:219], v[176:179], v[16:19]
	v_mfma_f32_16x16x32_bf16 v[4:7], v[208:211], v[200:203], v[4:7]
	v_mfma_f32_16x16x32_bf16 v[0:3], v[216:219], v[200:203], v[0:3]
	v_mfma_f32_16x16x32_bf16 v[52:55], v[212:215], v[164:167], v[52:55]
	v_mfma_f32_16x16x32_bf16 v[48:51], v[220:223], v[164:167], v[48:51]
	v_mfma_f32_16x16x32_bf16 v[36:39], v[212:215], v[172:175], v[36:39]
	v_mfma_f32_16x16x32_bf16 v[32:35], v[220:223], v[172:175], v[32:35]
	v_mfma_f32_16x16x32_bf16 v[20:23], v[212:215], v[196:199], v[20:23]
	v_mfma_f32_16x16x32_bf16 v[16:19], v[220:223], v[196:199], v[16:19]
	v_mfma_f32_16x16x32_bf16 v[4:7], v[212:215], v[204:207], v[4:7]
	v_mfma_f32_16x16x32_bf16 v[0:3], v[220:223], v[204:207], v[0:3]
	s_add_i32 s51, 0, 0x18000
	v_add_u32_e32 v156, s51, v146
	s_barrier
	ds_read_b128 v[138:141], v156
	ds_read_b128 v[148:151], v156 offset:1024
	ds_read_b128 v[152:155], v156 offset:2048
	ds_read_b128 v[156:159], v156 offset:3072
	s_add_u32 s28, s28, 0x100000
	s_addc_u32 s29, s29, 0
	s_mov_b32 m0, s41
	v_lshl_add_u64 v[208:209], s[28:29], 0, v[128:129]
	ds_read_b128 v[160:163], v147 offset:32768
	ds_read_b128 v[164:167], v147 offset:33792
	ds_read_b128 v[168:171], v147 offset:34816
	ds_read_b128 v[172:175], v147 offset:35840
	ds_read_b128 v[176:179], v147 offset:36864
	ds_read_b128 v[196:199], v147 offset:37888
	ds_read_b128 v[200:203], v147 offset:38912
	ds_read_b128 v[204:207], v147 offset:39936
	global_load_lds_dwordx4 v[208:209], off
	v_lshl_add_u64 v[208:209], s[28:29], 0, v[130:131]
	s_mov_b32 m0, s42
	s_nop 0
	global_load_lds_dwordx4 v[208:209], off
	s_waitcnt lgkmcnt(8)
	s_barrier
	s_waitcnt lgkmcnt(0)
	s_waitcnt lgkmcnt(0)
	v_mfma_f32_16x16x32_bf16 v[124:127], v[138:141], v[160:163], v[124:127]
	v_mfma_f32_16x16x32_bf16 v[120:123], v[152:155], v[160:163], v[120:123]
	v_mfma_f32_16x16x32_bf16 v[108:111], v[138:141], v[168:171], v[108:111]
	v_mfma_f32_16x16x32_bf16 v[104:107], v[152:155], v[168:171], v[104:107]
	v_mfma_f32_16x16x32_bf16 v[92:95], v[138:141], v[176:179], v[92:95]
	v_mfma_f32_16x16x32_bf16 v[88:91], v[152:155], v[176:179], v[88:91]
	v_mfma_f32_16x16x32_bf16 v[76:79], v[138:141], v[200:203], v[76:79]
	v_mfma_f32_16x16x32_bf16 v[72:75], v[152:155], v[200:203], v[72:75]
	v_mfma_f32_16x16x32_bf16 v[124:127], v[148:151], v[164:167], v[124:127]
	v_mfma_f32_16x16x32_bf16 v[120:123], v[156:159], v[164:167], v[120:123]
	v_mfma_f32_16x16x32_bf16 v[108:111], v[148:151], v[172:175], v[108:111]
	v_mfma_f32_16x16x32_bf16 v[104:107], v[156:159], v[172:175], v[104:107]
	v_mfma_f32_16x16x32_bf16 v[92:95], v[148:151], v[196:199], v[92:95]
	v_mfma_f32_16x16x32_bf16 v[88:91], v[156:159], v[196:199], v[88:91]
	v_mfma_f32_16x16x32_bf16 v[76:79], v[148:151], v[204:207], v[76:79]
	v_mfma_f32_16x16x32_bf16 v[72:75], v[156:159], v[204:207], v[72:75]
	s_barrier
	s_add_i32 s28, 0, 0x1c000
	s_add_i32 s29, s51, s38
	v_add_u32_e32 v220, s28, v146
	v_lshl_add_u64 v[142:143], v[142:143], 0, s[0:1]
	s_mov_b32 m0, s29
	ds_read_b128 v[208:211], v220
	ds_read_b128 v[212:215], v220 offset:1024
	ds_read_b128 v[216:219], v220 offset:2048
	ds_read_b128 v[220:223], v220 offset:3072
	global_load_lds_dwordx4 v[142:143], off
	v_lshl_add_u64 v[142:143], v[180:181], 0, s[0:1]
	s_add_i32 m0, s29, 0x2000
	s_nop 0
	global_load_lds_dwordx4 v[142:143], off
	s_barrier
	s_waitcnt lgkmcnt(0)
	s_waitcnt lgkmcnt(0)
	v_mfma_f32_16x16x32_bf16 v[116:119], v[208:211], v[160:163], v[116:119]
	v_mfma_f32_16x16x32_bf16 v[112:115], v[216:219], v[160:163], v[112:115]
	v_mfma_f32_16x16x32_bf16 v[100:103], v[208:211], v[168:171], v[100:103]
	v_mfma_f32_16x16x32_bf16 v[96:99], v[216:219], v[168:171], v[96:99]
	v_mfma_f32_16x16x32_bf16 v[84:87], v[208:211], v[176:179], v[84:87]
	v_mfma_f32_16x16x32_bf16 v[80:83], v[216:219], v[176:179], v[80:83]
	v_mfma_f32_16x16x32_bf16 v[68:71], v[208:211], v[200:203], v[68:71]
	v_mfma_f32_16x16x32_bf16 v[64:67], v[216:219], v[200:203], v[64:67]
	v_mfma_f32_16x16x32_bf16 v[116:119], v[212:215], v[164:167], v[116:119]
	v_mfma_f32_16x16x32_bf16 v[112:115], v[220:223], v[164:167], v[112:115]
	v_mfma_f32_16x16x32_bf16 v[100:103], v[212:215], v[172:175], v[100:103]
	v_mfma_f32_16x16x32_bf16 v[96:99], v[220:223], v[172:175], v[96:99]
	v_mfma_f32_16x16x32_bf16 v[84:87], v[212:215], v[196:199], v[84:87]
	v_mfma_f32_16x16x32_bf16 v[80:83], v[220:223], v[196:199], v[80:83]
	v_mfma_f32_16x16x32_bf16 v[68:71], v[212:215], v[204:207], v[68:71]
	v_mfma_f32_16x16x32_bf16 v[64:67], v[220:223], v[204:207], v[64:67]
	s_mov_b32 m0, s46
	v_lshl_add_u64 v[142:143], v[224:225], 0, s[0:1]
	s_barrier
	ds_read_b128 v[160:163], v147 offset:49152
	ds_read_b128 v[164:167], v147 offset:50176
	ds_read_b128 v[168:171], v147 offset:51200
	ds_read_b128 v[172:175], v147 offset:52224
	ds_read_b128 v[176:179], v147 offset:53248
	ds_read_b128 v[196:199], v147 offset:54272
	ds_read_b128 v[200:203], v147 offset:55296
	ds_read_b128 v[204:207], v147 offset:56320
	global_load_lds_dwordx4 v[142:143], off
	v_lshl_add_u64 v[142:143], v[226:227], 0, s[0:1]
	s_mov_b32 m0, s47
	s_nop 0
	global_load_lds_dwordx4 v[142:143], off
	s_barrier
; DI float bf2f(unsigned v) { return __uint_as_float(v << 16); }
; template <class Epi, class Sched>
; DI void gemm_phase(LAS unsigned char* lds, const Gemm g, const Sched& S, const Epi& E) {
;     ...
;       PG8_WAIT_V(6); PG8_BAR; PG8_MMA(1, 1, At, B1); PG8_BAR;
;       PG8_LDB(B0, 1, 0); PG8_SCHED; PG8_LDA(At, 1, 0); PG8_STAGE(PG8_SA(0, 1), a2 + hstep, voffA);
;       PG8_WAIT_L(8); PG8_BAR; PG8_WAIT_L(0); PG8_MMA(0, 0, At, B0); PG8_BAR; PG8_SCHED;
;       PG8_LDB(B1, 1, 1); PG8_STAGE(PG8_SB(1, 0), b3, voffB);
;       PG8_BAR; PG8_WAIT_L(0); PG8_MMA(0, 1, At, B1); PG8_BAR;
;       PG8_LDA(At, 1, 1); PG8_STAGE(PG8_SA(1, 0), a3, voffA);
;       PG8_BAR; PG8_WAIT_L(0); PG8_MMA(1, 0, At, B0); PG8_BAR; PG8_SCHED;
;       PG8_STAGE(PG8_SB(1, 1), b3 + hstep, voffB);
;       PG8_WAIT_V(6); PG8_BAR; PG8_MMA(1, 1, At, B1); PG8_BAR;
;     }
;   DI void operator()(const f32x4 (&acc)[2][2][4][2], const pg8::Unit& u, int wr, int wc, int fr_, int fq_) const {
;     ...
;             } else if (EPI == EPI_RESID) {
;               if (n == 0) {
;                 const int f8 = u.pn * 256 + bj * 128 + wc * 32 + 8 * fq;
;                 const f32x4 v1 = acc[ai][bj][m][1];
;                 f32x4 r0, r1;
;                 if (rsrc) {
;                   r0 = *(const f32x4*)(rsrc + (size_t)token * 1024 + f8); r1 = *(const f32x4*)(rsrc + (size_t)token * 1024 + f8 + 4);
;                 } else {
;                   const u32x4 xu = *(const u32x4*)(xr + (size_t)token * 1024 + f8);
;                   r0 = (f32x4){bf2f(xu.x & 0xffffu), bf2f(xu.x >> 16), bf2f(xu.y & 0xffffu), bf2f(xu.y >> 16)};
;                   r1 = (f32x4){bf2f(xu.z & 0xffffu), bf2f(xu.z >> 16), bf2f(xu.w & 0xffffu), bf2f(xu.w >> 16)};
;                 }
;                 r0 += v; r1 += v1;
;                 st_bf8(xr + (size_t)token * 1024 + f8, r0, r1, 1.f);
;                 ssq += r0[0] * r0[0] + r0[1] * r0[1] + r0[2] * r0[2] + r0[3] * r0[3] + r1[0] * r1[0] + r1[1] * r1[1] + r1[2] * r1[2] + r1[3] * r1[3];
;               }
;             } else {
;               if (n == 0) {
;                 const f32x4 v1 = acc[ai][bj][m][1];
;                 u32x4 o4;
;                 { const float t0 = fmaxf(v[0], 0.f) * rinv, t1 = fmaxf(v[1], 0.f) * rinv, t2 = fmaxf(v[2], 0.f) * rinv, t3 = fmaxf(v[3], 0.f) * rinv;
;                   o4.x = pack2(t0 * t0, t1 * t1); o4.y = pack2(t2 * t2, t3 * t3); }
	s_waitcnt lgkmcnt(0)
	s_waitcnt lgkmcnt(0)
	v_mfma_f32_16x16x32_bf16 v[60:63], v[138:141], v[160:163], v[60:63]
	v_mfma_f32_16x16x32_bf16 v[56:59], v[152:155], v[160:163], v[56:59]
	v_mfma_f32_16x16x32_bf16 v[44:47], v[138:141], v[168:171], v[44:47]
	v_mfma_f32_16x16x32_bf16 v[40:43], v[152:155], v[168:171], v[40:43]
	v_mfma_f32_16x16x32_bf16 v[28:31], v[138:141], v[176:179], v[28:31]
	v_mfma_f32_16x16x32_bf16 v[24:27], v[152:155], v[176:179], v[24:27]
	v_mfma_f32_16x16x32_bf16 v[12:15], v[138:141], v[200:203], v[12:15]
	v_mfma_f32_16x16x32_bf16 v[8:11], v[152:155], v[200:203], v[8:11]
	v_mfma_f32_16x16x32_bf16 v[60:63], v[148:151], v[164:167], v[60:63]
	v_mfma_f32_16x16x32_bf16 v[56:59], v[156:159], v[164:167], v[56:59]
	v_mfma_f32_16x16x32_bf16 v[44:47], v[148:151], v[172:175], v[44:47]
	v_mfma_f32_16x16x32_bf16 v[40:43], v[156:159], v[172:175], v[40:43]
	v_mfma_f32_16x16x32_bf16 v[28:31], v[148:151], v[196:199], v[28:31]
	v_mfma_f32_16x16x32_bf16 v[24:27], v[156:159], v[196:199], v[24:27]
	v_mfma_f32_16x16x32_bf16 v[12:15], v[148:151], v[204:207], v[12:15]
	v_mfma_f32_16x16x32_bf16 v[8:11], v[156:159], v[204:207], v[8:11]
	s_barrier
	s_add_u32 s22, s22, 0x100080
	s_addc_u32 s23, s23, 0
	s_add_i32 s28, s28, s38
	v_lshl_add_u64 v[138:139], s[22:23], 0, v[144:145]
	s_mov_b32 m0, s28
	s_nop 0
	global_load_lds_dwordx4 v[138:139], off
	v_lshl_add_u64 v[138:139], s[22:23], 0, v[132:133]
	s_add_i32 m0, s28, 0x2000
	s_nop 0
	global_load_lds_dwordx4 v[138:139], off
	s_waitcnt vmcnt(6)
	s_barrier
	v_mfma_f32_16x16x32_bf16 v[52:55], v[208:211], v[160:163], v[52:55]
	v_mfma_f32_16x16x32_bf16 v[48:51], v[216:219], v[160:163], v[48:51]
	v_mfma_f32_16x16x32_bf16 v[36:39], v[208:211], v[168:171], v[36:39]
	v_mfma_f32_16x16x32_bf16 v[32:35], v[216:219], v[168:171], v[32:35]
	v_mfma_f32_16x16x32_bf16 v[20:23], v[208:211], v[176:179], v[20:23]
	v_mfma_f32_16x16x32_bf16 v[16:19], v[216:219], v[176:179], v[16:19]
	v_mfma_f32_16x16x32_bf16 v[4:7], v[208:211], v[200:203], v[4:7]
	v_mfma_f32_16x16x32_bf16 v[0:3], v[216:219], v[200:203], v[0:3]
	v_mfma_f32_16x16x32_bf16 v[52:55], v[212:215], v[164:167], v[52:55]
	v_mfma_f32_16x16x32_bf16 v[48:51], v[220:223], v[164:167], v[48:51]
	v_mfma_f32_16x16x32_bf16 v[36:39], v[212:215], v[172:175], v[36:39]
	v_mfma_f32_16x16x32_bf16 v[32:35], v[220:223], v[172:175], v[32:35]
	v_mfma_f32_16x16x32_bf16 v[20:23], v[212:215], v[196:199], v[20:23]
	v_mfma_f32_16x16x32_bf16 v[16:19], v[220:223], v[196:199], v[16:19]
	v_mfma_f32_16x16x32_bf16 v[4:7], v[212:215], v[204:207], v[4:7]
	v_mfma_f32_16x16x32_bf16 v[0:3], v[220:223], v[204:207], v[0:3]
	s_add_i32 s50, s50, 2
	s_add_u32 s20, s20, 0x100
	s_addc_u32 s21, s21, 0
	s_add_u32 s24, s24, 0x100
	s_addc_u32 s49, s49, 0
	s_cmp_gt_u32 s50, 61
	s_barrier
	s_cbranch_scc0 .LBB0_1905
	s_lshl_b32 s7, s18, 8
	v_mov_b32_e32 v139, v182
	s_add_i32 s7, s7, s44
	s_nop 0
	v_and_or_b32 v140, v139, 15, s7
	s_lshl_b32 s7, s16, 8
	v_bfe_u32 v141, v139, 4, 2
	s_or_b32 s7, s7, s45
	v_lshl_or_b32 v138, v141, 3, s7
	v_cmp_eq_u32_e32 vcc, 0, v141
	v_ashrrev_i32_e32 v141, 31, v140
	v_lshlrev_b32_e32 v139, 2, v139
	s_movk_i32 s7, 0x80
	v_lshlrev_b64 v[142:143], 11, v[140:141]
	v_bitop3_b32 v149, v139, 64, v190 bitop3:0x6c
	v_bitop3_b32 v148, v139, s7, v190 bitop3:0x6c
	v_ashrrev_i32_e32 v139, 31, v138
	v_lshl_add_u64 v[142:143], s[4:5], 0, v[142:143]
	v_lshl_add_u64 v[142:143], v[138:139], 1, v[142:143]
	global_load_dwordx4 v[150:153], v[142:143], off
	s_lshl_b32 s16, s16, 2
	s_ashr_i32 s17, s16, 31
	s_waitcnt vmcnt(0)
	v_lshlrev_b32_e32 v154, 16, v150
	v_and_b32_e32 v155, 0xffff0000, v150
	v_lshlrev_b32_e32 v150, 16, v151
	v_and_b32_e32 v151, 0xffff0000, v151
	v_lshlrev_b32_e32 v156, 16, v152
	v_and_b32_e32 v157, 0xffff0000, v152
	v_lshlrev_b32_e32 v152, 16, v153
	v_and_b32_e32 v153, 0xffff0000, v153
	v_pk_add_f32 v[126:127], v[126:127], v[150:151]
	v_pk_add_f32 v[124:125], v[124:125], v[154:155]
	v_pk_add_f32 v[150:151], v[122:123], v[152:153]
	v_pk_add_f32 v[152:153], v[120:121], v[156:157]
	v_cvt_pk_bf16_f32 v120, v124, v125
	v_cvt_pk_bf16_f32 v121, v126, v127
	v_cvt_pk_bf16_f32 v122, v152, v153
	v_cvt_pk_bf16_f32 v123, v150, v151
	global_store_dwordx4 v[142:143], v[120:123], off
	global_load_dwordx4 v[120:123], v[142:143], off offset:256
	v_mul_f32_e32 v154, v125, v125
	v_fmac_f32_e32 v154, v124, v124
	v_fmac_f32_e32 v154, v126, v126
	v_fmac_f32_e32 v154, v127, v127
	v_fmac_f32_e32 v154, v152, v152
	v_fmac_f32_e32 v154, v153, v153
	v_fmac_f32_e32 v154, v150, v150
	v_fmac_f32_e32 v154, v151, v151
	s_waitcnt vmcnt(0)
	v_lshlrev_b32_e32 v124, 16, v120
	v_and_b32_e32 v125, 0xffff0000, v120
	v_lshlrev_b32_e32 v120, 16, v121
	v_and_b32_e32 v121, 0xffff0000, v121
	v_lshlrev_b32_e32 v126, 16, v122
	v_and_b32_e32 v127, 0xffff0000, v122
	v_lshlrev_b32_e32 v122, 16, v123
	v_and_b32_e32 v123, 0xffff0000, v123
	v_pk_add_f32 v[118:119], v[118:119], v[120:121]
	v_pk_add_f32 v[116:117], v[116:117], v[124:125]
	v_pk_add_f32 v[120:121], v[114:115], v[122:123]
	v_pk_add_f32 v[122:123], v[112:113], v[126:127]
	v_cvt_pk_bf16_f32 v112, v116, v117
	v_cvt_pk_bf16_f32 v113, v118, v119
	v_cvt_pk_bf16_f32 v114, v122, v123
	v_cvt_pk_bf16_f32 v115, v120, v121
	global_store_dwordx4 v[142:143], v[112:115], off offset:256
	s_nop 1
	v_mul_f32_e32 v112, v117, v117
	v_fmac_f32_e32 v112, v116, v116
	v_fmac_f32_e32 v112, v118, v118
	v_fmac_f32_e32 v112, v119, v119
	v_fmac_f32_e32 v112, v122, v122
	v_fmac_f32_e32 v112, v123, v123
	v_fmac_f32_e32 v112, v120, v120
	v_fmac_f32_e32 v112, v121, v121
	v_add_f32_e32 v112, v154, v112
	ds_bpermute_b32 v113, v149, v112
	s_waitcnt lgkmcnt(0)
	v_add_f32_e32 v112, v112, v113
	ds_bpermute_b32 v113, v148, v112
	s_and_saveexec_b64 s[18:19], vcc
	s_cbranch_execz .LBB0_1908
	s_waitcnt lgkmcnt(0)
	v_add_f32_e32 v114, v112, v113
	v_lshlrev_b64 v[112:113], 6, v[140:141]
	v_lshl_add_u64 v[112:113], s[2:3], 0, v[112:113]
	v_lshl_add_u64 v[112:113], s[16:17], 2, v[112:113]
	s_lshl_b32 s24, s43, 2
	v_lshl_add_u64 v[112:113], v[112:113], 0, s[24:25]
	global_store_dword v[112:113], v114, off
